# K-loop 6-piece load segments: the two A-operand pieces (served from beyond L2) are issued first, before the LDS reads and the four weight pieces, for the longest flight before the counted wait
# speedup vs baseline: 1.0001x; 1.0001x over previous
.LBB0_322:
	s_ashr_i32 s43, s42, 31
	s_lshl_b64 s[46:47], s[42:43], 19
	s_add_u32 s46, s12, s46
	s_addc_u32 s47, s13, s47
	s_and_b64 s[48:49], s[4:5], exec
	s_cselect_b32 s18, s47, s7
	s_cselect_b32 s43, s46, s6
	s_ashr_i32 s45, s44, 31
	s_lshl_b64 s[48:49], s[44:45], 19
	s_add_u32 s48, s59, s48
	s_addc_u32 s49, s60, s49
	s_and_b64 s[50:51], s[4:5], exec
	s_cselect_b32 s45, s49, s9
	s_cselect_b32 s55, s48, s8
	s_add_u32 s6, s6, 0x40080
	s_addc_u32 s7, s7, 0
	s_add_u32 s56, s8, 0x100
	s_addc_u32 s57, s9, 0
	s_mov_b32 s78, -2
	ds_read_b128 v[96:99], v209
	ds_read_b128 v[100:103], v209 offset:1024
	ds_read_b128 v[120:123], v209 offset:2048
	ds_read_b128 v[124:127], v209 offset:3072
	ds_read_b128 v[144:147], v210
	ds_read_b128 v[148:151], v210 offset:1024
	ds_read_b128 v[152:155], v210 offset:2048
	ds_read_b128 v[156:159], v210 offset:3072
	s_add_u32 s8, s6, 0xfffc0080
	s_addc_u32 s9, s7, -1
	s_cmp_eq_u32 s78, 12
	s_cselect_b32 s51, s18, s9
	s_cselect_b32 s50, s43, s8
	s_cselect_b32 s9, s45, s57
	s_cselect_b32 s8, s55, s56
	v_lshl_add_u64 v[206:207], s[6:7], 0, v[170:171]
	s_add_i32 m0, s17, 0xc000
	ds_read_b128 v[178:181], v211
	ds_read_b128 v[182:185], v211 offset:1024
	ds_read_b128 v[186:189], v211 offset:2048
	ds_read_b128 v[190:193], v211 offset:3072
	ds_read_b128 v[194:197], v211 offset:4096
	ds_read_b128 v[198:201], v211 offset:5120
	ds_read_b128 v[202:205], v211 offset:6144
	ds_read_b128 v[218:221], v211 offset:7168
	global_load_lds_dwordx4 v[206:207], off
	s_add_i32 m0, s17, 0xe000
	v_lshl_add_u64 v[206:207], s[6:7], 0, v[172:173]
	global_load_lds_dwordx4 v[206:207], off
	s_waitcnt vmcnt(8) lgkmcnt(0)
	s_barrier
	s_setprio 1
	v_mfma_f32_16x16x32_bf16 v[140:143], v[96:99], v[178:181], 0
	v_mfma_f32_16x16x32_bf16 v[136:139], v[120:123], v[178:181], 0
	v_mfma_f32_16x16x32_bf16 v[116:119], v[96:99], v[186:189], 0
	v_mfma_f32_16x16x32_bf16 v[112:115], v[120:123], v[186:189], 0
	v_mfma_f32_16x16x32_bf16 v[92:95], v[96:99], v[194:197], 0
	v_mfma_f32_16x16x32_bf16 v[88:91], v[120:123], v[194:197], 0
	v_mfma_f32_16x16x32_bf16 v[76:79], v[96:99], v[202:205], 0
	v_mfma_f32_16x16x32_bf16 v[72:75], v[120:123], v[202:205], 0
	v_mfma_f32_16x16x32_bf16 v[140:143], v[100:103], v[182:185], v[140:143]
	v_mfma_f32_16x16x32_bf16 v[136:139], v[124:127], v[182:185], v[136:139]
	v_mfma_f32_16x16x32_bf16 v[116:119], v[100:103], v[190:193], v[116:119]
	v_mfma_f32_16x16x32_bf16 v[112:115], v[124:127], v[190:193], v[112:115]
	v_mfma_f32_16x16x32_bf16 v[92:95], v[100:103], v[198:201], v[92:95]
	v_mfma_f32_16x16x32_bf16 v[88:91], v[124:127], v[198:201], v[88:91]
	v_mfma_f32_16x16x32_bf16 v[76:79], v[100:103], v[218:221], v[76:79]
	v_mfma_f32_16x16x32_bf16 v[72:75], v[124:127], v[218:221], v[72:75]
	v_mfma_f32_16x16x32_bf16 v[132:135], v[144:147], v[178:181], 0
	v_mfma_f32_16x16x32_bf16 v[128:131], v[152:155], v[178:181], 0
	v_mfma_f32_16x16x32_bf16 v[108:111], v[144:147], v[186:189], 0
	v_mfma_f32_16x16x32_bf16 v[104:107], v[152:155], v[186:189], 0
	v_mfma_f32_16x16x32_bf16 v[84:87], v[144:147], v[194:197], 0
	v_mfma_f32_16x16x32_bf16 v[80:83], v[152:155], v[194:197], 0
	v_mfma_f32_16x16x32_bf16 v[68:71], v[144:147], v[202:205], 0
	v_mfma_f32_16x16x32_bf16 v[64:67], v[152:155], v[202:205], 0
	v_mfma_f32_16x16x32_bf16 v[132:135], v[148:151], v[182:185], v[132:135]
	v_mfma_f32_16x16x32_bf16 v[128:131], v[156:159], v[182:185], v[128:131]
	v_mfma_f32_16x16x32_bf16 v[108:111], v[148:151], v[190:193], v[108:111]
	v_mfma_f32_16x16x32_bf16 v[104:107], v[156:159], v[190:193], v[104:107]
	s_setprio 2
	s_barrier
	v_mfma_f32_16x16x32_bf16 v[84:87], v[148:151], v[198:201], v[84:87]
	v_mfma_f32_16x16x32_bf16 v[80:83], v[156:159], v[198:201], v[80:83]
	v_mfma_f32_16x16x32_bf16 v[68:71], v[148:151], v[218:221], v[68:71]
	v_mfma_f32_16x16x32_bf16 v[64:67], v[156:159], v[218:221], v[64:67]
	s_setprio 2
	s_mov_b32 m0, s17
	v_lshl_add_u64 v[224:225], s[50:51], 0, v[160:161]
	global_load_lds_dwordx4 v[224:225], off
	s_mov_b32 m0, s62
	v_lshl_add_u64 v[226:227], s[50:51], 0, v[164:165]
	global_load_lds_dwordx4 v[226:227], off
	s_add_i32 s79, s73, s61
	v_lshl_add_u64 v[206:207], s[8:9], 0, v[162:163]
	s_mov_b32 m0, s79
	ds_read_b128 v[178:181], v211 offset:16384
	ds_read_b128 v[182:185], v211 offset:17408
	ds_read_b128 v[186:189], v211 offset:18432
	ds_read_b128 v[190:193], v211 offset:19456
	ds_read_b128 v[194:197], v211 offset:20480
	ds_read_b128 v[198:201], v211 offset:21504
	ds_read_b128 v[202:205], v211 offset:22528
	ds_read_b128 v[218:221], v211 offset:23552
	global_load_lds_dwordx4 v[206:207], off
	s_add_i32 m0, s79, 0x2000
	s_add_u32 s80, s8, 0x40000
	v_lshl_add_u64 v[222:223], s[8:9], 0, v[166:167]
	s_addc_u32 s81, s9, 0
	s_add_i32 s79, s74, s61
	global_load_lds_dwordx4 v[222:223], off
	v_lshl_add_u64 v[242:243], s[80:81], 0, v[162:163]
	s_mov_b32 m0, s79
	global_load_lds_dwordx4 v[242:243], off
	s_add_i32 m0, s79, 0x2000
	v_lshl_add_u64 v[242:243], s[80:81], 0, v[166:167]
	global_load_lds_dwordx4 v[242:243], off
	s_waitcnt vmcnt(8) lgkmcnt(0)
	s_barrier
	s_setprio 1
	v_mfma_f32_16x16x32_bf16 v[60:63], v[96:99], v[178:181], 0
	v_mfma_f32_16x16x32_bf16 v[56:59], v[120:123], v[178:181], 0
	v_mfma_f32_16x16x32_bf16 v[44:47], v[96:99], v[186:189], 0
	v_mfma_f32_16x16x32_bf16 v[40:43], v[120:123], v[186:189], 0
	v_mfma_f32_16x16x32_bf16 v[28:31], v[96:99], v[194:197], 0
	v_mfma_f32_16x16x32_bf16 v[24:27], v[120:123], v[194:197], 0
	v_mfma_f32_16x16x32_bf16 v[12:15], v[96:99], v[202:205], 0
	v_mfma_f32_16x16x32_bf16 v[8:11], v[120:123], v[202:205], 0
	v_mfma_f32_16x16x32_bf16 v[60:63], v[100:103], v[182:185], v[60:63]
	v_mfma_f32_16x16x32_bf16 v[56:59], v[124:127], v[182:185], v[56:59]
	v_mfma_f32_16x16x32_bf16 v[44:47], v[100:103], v[190:193], v[44:47]
	v_mfma_f32_16x16x32_bf16 v[40:43], v[124:127], v[190:193], v[40:43]
	v_mfma_f32_16x16x32_bf16 v[28:31], v[100:103], v[198:201], v[28:31]
	v_mfma_f32_16x16x32_bf16 v[24:27], v[124:127], v[198:201], v[24:27]
	v_mfma_f32_16x16x32_bf16 v[12:15], v[100:103], v[218:221], v[12:15]
	v_mfma_f32_16x16x32_bf16 v[8:11], v[124:127], v[218:221], v[8:11]
	v_mfma_f32_16x16x32_bf16 v[52:55], v[144:147], v[178:181], 0
	v_mfma_f32_16x16x32_bf16 v[48:51], v[152:155], v[178:181], 0
	v_mfma_f32_16x16x32_bf16 v[36:39], v[144:147], v[186:189], 0
	v_mfma_f32_16x16x32_bf16 v[32:35], v[152:155], v[186:189], 0
	v_mfma_f32_16x16x32_bf16 v[20:23], v[144:147], v[194:197], 0
	v_mfma_f32_16x16x32_bf16 v[16:19], v[152:155], v[194:197], 0
	v_mfma_f32_16x16x32_bf16 v[4:7], v[144:147], v[202:205], 0
	v_mfma_f32_16x16x32_bf16 v[0:3], v[152:155], v[202:205], 0
	v_mfma_f32_16x16x32_bf16 v[52:55], v[148:151], v[182:185], v[52:55]
	v_mfma_f32_16x16x32_bf16 v[48:51], v[156:159], v[182:185], v[48:51]
	v_mfma_f32_16x16x32_bf16 v[36:39], v[148:151], v[190:193], v[36:39]
	v_mfma_f32_16x16x32_bf16 v[32:35], v[156:159], v[190:193], v[32:35]
	s_setprio 2
	s_barrier
	v_mfma_f32_16x16x32_bf16 v[20:23], v[148:151], v[198:201], v[20:23]
	v_mfma_f32_16x16x32_bf16 v[16:19], v[156:159], v[198:201], v[16:19]
	v_mfma_f32_16x16x32_bf16 v[4:7], v[148:151], v[218:221], v[4:7]
	v_mfma_f32_16x16x32_bf16 v[0:3], v[156:159], v[218:221], v[0:3]
	s_setprio 0
	s_add_i32 s79, 0, 0x18000
	s_add_i32 s80, 0, 0x1c000
	v_add_u32_e32 v124, s79, v208
	v_add_u32_e32 v156, s80, v208
	ds_read_b128 v[96:99], v124
	ds_read_b128 v[100:103], v124 offset:1024
	ds_read_b128 v[120:123], v124 offset:2048
	ds_read_b128 v[124:127], v124 offset:3072
	ds_read_b128 v[144:147], v156
	ds_read_b128 v[148:151], v156 offset:1024
	ds_read_b128 v[152:155], v156 offset:2048
	ds_read_b128 v[156:159], v156 offset:3072
	s_add_u32 s50, s50, 0x40000
	s_addc_u32 s51, s51, 0
	s_mov_b32 m0, s63
	v_lshl_add_u64 v[228:229], s[50:51], 0, v[160:161]
	ds_read_b128 v[178:181], v211 offset:32768
	ds_read_b128 v[182:185], v211 offset:33792
	ds_read_b128 v[186:189], v211 offset:34816
	ds_read_b128 v[190:193], v211 offset:35840
	ds_read_b128 v[194:197], v211 offset:36864
	ds_read_b128 v[198:201], v211 offset:37888
	ds_read_b128 v[202:205], v211 offset:38912
	ds_read_b128 v[218:221], v211 offset:39936
	global_load_lds_dwordx4 v[228:229], off
	s_mov_b32 m0, s64
	v_lshl_add_u64 v[228:229], s[50:51], 0, v[164:165]
	global_load_lds_dwordx4 v[228:229], off
	s_waitcnt vmcnt(8) lgkmcnt(0)
	s_barrier
	s_setprio 1
	v_mfma_f32_16x16x32_bf16 v[140:143], v[96:99], v[178:181], v[140:143]
	v_mfma_f32_16x16x32_bf16 v[136:139], v[120:123], v[178:181], v[136:139]
	v_mfma_f32_16x16x32_bf16 v[116:119], v[96:99], v[186:189], v[116:119]
	v_mfma_f32_16x16x32_bf16 v[112:115], v[120:123], v[186:189], v[112:115]
	v_mfma_f32_16x16x32_bf16 v[92:95], v[96:99], v[194:197], v[92:95]
	v_mfma_f32_16x16x32_bf16 v[88:91], v[120:123], v[194:197], v[88:91]
	v_mfma_f32_16x16x32_bf16 v[76:79], v[96:99], v[202:205], v[76:79]
	v_mfma_f32_16x16x32_bf16 v[72:75], v[120:123], v[202:205], v[72:75]
	v_mfma_f32_16x16x32_bf16 v[140:143], v[100:103], v[182:185], v[140:143]
	v_mfma_f32_16x16x32_bf16 v[136:139], v[124:127], v[182:185], v[136:139]
	v_mfma_f32_16x16x32_bf16 v[116:119], v[100:103], v[190:193], v[116:119]
	v_mfma_f32_16x16x32_bf16 v[112:115], v[124:127], v[190:193], v[112:115]
	v_mfma_f32_16x16x32_bf16 v[92:95], v[100:103], v[198:201], v[92:95]
	v_mfma_f32_16x16x32_bf16 v[88:91], v[124:127], v[198:201], v[88:91]
	v_mfma_f32_16x16x32_bf16 v[76:79], v[100:103], v[218:221], v[76:79]
	v_mfma_f32_16x16x32_bf16 v[72:75], v[124:127], v[218:221], v[72:75]
	v_mfma_f32_16x16x32_bf16 v[132:135], v[144:147], v[178:181], v[132:135]
	v_mfma_f32_16x16x32_bf16 v[128:131], v[152:155], v[178:181], v[128:131]
	v_mfma_f32_16x16x32_bf16 v[108:111], v[144:147], v[186:189], v[108:111]
	v_mfma_f32_16x16x32_bf16 v[104:107], v[152:155], v[186:189], v[104:107]
	v_mfma_f32_16x16x32_bf16 v[84:87], v[144:147], v[194:197], v[84:87]
	v_mfma_f32_16x16x32_bf16 v[80:83], v[152:155], v[194:197], v[80:83]
	v_mfma_f32_16x16x32_bf16 v[68:71], v[144:147], v[202:205], v[68:71]
	v_mfma_f32_16x16x32_bf16 v[64:67], v[152:155], v[202:205], v[64:67]
	v_mfma_f32_16x16x32_bf16 v[132:135], v[148:151], v[182:185], v[132:135]
	v_mfma_f32_16x16x32_bf16 v[128:131], v[156:159], v[182:185], v[128:131]
	v_mfma_f32_16x16x32_bf16 v[108:111], v[148:151], v[190:193], v[108:111]
	v_mfma_f32_16x16x32_bf16 v[104:107], v[156:159], v[190:193], v[104:107]
	s_setprio 2
	s_barrier
	v_mfma_f32_16x16x32_bf16 v[84:87], v[148:151], v[198:201], v[84:87]
	v_mfma_f32_16x16x32_bf16 v[80:83], v[156:159], v[198:201], v[80:83]
	v_mfma_f32_16x16x32_bf16 v[68:71], v[148:151], v[218:221], v[68:71]
	v_mfma_f32_16x16x32_bf16 v[64:67], v[156:159], v[218:221], v[64:67]
	s_setprio 2
	s_mov_b32 m0, s68
	v_lshl_add_u64 v[242:243], v[224:225], 0, s[36:37]
	global_load_lds_dwordx4 v[242:243], off
	s_mov_b32 m0, s69
	v_lshl_add_u64 v[242:243], v[226:227], 0, s[36:37]
	global_load_lds_dwordx4 v[242:243], off
	s_add_i32 s50, s79, s61
	v_lshl_add_u64 v[206:207], v[206:207], 0, s[36:37]
	s_mov_b32 m0, s50
	ds_read_b128 v[178:181], v211 offset:49152
	ds_read_b128 v[182:185], v211 offset:50176
	ds_read_b128 v[186:189], v211 offset:51200
	ds_read_b128 v[190:193], v211 offset:52224
	ds_read_b128 v[194:197], v211 offset:53248
	ds_read_b128 v[198:201], v211 offset:54272
	ds_read_b128 v[202:205], v211 offset:55296
	ds_read_b128 v[218:221], v211 offset:56320
	global_load_lds_dwordx4 v[206:207], off
	s_add_i32 m0, s50, 0x2000
	s_add_u32 s8, s8, 0x40080
	v_lshl_add_u64 v[206:207], v[222:223], 0, s[36:37]
	s_addc_u32 s9, s9, 0
	s_add_i32 s50, s80, s61
	global_load_lds_dwordx4 v[206:207], off
	s_mov_b32 m0, s50
	v_lshl_add_u64 v[206:207], s[8:9], 0, v[162:163]
	global_load_lds_dwordx4 v[206:207], off
	s_add_i32 m0, s50, 0x2000
	v_lshl_add_u64 v[206:207], s[8:9], 0, v[166:167]
	global_load_lds_dwordx4 v[206:207], off
	s_waitcnt vmcnt(8) lgkmcnt(0)
	s_barrier
	s_setprio 1
	v_mfma_f32_16x16x32_bf16 v[60:63], v[96:99], v[178:181], v[60:63]
	v_mfma_f32_16x16x32_bf16 v[56:59], v[120:123], v[178:181], v[56:59]
	v_mfma_f32_16x16x32_bf16 v[44:47], v[96:99], v[186:189], v[44:47]
	v_mfma_f32_16x16x32_bf16 v[40:43], v[120:123], v[186:189], v[40:43]
	v_mfma_f32_16x16x32_bf16 v[28:31], v[96:99], v[194:197], v[28:31]
	v_mfma_f32_16x16x32_bf16 v[24:27], v[120:123], v[194:197], v[24:27]
	v_mfma_f32_16x16x32_bf16 v[12:15], v[96:99], v[202:205], v[12:15]
	v_mfma_f32_16x16x32_bf16 v[8:11], v[120:123], v[202:205], v[8:11]
	v_mfma_f32_16x16x32_bf16 v[60:63], v[100:103], v[182:185], v[60:63]
	v_mfma_f32_16x16x32_bf16 v[56:59], v[124:127], v[182:185], v[56:59]
	v_mfma_f32_16x16x32_bf16 v[44:47], v[100:103], v[190:193], v[44:47]
	v_mfma_f32_16x16x32_bf16 v[40:43], v[124:127], v[190:193], v[40:43]
	v_mfma_f32_16x16x32_bf16 v[28:31], v[100:103], v[198:201], v[28:31]
	v_mfma_f32_16x16x32_bf16 v[24:27], v[124:127], v[198:201], v[24:27]
	v_mfma_f32_16x16x32_bf16 v[12:15], v[100:103], v[218:221], v[12:15]
	v_mfma_f32_16x16x32_bf16 v[8:11], v[124:127], v[218:221], v[8:11]
	v_mfma_f32_16x16x32_bf16 v[52:55], v[144:147], v[178:181], v[52:55]
	v_mfma_f32_16x16x32_bf16 v[48:51], v[152:155], v[178:181], v[48:51]
	v_mfma_f32_16x16x32_bf16 v[36:39], v[144:147], v[186:189], v[36:39]
	v_mfma_f32_16x16x32_bf16 v[32:35], v[152:155], v[186:189], v[32:35]
	v_mfma_f32_16x16x32_bf16 v[20:23], v[144:147], v[194:197], v[20:23]
	v_mfma_f32_16x16x32_bf16 v[16:19], v[152:155], v[194:197], v[16:19]
	v_mfma_f32_16x16x32_bf16 v[4:7], v[144:147], v[202:205], v[4:7]
	v_mfma_f32_16x16x32_bf16 v[0:3], v[152:155], v[202:205], v[0:3]
	v_mfma_f32_16x16x32_bf16 v[52:55], v[148:151], v[182:185], v[52:55]
	v_mfma_f32_16x16x32_bf16 v[48:51], v[156:159], v[182:185], v[48:51]
	v_mfma_f32_16x16x32_bf16 v[36:39], v[148:151], v[190:193], v[36:39]
	v_mfma_f32_16x16x32_bf16 v[32:35], v[156:159], v[190:193], v[32:35]
	s_setprio 2
	s_barrier
	v_mfma_f32_16x16x32_bf16 v[20:23], v[148:151], v[198:201], v[20:23]
	v_mfma_f32_16x16x32_bf16 v[16:19], v[156:159], v[198:201], v[16:19]
	v_mfma_f32_16x16x32_bf16 v[4:7], v[148:151], v[218:221], v[4:7]
	v_mfma_f32_16x16x32_bf16 v[0:3], v[156:159], v[218:221], v[0:3]
	s_setprio 0
	s_add_i32 s78, s78, 2
	s_add_u32 s6, s6, 0x100
	s_addc_u32 s7, s7, 0
	s_add_u32 s56, s56, 0x100
	s_addc_u32 s57, s57, 0
	s_cmp_gt_u32 s78, 13
.LBB0_323:
	ds_read_b128 v[96:99], v209
	ds_read_b128 v[100:103], v209 offset:1024
	ds_read_b128 v[120:123], v209 offset:2048
	ds_read_b128 v[124:127], v209 offset:3072
	ds_read_b128 v[144:147], v210
	ds_read_b128 v[148:151], v210 offset:1024
	ds_read_b128 v[152:155], v210 offset:2048
	ds_read_b128 v[156:159], v210 offset:3072
	s_add_u32 s8, s6, 0xfffc0080
	s_addc_u32 s9, s7, -1
	s_cmp_eq_u32 s78, 12
	s_cselect_b32 s51, s18, s9
	s_cselect_b32 s50, s43, s8
	s_cselect_b32 s9, s45, s57
	s_cselect_b32 s8, s55, s56
	v_lshl_add_u64 v[206:207], s[6:7], 0, v[170:171]
	s_add_i32 m0, s17, 0xc000
	ds_read_b128 v[178:181], v211
	ds_read_b128 v[182:185], v211 offset:1024
	ds_read_b128 v[186:189], v211 offset:2048
	ds_read_b128 v[190:193], v211 offset:3072
	ds_read_b128 v[194:197], v211 offset:4096
	ds_read_b128 v[198:201], v211 offset:5120
	ds_read_b128 v[202:205], v211 offset:6144
	ds_read_b128 v[218:221], v211 offset:7168
	global_load_lds_dwordx4 v[206:207], off
	s_add_i32 m0, s17, 0xe000
	v_lshl_add_u64 v[206:207], s[6:7], 0, v[172:173]
	global_load_lds_dwordx4 v[206:207], off
	s_waitcnt vmcnt(8) lgkmcnt(0)
	s_barrier
	s_setprio 1
	v_mfma_f32_16x16x32_bf16 v[140:143], v[96:99], v[178:181], v[140:143]
	v_mfma_f32_16x16x32_bf16 v[136:139], v[120:123], v[178:181], v[136:139]
	v_mfma_f32_16x16x32_bf16 v[116:119], v[96:99], v[186:189], v[116:119]
	v_mfma_f32_16x16x32_bf16 v[112:115], v[120:123], v[186:189], v[112:115]
	v_mfma_f32_16x16x32_bf16 v[92:95], v[96:99], v[194:197], v[92:95]
	v_mfma_f32_16x16x32_bf16 v[88:91], v[120:123], v[194:197], v[88:91]
	v_mfma_f32_16x16x32_bf16 v[76:79], v[96:99], v[202:205], v[76:79]
	v_mfma_f32_16x16x32_bf16 v[72:75], v[120:123], v[202:205], v[72:75]
	v_mfma_f32_16x16x32_bf16 v[140:143], v[100:103], v[182:185], v[140:143]
	v_mfma_f32_16x16x32_bf16 v[136:139], v[124:127], v[182:185], v[136:139]
	v_mfma_f32_16x16x32_bf16 v[116:119], v[100:103], v[190:193], v[116:119]
	v_mfma_f32_16x16x32_bf16 v[112:115], v[124:127], v[190:193], v[112:115]
	v_mfma_f32_16x16x32_bf16 v[92:95], v[100:103], v[198:201], v[92:95]
	v_mfma_f32_16x16x32_bf16 v[88:91], v[124:127], v[198:201], v[88:91]
	v_mfma_f32_16x16x32_bf16 v[76:79], v[100:103], v[218:221], v[76:79]
	v_mfma_f32_16x16x32_bf16 v[72:75], v[124:127], v[218:221], v[72:75]
	v_mfma_f32_16x16x32_bf16 v[132:135], v[144:147], v[178:181], v[132:135]
	v_mfma_f32_16x16x32_bf16 v[128:131], v[152:155], v[178:181], v[128:131]
	v_mfma_f32_16x16x32_bf16 v[108:111], v[144:147], v[186:189], v[108:111]
	v_mfma_f32_16x16x32_bf16 v[104:107], v[152:155], v[186:189], v[104:107]
	v_mfma_f32_16x16x32_bf16 v[84:87], v[144:147], v[194:197], v[84:87]
	v_mfma_f32_16x16x32_bf16 v[80:83], v[152:155], v[194:197], v[80:83]
	v_mfma_f32_16x16x32_bf16 v[68:71], v[144:147], v[202:205], v[68:71]
	v_mfma_f32_16x16x32_bf16 v[64:67], v[152:155], v[202:205], v[64:67]
	v_mfma_f32_16x16x32_bf16 v[132:135], v[148:151], v[182:185], v[132:135]
	v_mfma_f32_16x16x32_bf16 v[128:131], v[156:159], v[182:185], v[128:131]
	v_mfma_f32_16x16x32_bf16 v[108:111], v[148:151], v[190:193], v[108:111]
	v_mfma_f32_16x16x32_bf16 v[104:107], v[156:159], v[190:193], v[104:107]
	s_setprio 2
	s_barrier
	v_mfma_f32_16x16x32_bf16 v[84:87], v[148:151], v[198:201], v[84:87]
	v_mfma_f32_16x16x32_bf16 v[80:83], v[156:159], v[198:201], v[80:83]
	v_mfma_f32_16x16x32_bf16 v[68:71], v[148:151], v[218:221], v[68:71]
	v_mfma_f32_16x16x32_bf16 v[64:67], v[156:159], v[218:221], v[64:67]
	s_setprio 2
	s_mov_b32 m0, s17
	v_lshl_add_u64 v[224:225], s[50:51], 0, v[160:161]
	global_load_lds_dwordx4 v[224:225], off
	s_mov_b32 m0, s62
	v_lshl_add_u64 v[226:227], s[50:51], 0, v[164:165]
	global_load_lds_dwordx4 v[226:227], off
	s_add_i32 s79, s73, s61
	v_lshl_add_u64 v[206:207], s[8:9], 0, v[162:163]
	s_mov_b32 m0, s79
	ds_read_b128 v[178:181], v211 offset:16384
	ds_read_b128 v[182:185], v211 offset:17408
	ds_read_b128 v[186:189], v211 offset:18432
	ds_read_b128 v[190:193], v211 offset:19456
	ds_read_b128 v[194:197], v211 offset:20480
	ds_read_b128 v[198:201], v211 offset:21504
	ds_read_b128 v[202:205], v211 offset:22528
	ds_read_b128 v[218:221], v211 offset:23552
	global_load_lds_dwordx4 v[206:207], off
	s_add_i32 m0, s79, 0x2000
	s_add_u32 s80, s8, 0x40000
	v_lshl_add_u64 v[222:223], s[8:9], 0, v[166:167]
	s_addc_u32 s81, s9, 0
	s_add_i32 s79, s74, s61
	global_load_lds_dwordx4 v[222:223], off
	v_lshl_add_u64 v[242:243], s[80:81], 0, v[162:163]
	s_mov_b32 m0, s79
	global_load_lds_dwordx4 v[242:243], off
	s_add_i32 m0, s79, 0x2000
	v_lshl_add_u64 v[242:243], s[80:81], 0, v[166:167]
	global_load_lds_dwordx4 v[242:243], off
	s_waitcnt vmcnt(8) lgkmcnt(0)
	s_barrier
	s_setprio 1
	v_mfma_f32_16x16x32_bf16 v[60:63], v[96:99], v[178:181], v[60:63]
	v_mfma_f32_16x16x32_bf16 v[56:59], v[120:123], v[178:181], v[56:59]
	v_mfma_f32_16x16x32_bf16 v[44:47], v[96:99], v[186:189], v[44:47]
	v_mfma_f32_16x16x32_bf16 v[40:43], v[120:123], v[186:189], v[40:43]
	v_mfma_f32_16x16x32_bf16 v[28:31], v[96:99], v[194:197], v[28:31]
	v_mfma_f32_16x16x32_bf16 v[24:27], v[120:123], v[194:197], v[24:27]
	v_mfma_f32_16x16x32_bf16 v[12:15], v[96:99], v[202:205], v[12:15]
	v_mfma_f32_16x16x32_bf16 v[8:11], v[120:123], v[202:205], v[8:11]
	v_mfma_f32_16x16x32_bf16 v[60:63], v[100:103], v[182:185], v[60:63]
	v_mfma_f32_16x16x32_bf16 v[56:59], v[124:127], v[182:185], v[56:59]
	v_mfma_f32_16x16x32_bf16 v[44:47], v[100:103], v[190:193], v[44:47]
	v_mfma_f32_16x16x32_bf16 v[40:43], v[124:127], v[190:193], v[40:43]
	v_mfma_f32_16x16x32_bf16 v[28:31], v[100:103], v[198:201], v[28:31]
	v_mfma_f32_16x16x32_bf16 v[24:27], v[124:127], v[198:201], v[24:27]
	v_mfma_f32_16x16x32_bf16 v[12:15], v[100:103], v[218:221], v[12:15]
	v_mfma_f32_16x16x32_bf16 v[8:11], v[124:127], v[218:221], v[8:11]
	v_mfma_f32_16x16x32_bf16 v[52:55], v[144:147], v[178:181], v[52:55]
	v_mfma_f32_16x16x32_bf16 v[48:51], v[152:155], v[178:181], v[48:51]
	v_mfma_f32_16x16x32_bf16 v[36:39], v[144:147], v[186:189], v[36:39]
	v_mfma_f32_16x16x32_bf16 v[32:35], v[152:155], v[186:189], v[32:35]
	v_mfma_f32_16x16x32_bf16 v[20:23], v[144:147], v[194:197], v[20:23]
	v_mfma_f32_16x16x32_bf16 v[16:19], v[152:155], v[194:197], v[16:19]
	v_mfma_f32_16x16x32_bf16 v[4:7], v[144:147], v[202:205], v[4:7]
	v_mfma_f32_16x16x32_bf16 v[0:3], v[152:155], v[202:205], v[0:3]
	v_mfma_f32_16x16x32_bf16 v[52:55], v[148:151], v[182:185], v[52:55]
	v_mfma_f32_16x16x32_bf16 v[48:51], v[156:159], v[182:185], v[48:51]
	v_mfma_f32_16x16x32_bf16 v[36:39], v[148:151], v[190:193], v[36:39]
	v_mfma_f32_16x16x32_bf16 v[32:35], v[156:159], v[190:193], v[32:35]
	s_setprio 2
	s_barrier
	v_mfma_f32_16x16x32_bf16 v[20:23], v[148:151], v[198:201], v[20:23]
	v_mfma_f32_16x16x32_bf16 v[16:19], v[156:159], v[198:201], v[16:19]
	v_mfma_f32_16x16x32_bf16 v[4:7], v[148:151], v[218:221], v[4:7]
	v_mfma_f32_16x16x32_bf16 v[0:3], v[156:159], v[218:221], v[0:3]
	s_setprio 0
	s_add_i32 s79, 0, 0x18000
	s_add_i32 s80, 0, 0x1c000
	v_add_u32_e32 v124, s79, v208
	v_add_u32_e32 v156, s80, v208
	ds_read_b128 v[96:99], v124
	ds_read_b128 v[100:103], v124 offset:1024
	ds_read_b128 v[120:123], v124 offset:2048
	ds_read_b128 v[124:127], v124 offset:3072
	ds_read_b128 v[144:147], v156
	ds_read_b128 v[148:151], v156 offset:1024
	ds_read_b128 v[152:155], v156 offset:2048
	ds_read_b128 v[156:159], v156 offset:3072
	s_add_u32 s50, s50, 0x40000
	s_addc_u32 s51, s51, 0
	s_mov_b32 m0, s63
	v_lshl_add_u64 v[228:229], s[50:51], 0, v[160:161]
	ds_read_b128 v[178:181], v211 offset:32768
	ds_read_b128 v[182:185], v211 offset:33792
	ds_read_b128 v[186:189], v211 offset:34816
	ds_read_b128 v[190:193], v211 offset:35840
	ds_read_b128 v[194:197], v211 offset:36864
	ds_read_b128 v[198:201], v211 offset:37888
	ds_read_b128 v[202:205], v211 offset:38912
	ds_read_b128 v[218:221], v211 offset:39936
	global_load_lds_dwordx4 v[228:229], off
	s_mov_b32 m0, s64
	v_lshl_add_u64 v[228:229], s[50:51], 0, v[164:165]
	global_load_lds_dwordx4 v[228:229], off
	s_waitcnt vmcnt(8) lgkmcnt(0)
	s_barrier
	s_setprio 1
	v_mfma_f32_16x16x32_bf16 v[140:143], v[96:99], v[178:181], v[140:143]
	v_mfma_f32_16x16x32_bf16 v[136:139], v[120:123], v[178:181], v[136:139]
	v_mfma_f32_16x16x32_bf16 v[116:119], v[96:99], v[186:189], v[116:119]
	v_mfma_f32_16x16x32_bf16 v[112:115], v[120:123], v[186:189], v[112:115]
	v_mfma_f32_16x16x32_bf16 v[92:95], v[96:99], v[194:197], v[92:95]
	v_mfma_f32_16x16x32_bf16 v[88:91], v[120:123], v[194:197], v[88:91]
	v_mfma_f32_16x16x32_bf16 v[76:79], v[96:99], v[202:205], v[76:79]
	v_mfma_f32_16x16x32_bf16 v[72:75], v[120:123], v[202:205], v[72:75]
	v_mfma_f32_16x16x32_bf16 v[140:143], v[100:103], v[182:185], v[140:143]
	v_mfma_f32_16x16x32_bf16 v[136:139], v[124:127], v[182:185], v[136:139]
	v_mfma_f32_16x16x32_bf16 v[116:119], v[100:103], v[190:193], v[116:119]
	v_mfma_f32_16x16x32_bf16 v[112:115], v[124:127], v[190:193], v[112:115]
	v_mfma_f32_16x16x32_bf16 v[92:95], v[100:103], v[198:201], v[92:95]
	v_mfma_f32_16x16x32_bf16 v[88:91], v[124:127], v[198:201], v[88:91]
	v_mfma_f32_16x16x32_bf16 v[76:79], v[100:103], v[218:221], v[76:79]
	v_mfma_f32_16x16x32_bf16 v[72:75], v[124:127], v[218:221], v[72:75]
	v_mfma_f32_16x16x32_bf16 v[132:135], v[144:147], v[178:181], v[132:135]
	v_mfma_f32_16x16x32_bf16 v[128:131], v[152:155], v[178:181], v[128:131]
	v_mfma_f32_16x16x32_bf16 v[108:111], v[144:147], v[186:189], v[108:111]
	v_mfma_f32_16x16x32_bf16 v[104:107], v[152:155], v[186:189], v[104:107]
	v_mfma_f32_16x16x32_bf16 v[84:87], v[144:147], v[194:197], v[84:87]
	v_mfma_f32_16x16x32_bf16 v[80:83], v[152:155], v[194:197], v[80:83]
	v_mfma_f32_16x16x32_bf16 v[68:71], v[144:147], v[202:205], v[68:71]
	v_mfma_f32_16x16x32_bf16 v[64:67], v[152:155], v[202:205], v[64:67]
	v_mfma_f32_16x16x32_bf16 v[132:135], v[148:151], v[182:185], v[132:135]
	v_mfma_f32_16x16x32_bf16 v[128:131], v[156:159], v[182:185], v[128:131]
	v_mfma_f32_16x16x32_bf16 v[108:111], v[148:151], v[190:193], v[108:111]
	v_mfma_f32_16x16x32_bf16 v[104:107], v[156:159], v[190:193], v[104:107]
	s_setprio 2
	s_barrier
	v_mfma_f32_16x16x32_bf16 v[84:87], v[148:151], v[198:201], v[84:87]
	v_mfma_f32_16x16x32_bf16 v[80:83], v[156:159], v[198:201], v[80:83]
	v_mfma_f32_16x16x32_bf16 v[68:71], v[148:151], v[218:221], v[68:71]
	v_mfma_f32_16x16x32_bf16 v[64:67], v[156:159], v[218:221], v[64:67]
	s_setprio 2
	s_mov_b32 m0, s68
	v_lshl_add_u64 v[242:243], v[224:225], 0, s[36:37]
	global_load_lds_dwordx4 v[242:243], off
	s_mov_b32 m0, s69
	v_lshl_add_u64 v[242:243], v[226:227], 0, s[36:37]
	global_load_lds_dwordx4 v[242:243], off
	s_add_i32 s50, s79, s61
	v_lshl_add_u64 v[206:207], v[206:207], 0, s[36:37]
	s_mov_b32 m0, s50
	ds_read_b128 v[178:181], v211 offset:49152
	ds_read_b128 v[182:185], v211 offset:50176
	ds_read_b128 v[186:189], v211 offset:51200
	ds_read_b128 v[190:193], v211 offset:52224
	ds_read_b128 v[194:197], v211 offset:53248
	ds_read_b128 v[198:201], v211 offset:54272
	ds_read_b128 v[202:205], v211 offset:55296
	ds_read_b128 v[218:221], v211 offset:56320
	global_load_lds_dwordx4 v[206:207], off
	s_add_i32 m0, s50, 0x2000
	s_add_u32 s8, s8, 0x40080
	v_lshl_add_u64 v[206:207], v[222:223], 0, s[36:37]
	s_addc_u32 s9, s9, 0
	s_add_i32 s50, s80, s61
	global_load_lds_dwordx4 v[206:207], off
	s_mov_b32 m0, s50
	v_lshl_add_u64 v[206:207], s[8:9], 0, v[162:163]
	global_load_lds_dwordx4 v[206:207], off
	s_add_i32 m0, s50, 0x2000
	v_lshl_add_u64 v[206:207], s[8:9], 0, v[166:167]
	global_load_lds_dwordx4 v[206:207], off
	s_waitcnt vmcnt(8) lgkmcnt(0)
	s_barrier
	s_setprio 1
	v_mfma_f32_16x16x32_bf16 v[60:63], v[96:99], v[178:181], v[60:63]
	v_mfma_f32_16x16x32_bf16 v[56:59], v[120:123], v[178:181], v[56:59]
	v_mfma_f32_16x16x32_bf16 v[44:47], v[96:99], v[186:189], v[44:47]
	v_mfma_f32_16x16x32_bf16 v[40:43], v[120:123], v[186:189], v[40:43]
	v_mfma_f32_16x16x32_bf16 v[28:31], v[96:99], v[194:197], v[28:31]
	v_mfma_f32_16x16x32_bf16 v[24:27], v[120:123], v[194:197], v[24:27]
	v_mfma_f32_16x16x32_bf16 v[12:15], v[96:99], v[202:205], v[12:15]
	v_mfma_f32_16x16x32_bf16 v[8:11], v[120:123], v[202:205], v[8:11]
	v_mfma_f32_16x16x32_bf16 v[60:63], v[100:103], v[182:185], v[60:63]
	v_mfma_f32_16x16x32_bf16 v[56:59], v[124:127], v[182:185], v[56:59]
	v_mfma_f32_16x16x32_bf16 v[44:47], v[100:103], v[190:193], v[44:47]
	v_mfma_f32_16x16x32_bf16 v[40:43], v[124:127], v[190:193], v[40:43]
	v_mfma_f32_16x16x32_bf16 v[28:31], v[100:103], v[198:201], v[28:31]
	v_mfma_f32_16x16x32_bf16 v[24:27], v[124:127], v[198:201], v[24:27]
	v_mfma_f32_16x16x32_bf16 v[12:15], v[100:103], v[218:221], v[12:15]
	v_mfma_f32_16x16x32_bf16 v[8:11], v[124:127], v[218:221], v[8:11]
	v_mfma_f32_16x16x32_bf16 v[52:55], v[144:147], v[178:181], v[52:55]
	v_mfma_f32_16x16x32_bf16 v[48:51], v[152:155], v[178:181], v[48:51]
	v_mfma_f32_16x16x32_bf16 v[36:39], v[144:147], v[186:189], v[36:39]
	v_mfma_f32_16x16x32_bf16 v[32:35], v[152:155], v[186:189], v[32:35]
	v_mfma_f32_16x16x32_bf16 v[20:23], v[144:147], v[194:197], v[20:23]
	v_mfma_f32_16x16x32_bf16 v[16:19], v[152:155], v[194:197], v[16:19]
	v_mfma_f32_16x16x32_bf16 v[4:7], v[144:147], v[202:205], v[4:7]
	v_mfma_f32_16x16x32_bf16 v[0:3], v[152:155], v[202:205], v[0:3]
	v_mfma_f32_16x16x32_bf16 v[52:55], v[148:151], v[182:185], v[52:55]
	v_mfma_f32_16x16x32_bf16 v[48:51], v[156:159], v[182:185], v[48:51]
	v_mfma_f32_16x16x32_bf16 v[36:39], v[148:151], v[190:193], v[36:39]
	v_mfma_f32_16x16x32_bf16 v[32:35], v[156:159], v[190:193], v[32:35]
	s_setprio 2
	s_barrier
	v_mfma_f32_16x16x32_bf16 v[20:23], v[148:151], v[198:201], v[20:23]
	v_mfma_f32_16x16x32_bf16 v[16:19], v[156:159], v[198:201], v[16:19]
	v_mfma_f32_16x16x32_bf16 v[4:7], v[148:151], v[218:221], v[4:7]
	v_mfma_f32_16x16x32_bf16 v[0:3], v[156:159], v[218:221], v[0:3]
	s_setprio 0
	s_add_i32 s78, s78, 2
	s_add_u32 s6, s6, 0x100
	s_addc_u32 s7, s7, 0
	s_add_u32 s56, s56, 0x100
	s_addc_u32 s57, s57, 0
	s_cmp_gt_u32 s78, 13
	s_cbranch_scc0 .LBB0_323

.LBB0_783:
	s_ashr_i32 s23, s22, 31
	s_lshl_b64 s[26:27], s[22:23], 19
	s_add_u32 s26, s43, s26
	s_addc_u32 s27, s44, s27
	s_and_b64 s[28:29], s[4:5], exec
	s_cselect_b32 s23, s27, s37
	s_cselect_b32 s31, s26, s36
	s_ashr_i32 s25, s24, 31
	s_lshl_b64 s[28:29], s[24:25], 19
	s_add_u32 s28, s45, s28
	s_addc_u32 s29, s46, s29
	s_and_b64 s[40:41], s[4:5], exec
	s_cselect_b32 s25, s29, s39
	s_cselect_b32 s62, s28, s38
	s_add_u32 s36, s36, 0x40080
	s_addc_u32 s37, s37, 0
	s_add_u32 s63, s38, 0x100
	s_addc_u32 s64, s39, 0
	s_mov_b32 s65, -2
	ds_read_b128 v[144:147], v163
	ds_read_b128 v[148:151], v163 offset:1024
	ds_read_b128 v[152:155], v163 offset:2048
	ds_read_b128 v[156:159], v163 offset:3072
	ds_read_b128 v[168:171], v164
	ds_read_b128 v[172:175], v164 offset:1024
	ds_read_b128 v[176:179], v164 offset:2048
	ds_read_b128 v[180:183], v164 offset:3072
	s_add_u32 s38, s36, 0xfffc0080
	s_addc_u32 s39, s37, -1
	s_cmp_eq_u32 s65, 12
	s_cselect_b32 s41, s23, s39
	s_cselect_b32 s40, s31, s38
	s_cselect_b32 s39, s25, s64
	s_cselect_b32 s38, s62, s63
	v_lshl_add_u64 v[160:161], s[36:37], 0, v[136:137]
	s_add_i32 m0, s50, 0xc000
	ds_read_b128 v[184:187], v165
	ds_read_b128 v[188:191], v165 offset:1024
	ds_read_b128 v[192:195], v165 offset:2048
	ds_read_b128 v[196:199], v165 offset:3072
	ds_read_b128 v[200:203], v165 offset:4096
	ds_read_b128 v[204:207], v165 offset:5120
	ds_read_b128 v[208:211], v165 offset:6144
	ds_read_b128 v[212:215], v165 offset:7168
	global_load_lds_dwordx4 v[160:161], off
	s_add_i32 m0, s50, 0xe000
	v_lshl_add_u64 v[160:161], s[36:37], 0, v[138:139]
	global_load_lds_dwordx4 v[160:161], off
	s_waitcnt vmcnt(8) lgkmcnt(0)
	s_barrier
	s_setprio 1
	v_mfma_f32_16x16x32_bf16 v[124:127], v[144:147], v[184:187], 0
	v_mfma_f32_16x16x32_bf16 v[120:123], v[152:155], v[184:187], 0
	v_mfma_f32_16x16x32_bf16 v[108:111], v[144:147], v[192:195], 0
	v_mfma_f32_16x16x32_bf16 v[104:107], v[152:155], v[192:195], 0
	v_mfma_f32_16x16x32_bf16 v[92:95], v[144:147], v[200:203], 0
	v_mfma_f32_16x16x32_bf16 v[88:91], v[152:155], v[200:203], 0
	v_mfma_f32_16x16x32_bf16 v[76:79], v[144:147], v[208:211], 0
	v_mfma_f32_16x16x32_bf16 v[72:75], v[152:155], v[208:211], 0
	v_mfma_f32_16x16x32_bf16 v[124:127], v[148:151], v[188:191], v[124:127]
	v_mfma_f32_16x16x32_bf16 v[120:123], v[156:159], v[188:191], v[120:123]
	v_mfma_f32_16x16x32_bf16 v[108:111], v[148:151], v[196:199], v[108:111]
	v_mfma_f32_16x16x32_bf16 v[104:107], v[156:159], v[196:199], v[104:107]
	v_mfma_f32_16x16x32_bf16 v[92:95], v[148:151], v[204:207], v[92:95]
	v_mfma_f32_16x16x32_bf16 v[88:91], v[156:159], v[204:207], v[88:91]
	v_mfma_f32_16x16x32_bf16 v[76:79], v[148:151], v[212:215], v[76:79]
	v_mfma_f32_16x16x32_bf16 v[72:75], v[156:159], v[212:215], v[72:75]
	v_mfma_f32_16x16x32_bf16 v[116:119], v[168:171], v[184:187], 0
	v_mfma_f32_16x16x32_bf16 v[112:115], v[176:179], v[184:187], 0
	v_mfma_f32_16x16x32_bf16 v[100:103], v[168:171], v[192:195], 0
	v_mfma_f32_16x16x32_bf16 v[96:99], v[176:179], v[192:195], 0
	v_mfma_f32_16x16x32_bf16 v[84:87], v[168:171], v[200:203], 0
	v_mfma_f32_16x16x32_bf16 v[80:83], v[176:179], v[200:203], 0
	v_mfma_f32_16x16x32_bf16 v[68:71], v[168:171], v[208:211], 0
	v_mfma_f32_16x16x32_bf16 v[64:67], v[176:179], v[208:211], 0
	v_mfma_f32_16x16x32_bf16 v[116:119], v[172:175], v[188:191], v[116:119]
	v_mfma_f32_16x16x32_bf16 v[112:115], v[180:183], v[188:191], v[112:115]
	v_mfma_f32_16x16x32_bf16 v[100:103], v[172:175], v[196:199], v[100:103]
	v_mfma_f32_16x16x32_bf16 v[96:99], v[180:183], v[196:199], v[96:99]
	s_setprio 2
	s_barrier
	v_mfma_f32_16x16x32_bf16 v[84:87], v[172:175], v[204:207], v[84:87]
	v_mfma_f32_16x16x32_bf16 v[80:83], v[180:183], v[204:207], v[80:83]
	v_mfma_f32_16x16x32_bf16 v[68:71], v[172:175], v[212:215], v[68:71]
	v_mfma_f32_16x16x32_bf16 v[64:67], v[180:183], v[212:215], v[64:67]
	s_setprio 2
	s_mov_b32 m0, s50
	v_lshl_add_u64 v[218:219], s[40:41], 0, v[134:135]
	global_load_lds_dwordx4 v[218:219], off
	s_mov_b32 m0, s51
	v_lshl_add_u64 v[220:221], s[40:41], 0, v[130:131]
	global_load_lds_dwordx4 v[220:221], off
	s_add_i32 s66, s59, s47
	v_lshl_add_u64 v[160:161], s[38:39], 0, v[132:133]
	s_mov_b32 m0, s66
	ds_read_b128 v[184:187], v165 offset:16384
	ds_read_b128 v[188:191], v165 offset:17408
	ds_read_b128 v[192:195], v165 offset:18432
	ds_read_b128 v[196:199], v165 offset:19456
	ds_read_b128 v[200:203], v165 offset:20480
	ds_read_b128 v[204:207], v165 offset:21504
	ds_read_b128 v[208:211], v165 offset:22528
	ds_read_b128 v[212:215], v165 offset:23552
	global_load_lds_dwordx4 v[160:161], off
	s_add_i32 m0, s66, 0x2000
	s_add_u32 s66, s38, 0x40000
	v_lshl_add_u64 v[216:217], s[38:39], 0, v[128:129]
	s_addc_u32 s67, s39, 0
	s_add_i32 s68, s60, s47
	global_load_lds_dwordx4 v[216:217], off
	v_lshl_add_u64 v[248:249], s[66:67], 0, v[132:133]
	s_mov_b32 m0, s68
	global_load_lds_dwordx4 v[248:249], off
	s_add_i32 m0, s68, 0x2000
	v_lshl_add_u64 v[248:249], s[66:67], 0, v[128:129]
	global_load_lds_dwordx4 v[248:249], off
	s_waitcnt vmcnt(8) lgkmcnt(0)
	s_barrier
	s_setprio 1
	v_mfma_f32_16x16x32_bf16 v[60:63], v[144:147], v[184:187], 0
	v_mfma_f32_16x16x32_bf16 v[56:59], v[152:155], v[184:187], 0
	v_mfma_f32_16x16x32_bf16 v[44:47], v[144:147], v[192:195], 0
	v_mfma_f32_16x16x32_bf16 v[40:43], v[152:155], v[192:195], 0
	v_mfma_f32_16x16x32_bf16 v[28:31], v[144:147], v[200:203], 0
	v_mfma_f32_16x16x32_bf16 v[24:27], v[152:155], v[200:203], 0
	v_mfma_f32_16x16x32_bf16 v[12:15], v[144:147], v[208:211], 0
	v_mfma_f32_16x16x32_bf16 v[8:11], v[152:155], v[208:211], 0
	v_mfma_f32_16x16x32_bf16 v[60:63], v[148:151], v[188:191], v[60:63]
	v_mfma_f32_16x16x32_bf16 v[56:59], v[156:159], v[188:191], v[56:59]
	v_mfma_f32_16x16x32_bf16 v[44:47], v[148:151], v[196:199], v[44:47]
	v_mfma_f32_16x16x32_bf16 v[40:43], v[156:159], v[196:199], v[40:43]
	v_mfma_f32_16x16x32_bf16 v[28:31], v[148:151], v[204:207], v[28:31]
	v_mfma_f32_16x16x32_bf16 v[24:27], v[156:159], v[204:207], v[24:27]
	v_mfma_f32_16x16x32_bf16 v[12:15], v[148:151], v[212:215], v[12:15]
	v_mfma_f32_16x16x32_bf16 v[8:11], v[156:159], v[212:215], v[8:11]
	v_mfma_f32_16x16x32_bf16 v[52:55], v[168:171], v[184:187], 0
	v_mfma_f32_16x16x32_bf16 v[48:51], v[176:179], v[184:187], 0
	v_mfma_f32_16x16x32_bf16 v[36:39], v[168:171], v[192:195], 0
	v_mfma_f32_16x16x32_bf16 v[32:35], v[176:179], v[192:195], 0
	v_mfma_f32_16x16x32_bf16 v[20:23], v[168:171], v[200:203], 0
	v_mfma_f32_16x16x32_bf16 v[16:19], v[176:179], v[200:203], 0
	v_mfma_f32_16x16x32_bf16 v[4:7], v[168:171], v[208:211], 0
	v_mfma_f32_16x16x32_bf16 v[0:3], v[176:179], v[208:211], 0
	v_mfma_f32_16x16x32_bf16 v[52:55], v[172:175], v[188:191], v[52:55]
	v_mfma_f32_16x16x32_bf16 v[48:51], v[180:183], v[188:191], v[48:51]
	v_mfma_f32_16x16x32_bf16 v[36:39], v[172:175], v[196:199], v[36:39]
	v_mfma_f32_16x16x32_bf16 v[32:35], v[180:183], v[196:199], v[32:35]
	s_setprio 2
	s_barrier
	v_mfma_f32_16x16x32_bf16 v[20:23], v[172:175], v[204:207], v[20:23]
	v_mfma_f32_16x16x32_bf16 v[16:19], v[180:183], v[204:207], v[16:19]
	v_mfma_f32_16x16x32_bf16 v[4:7], v[172:175], v[212:215], v[4:7]
	v_mfma_f32_16x16x32_bf16 v[0:3], v[180:183], v[212:215], v[0:3]
	s_setprio 0
	s_add_i32 s66, 0, 0x18000
	s_add_i32 s67, 0, 0x1c000
	v_add_u32_e32 v156, s66, v162
	v_add_u32_e32 v167, s67, v162
	ds_read_b128 v[144:147], v156
	ds_read_b128 v[148:151], v156 offset:1024
	ds_read_b128 v[152:155], v156 offset:2048
	ds_read_b128 v[156:159], v156 offset:3072
	ds_read_b128 v[168:171], v167
	ds_read_b128 v[172:175], v167 offset:1024
	ds_read_b128 v[176:179], v167 offset:2048
	ds_read_b128 v[180:183], v167 offset:3072
	s_add_u32 s40, s40, 0x40000
	s_addc_u32 s41, s41, 0
	s_mov_b32 m0, s54
	v_lshl_add_u64 v[222:223], s[40:41], 0, v[134:135]
	ds_read_b128 v[184:187], v165 offset:32768
	ds_read_b128 v[188:191], v165 offset:33792
	ds_read_b128 v[192:195], v165 offset:34816
	ds_read_b128 v[196:199], v165 offset:35840
	ds_read_b128 v[200:203], v165 offset:36864
	ds_read_b128 v[204:207], v165 offset:37888
	ds_read_b128 v[208:211], v165 offset:38912
	ds_read_b128 v[212:215], v165 offset:39936
	global_load_lds_dwordx4 v[222:223], off
	s_mov_b32 m0, s55
	v_lshl_add_u64 v[222:223], s[40:41], 0, v[130:131]
	global_load_lds_dwordx4 v[222:223], off
	s_waitcnt vmcnt(8) lgkmcnt(0)
	s_barrier
	s_setprio 1
	v_mfma_f32_16x16x32_bf16 v[124:127], v[144:147], v[184:187], v[124:127]
	v_mfma_f32_16x16x32_bf16 v[120:123], v[152:155], v[184:187], v[120:123]
	v_mfma_f32_16x16x32_bf16 v[108:111], v[144:147], v[192:195], v[108:111]
	v_mfma_f32_16x16x32_bf16 v[104:107], v[152:155], v[192:195], v[104:107]
	v_mfma_f32_16x16x32_bf16 v[92:95], v[144:147], v[200:203], v[92:95]
	v_mfma_f32_16x16x32_bf16 v[88:91], v[152:155], v[200:203], v[88:91]
	v_mfma_f32_16x16x32_bf16 v[76:79], v[144:147], v[208:211], v[76:79]
	v_mfma_f32_16x16x32_bf16 v[72:75], v[152:155], v[208:211], v[72:75]
	v_mfma_f32_16x16x32_bf16 v[124:127], v[148:151], v[188:191], v[124:127]
	v_mfma_f32_16x16x32_bf16 v[120:123], v[156:159], v[188:191], v[120:123]
	v_mfma_f32_16x16x32_bf16 v[108:111], v[148:151], v[196:199], v[108:111]
	v_mfma_f32_16x16x32_bf16 v[104:107], v[156:159], v[196:199], v[104:107]
	v_mfma_f32_16x16x32_bf16 v[92:95], v[148:151], v[204:207], v[92:95]
	v_mfma_f32_16x16x32_bf16 v[88:91], v[156:159], v[204:207], v[88:91]
	v_mfma_f32_16x16x32_bf16 v[76:79], v[148:151], v[212:215], v[76:79]
	v_mfma_f32_16x16x32_bf16 v[72:75], v[156:159], v[212:215], v[72:75]
	v_mfma_f32_16x16x32_bf16 v[116:119], v[168:171], v[184:187], v[116:119]
	v_mfma_f32_16x16x32_bf16 v[112:115], v[176:179], v[184:187], v[112:115]
	v_mfma_f32_16x16x32_bf16 v[100:103], v[168:171], v[192:195], v[100:103]
	v_mfma_f32_16x16x32_bf16 v[96:99], v[176:179], v[192:195], v[96:99]
	v_mfma_f32_16x16x32_bf16 v[84:87], v[168:171], v[200:203], v[84:87]
	v_mfma_f32_16x16x32_bf16 v[80:83], v[176:179], v[200:203], v[80:83]
	v_mfma_f32_16x16x32_bf16 v[68:71], v[168:171], v[208:211], v[68:71]
	v_mfma_f32_16x16x32_bf16 v[64:67], v[176:179], v[208:211], v[64:67]
	v_mfma_f32_16x16x32_bf16 v[116:119], v[172:175], v[188:191], v[116:119]
	v_mfma_f32_16x16x32_bf16 v[112:115], v[180:183], v[188:191], v[112:115]
	v_mfma_f32_16x16x32_bf16 v[100:103], v[172:175], v[196:199], v[100:103]
	v_mfma_f32_16x16x32_bf16 v[96:99], v[180:183], v[196:199], v[96:99]
	s_setprio 2
	s_barrier
	v_mfma_f32_16x16x32_bf16 v[84:87], v[172:175], v[204:207], v[84:87]
	v_mfma_f32_16x16x32_bf16 v[80:83], v[180:183], v[204:207], v[80:83]
	v_mfma_f32_16x16x32_bf16 v[68:71], v[172:175], v[212:215], v[68:71]
	v_mfma_f32_16x16x32_bf16 v[64:67], v[180:183], v[212:215], v[64:67]
	s_setprio 2
	s_mov_b32 m0, s57
	v_lshl_add_u64 v[248:249], v[218:219], 0, s[16:17]
	global_load_lds_dwordx4 v[248:249], off
	s_mov_b32 m0, s58
	v_lshl_add_u64 v[248:249], v[220:221], 0, s[16:17]
	global_load_lds_dwordx4 v[248:249], off
	s_add_i32 s40, s66, s47
	v_lshl_add_u64 v[160:161], v[160:161], 0, s[16:17]
	s_mov_b32 m0, s40
	ds_read_b128 v[184:187], v165 offset:49152
	ds_read_b128 v[188:191], v165 offset:50176
	ds_read_b128 v[192:195], v165 offset:51200
	ds_read_b128 v[196:199], v165 offset:52224
	ds_read_b128 v[200:203], v165 offset:53248
	ds_read_b128 v[204:207], v165 offset:54272
	ds_read_b128 v[208:211], v165 offset:55296
	ds_read_b128 v[212:215], v165 offset:56320
	global_load_lds_dwordx4 v[160:161], off
	s_add_i32 m0, s40, 0x2000
	s_add_u32 s38, s38, 0x40080
	v_lshl_add_u64 v[160:161], v[216:217], 0, s[16:17]
	s_addc_u32 s39, s39, 0
	s_add_i32 s40, s67, s47
	global_load_lds_dwordx4 v[160:161], off
	s_mov_b32 m0, s40
	v_lshl_add_u64 v[160:161], s[38:39], 0, v[132:133]
	global_load_lds_dwordx4 v[160:161], off
	s_add_i32 m0, s40, 0x2000
	v_lshl_add_u64 v[160:161], s[38:39], 0, v[128:129]
	global_load_lds_dwordx4 v[160:161], off
	s_waitcnt vmcnt(8) lgkmcnt(0)
	s_barrier
	s_setprio 1
	v_mfma_f32_16x16x32_bf16 v[60:63], v[144:147], v[184:187], v[60:63]
	v_mfma_f32_16x16x32_bf16 v[56:59], v[152:155], v[184:187], v[56:59]
	v_mfma_f32_16x16x32_bf16 v[44:47], v[144:147], v[192:195], v[44:47]
	v_mfma_f32_16x16x32_bf16 v[40:43], v[152:155], v[192:195], v[40:43]
	v_mfma_f32_16x16x32_bf16 v[28:31], v[144:147], v[200:203], v[28:31]
	v_mfma_f32_16x16x32_bf16 v[24:27], v[152:155], v[200:203], v[24:27]
	v_mfma_f32_16x16x32_bf16 v[12:15], v[144:147], v[208:211], v[12:15]
	v_mfma_f32_16x16x32_bf16 v[8:11], v[152:155], v[208:211], v[8:11]
	v_mfma_f32_16x16x32_bf16 v[60:63], v[148:151], v[188:191], v[60:63]
	v_mfma_f32_16x16x32_bf16 v[56:59], v[156:159], v[188:191], v[56:59]
	v_mfma_f32_16x16x32_bf16 v[44:47], v[148:151], v[196:199], v[44:47]
	v_mfma_f32_16x16x32_bf16 v[40:43], v[156:159], v[196:199], v[40:43]
	v_mfma_f32_16x16x32_bf16 v[28:31], v[148:151], v[204:207], v[28:31]
	v_mfma_f32_16x16x32_bf16 v[24:27], v[156:159], v[204:207], v[24:27]
	v_mfma_f32_16x16x32_bf16 v[12:15], v[148:151], v[212:215], v[12:15]
	v_mfma_f32_16x16x32_bf16 v[8:11], v[156:159], v[212:215], v[8:11]
	v_mfma_f32_16x16x32_bf16 v[52:55], v[168:171], v[184:187], v[52:55]
	v_mfma_f32_16x16x32_bf16 v[48:51], v[176:179], v[184:187], v[48:51]
	v_mfma_f32_16x16x32_bf16 v[36:39], v[168:171], v[192:195], v[36:39]
	v_mfma_f32_16x16x32_bf16 v[32:35], v[176:179], v[192:195], v[32:35]
	v_mfma_f32_16x16x32_bf16 v[20:23], v[168:171], v[200:203], v[20:23]
	v_mfma_f32_16x16x32_bf16 v[16:19], v[176:179], v[200:203], v[16:19]
	v_mfma_f32_16x16x32_bf16 v[4:7], v[168:171], v[208:211], v[4:7]
	v_mfma_f32_16x16x32_bf16 v[0:3], v[176:179], v[208:211], v[0:3]
	v_mfma_f32_16x16x32_bf16 v[52:55], v[172:175], v[188:191], v[52:55]
	v_mfma_f32_16x16x32_bf16 v[48:51], v[180:183], v[188:191], v[48:51]
	v_mfma_f32_16x16x32_bf16 v[36:39], v[172:175], v[196:199], v[36:39]
	v_mfma_f32_16x16x32_bf16 v[32:35], v[180:183], v[196:199], v[32:35]
	s_setprio 2
	s_barrier
	v_mfma_f32_16x16x32_bf16 v[20:23], v[172:175], v[204:207], v[20:23]
	v_mfma_f32_16x16x32_bf16 v[16:19], v[180:183], v[204:207], v[16:19]
	v_mfma_f32_16x16x32_bf16 v[4:7], v[172:175], v[212:215], v[4:7]
	v_mfma_f32_16x16x32_bf16 v[0:3], v[180:183], v[212:215], v[0:3]
	s_setprio 0
	s_add_i32 s65, s65, 2
	s_add_u32 s36, s36, 0x100
	s_addc_u32 s37, s37, 0
	s_add_u32 s63, s63, 0x100
	s_addc_u32 s64, s64, 0
	s_cmp_gt_u32 s65, 13
.LBB0_784:
	ds_read_b128 v[144:147], v163
	ds_read_b128 v[148:151], v163 offset:1024
	ds_read_b128 v[152:155], v163 offset:2048
	ds_read_b128 v[156:159], v163 offset:3072
	ds_read_b128 v[168:171], v164
	ds_read_b128 v[172:175], v164 offset:1024
	ds_read_b128 v[176:179], v164 offset:2048
	ds_read_b128 v[180:183], v164 offset:3072
	s_add_u32 s38, s36, 0xfffc0080
	s_addc_u32 s39, s37, -1
	s_cmp_eq_u32 s65, 12
	s_cselect_b32 s41, s23, s39
	s_cselect_b32 s40, s31, s38
	s_cselect_b32 s39, s25, s64
	s_cselect_b32 s38, s62, s63
	v_lshl_add_u64 v[160:161], s[36:37], 0, v[136:137]
	s_add_i32 m0, s50, 0xc000
	ds_read_b128 v[184:187], v165
	ds_read_b128 v[188:191], v165 offset:1024
	ds_read_b128 v[192:195], v165 offset:2048
	ds_read_b128 v[196:199], v165 offset:3072
	ds_read_b128 v[200:203], v165 offset:4096
	ds_read_b128 v[204:207], v165 offset:5120
	ds_read_b128 v[208:211], v165 offset:6144
	ds_read_b128 v[212:215], v165 offset:7168
	global_load_lds_dwordx4 v[160:161], off
	s_add_i32 m0, s50, 0xe000
	v_lshl_add_u64 v[160:161], s[36:37], 0, v[138:139]
	global_load_lds_dwordx4 v[160:161], off
	s_waitcnt vmcnt(8) lgkmcnt(0)
	s_barrier
	s_setprio 1
	v_mfma_f32_16x16x32_bf16 v[124:127], v[144:147], v[184:187], v[124:127]
	v_mfma_f32_16x16x32_bf16 v[120:123], v[152:155], v[184:187], v[120:123]
	v_mfma_f32_16x16x32_bf16 v[108:111], v[144:147], v[192:195], v[108:111]
	v_mfma_f32_16x16x32_bf16 v[104:107], v[152:155], v[192:195], v[104:107]
	v_mfma_f32_16x16x32_bf16 v[92:95], v[144:147], v[200:203], v[92:95]
	v_mfma_f32_16x16x32_bf16 v[88:91], v[152:155], v[200:203], v[88:91]
	v_mfma_f32_16x16x32_bf16 v[76:79], v[144:147], v[208:211], v[76:79]
	v_mfma_f32_16x16x32_bf16 v[72:75], v[152:155], v[208:211], v[72:75]
	v_mfma_f32_16x16x32_bf16 v[124:127], v[148:151], v[188:191], v[124:127]
	v_mfma_f32_16x16x32_bf16 v[120:123], v[156:159], v[188:191], v[120:123]
	v_mfma_f32_16x16x32_bf16 v[108:111], v[148:151], v[196:199], v[108:111]
	v_mfma_f32_16x16x32_bf16 v[104:107], v[156:159], v[196:199], v[104:107]
	v_mfma_f32_16x16x32_bf16 v[92:95], v[148:151], v[204:207], v[92:95]
	v_mfma_f32_16x16x32_bf16 v[88:91], v[156:159], v[204:207], v[88:91]
	v_mfma_f32_16x16x32_bf16 v[76:79], v[148:151], v[212:215], v[76:79]
	v_mfma_f32_16x16x32_bf16 v[72:75], v[156:159], v[212:215], v[72:75]
	v_mfma_f32_16x16x32_bf16 v[116:119], v[168:171], v[184:187], v[116:119]
	v_mfma_f32_16x16x32_bf16 v[112:115], v[176:179], v[184:187], v[112:115]
	v_mfma_f32_16x16x32_bf16 v[100:103], v[168:171], v[192:195], v[100:103]
	v_mfma_f32_16x16x32_bf16 v[96:99], v[176:179], v[192:195], v[96:99]
	v_mfma_f32_16x16x32_bf16 v[84:87], v[168:171], v[200:203], v[84:87]
	v_mfma_f32_16x16x32_bf16 v[80:83], v[176:179], v[200:203], v[80:83]
	v_mfma_f32_16x16x32_bf16 v[68:71], v[168:171], v[208:211], v[68:71]
	v_mfma_f32_16x16x32_bf16 v[64:67], v[176:179], v[208:211], v[64:67]
	v_mfma_f32_16x16x32_bf16 v[116:119], v[172:175], v[188:191], v[116:119]
	v_mfma_f32_16x16x32_bf16 v[112:115], v[180:183], v[188:191], v[112:115]
	v_mfma_f32_16x16x32_bf16 v[100:103], v[172:175], v[196:199], v[100:103]
	v_mfma_f32_16x16x32_bf16 v[96:99], v[180:183], v[196:199], v[96:99]
	s_setprio 2
	s_barrier
	v_mfma_f32_16x16x32_bf16 v[84:87], v[172:175], v[204:207], v[84:87]
	v_mfma_f32_16x16x32_bf16 v[80:83], v[180:183], v[204:207], v[80:83]
	v_mfma_f32_16x16x32_bf16 v[68:71], v[172:175], v[212:215], v[68:71]
	v_mfma_f32_16x16x32_bf16 v[64:67], v[180:183], v[212:215], v[64:67]
	s_setprio 2
	s_mov_b32 m0, s50
	v_lshl_add_u64 v[218:219], s[40:41], 0, v[134:135]
	global_load_lds_dwordx4 v[218:219], off
	s_mov_b32 m0, s51
	v_lshl_add_u64 v[220:221], s[40:41], 0, v[130:131]
	global_load_lds_dwordx4 v[220:221], off
	s_add_i32 s66, s59, s47
	v_lshl_add_u64 v[160:161], s[38:39], 0, v[132:133]
	s_mov_b32 m0, s66
	ds_read_b128 v[184:187], v165 offset:16384
	ds_read_b128 v[188:191], v165 offset:17408
	ds_read_b128 v[192:195], v165 offset:18432
	ds_read_b128 v[196:199], v165 offset:19456
	ds_read_b128 v[200:203], v165 offset:20480
	ds_read_b128 v[204:207], v165 offset:21504
	ds_read_b128 v[208:211], v165 offset:22528
	ds_read_b128 v[212:215], v165 offset:23552
	global_load_lds_dwordx4 v[160:161], off
	s_add_i32 m0, s66, 0x2000
	s_add_u32 s66, s38, 0x40000
	v_lshl_add_u64 v[216:217], s[38:39], 0, v[128:129]
	s_addc_u32 s67, s39, 0
	s_add_i32 s68, s60, s47
	global_load_lds_dwordx4 v[216:217], off
	v_lshl_add_u64 v[248:249], s[66:67], 0, v[132:133]
	s_mov_b32 m0, s68
	global_load_lds_dwordx4 v[248:249], off
	s_add_i32 m0, s68, 0x2000
	v_lshl_add_u64 v[248:249], s[66:67], 0, v[128:129]
	global_load_lds_dwordx4 v[248:249], off
	s_waitcnt vmcnt(8) lgkmcnt(0)
	s_barrier
	s_setprio 1
	v_mfma_f32_16x16x32_bf16 v[60:63], v[144:147], v[184:187], v[60:63]
	v_mfma_f32_16x16x32_bf16 v[56:59], v[152:155], v[184:187], v[56:59]
	v_mfma_f32_16x16x32_bf16 v[44:47], v[144:147], v[192:195], v[44:47]
	v_mfma_f32_16x16x32_bf16 v[40:43], v[152:155], v[192:195], v[40:43]
	v_mfma_f32_16x16x32_bf16 v[28:31], v[144:147], v[200:203], v[28:31]
	v_mfma_f32_16x16x32_bf16 v[24:27], v[152:155], v[200:203], v[24:27]
	v_mfma_f32_16x16x32_bf16 v[12:15], v[144:147], v[208:211], v[12:15]
	v_mfma_f32_16x16x32_bf16 v[8:11], v[152:155], v[208:211], v[8:11]
	v_mfma_f32_16x16x32_bf16 v[60:63], v[148:151], v[188:191], v[60:63]
	v_mfma_f32_16x16x32_bf16 v[56:59], v[156:159], v[188:191], v[56:59]
	v_mfma_f32_16x16x32_bf16 v[44:47], v[148:151], v[196:199], v[44:47]
	v_mfma_f32_16x16x32_bf16 v[40:43], v[156:159], v[196:199], v[40:43]
	v_mfma_f32_16x16x32_bf16 v[28:31], v[148:151], v[204:207], v[28:31]
	v_mfma_f32_16x16x32_bf16 v[24:27], v[156:159], v[204:207], v[24:27]
	v_mfma_f32_16x16x32_bf16 v[12:15], v[148:151], v[212:215], v[12:15]
	v_mfma_f32_16x16x32_bf16 v[8:11], v[156:159], v[212:215], v[8:11]
	v_mfma_f32_16x16x32_bf16 v[52:55], v[168:171], v[184:187], v[52:55]
	v_mfma_f32_16x16x32_bf16 v[48:51], v[176:179], v[184:187], v[48:51]
	v_mfma_f32_16x16x32_bf16 v[36:39], v[168:171], v[192:195], v[36:39]
	v_mfma_f32_16x16x32_bf16 v[32:35], v[176:179], v[192:195], v[32:35]
	v_mfma_f32_16x16x32_bf16 v[20:23], v[168:171], v[200:203], v[20:23]
	v_mfma_f32_16x16x32_bf16 v[16:19], v[176:179], v[200:203], v[16:19]
	v_mfma_f32_16x16x32_bf16 v[4:7], v[168:171], v[208:211], v[4:7]
	v_mfma_f32_16x16x32_bf16 v[0:3], v[176:179], v[208:211], v[0:3]
	v_mfma_f32_16x16x32_bf16 v[52:55], v[172:175], v[188:191], v[52:55]
	v_mfma_f32_16x16x32_bf16 v[48:51], v[180:183], v[188:191], v[48:51]
	v_mfma_f32_16x16x32_bf16 v[36:39], v[172:175], v[196:199], v[36:39]
	v_mfma_f32_16x16x32_bf16 v[32:35], v[180:183], v[196:199], v[32:35]
	s_setprio 2
	s_barrier
	v_mfma_f32_16x16x32_bf16 v[20:23], v[172:175], v[204:207], v[20:23]
	v_mfma_f32_16x16x32_bf16 v[16:19], v[180:183], v[204:207], v[16:19]
	v_mfma_f32_16x16x32_bf16 v[4:7], v[172:175], v[212:215], v[4:7]
	v_mfma_f32_16x16x32_bf16 v[0:3], v[180:183], v[212:215], v[0:3]
	s_setprio 0
	s_add_i32 s66, 0, 0x18000
	s_add_i32 s67, 0, 0x1c000
	v_add_u32_e32 v156, s66, v162
	v_add_u32_e32 v167, s67, v162
	ds_read_b128 v[144:147], v156
	ds_read_b128 v[148:151], v156 offset:1024
	ds_read_b128 v[152:155], v156 offset:2048
	ds_read_b128 v[156:159], v156 offset:3072
	ds_read_b128 v[168:171], v167
	ds_read_b128 v[172:175], v167 offset:1024
	ds_read_b128 v[176:179], v167 offset:2048
	ds_read_b128 v[180:183], v167 offset:3072
	s_add_u32 s40, s40, 0x40000
	s_addc_u32 s41, s41, 0
	s_mov_b32 m0, s54
	v_lshl_add_u64 v[222:223], s[40:41], 0, v[134:135]
	ds_read_b128 v[184:187], v165 offset:32768
	ds_read_b128 v[188:191], v165 offset:33792
	ds_read_b128 v[192:195], v165 offset:34816
	ds_read_b128 v[196:199], v165 offset:35840
	ds_read_b128 v[200:203], v165 offset:36864
	ds_read_b128 v[204:207], v165 offset:37888
	ds_read_b128 v[208:211], v165 offset:38912
	ds_read_b128 v[212:215], v165 offset:39936
	global_load_lds_dwordx4 v[222:223], off
	s_mov_b32 m0, s55
	v_lshl_add_u64 v[222:223], s[40:41], 0, v[130:131]
	global_load_lds_dwordx4 v[222:223], off
	s_waitcnt vmcnt(8) lgkmcnt(0)
	s_barrier
	s_setprio 1
	v_mfma_f32_16x16x32_bf16 v[124:127], v[144:147], v[184:187], v[124:127]
	v_mfma_f32_16x16x32_bf16 v[120:123], v[152:155], v[184:187], v[120:123]
	v_mfma_f32_16x16x32_bf16 v[108:111], v[144:147], v[192:195], v[108:111]
	v_mfma_f32_16x16x32_bf16 v[104:107], v[152:155], v[192:195], v[104:107]
	v_mfma_f32_16x16x32_bf16 v[92:95], v[144:147], v[200:203], v[92:95]
	v_mfma_f32_16x16x32_bf16 v[88:91], v[152:155], v[200:203], v[88:91]
	v_mfma_f32_16x16x32_bf16 v[76:79], v[144:147], v[208:211], v[76:79]
	v_mfma_f32_16x16x32_bf16 v[72:75], v[152:155], v[208:211], v[72:75]
	v_mfma_f32_16x16x32_bf16 v[124:127], v[148:151], v[188:191], v[124:127]
	v_mfma_f32_16x16x32_bf16 v[120:123], v[156:159], v[188:191], v[120:123]
	v_mfma_f32_16x16x32_bf16 v[108:111], v[148:151], v[196:199], v[108:111]
	v_mfma_f32_16x16x32_bf16 v[104:107], v[156:159], v[196:199], v[104:107]
	v_mfma_f32_16x16x32_bf16 v[92:95], v[148:151], v[204:207], v[92:95]
	v_mfma_f32_16x16x32_bf16 v[88:91], v[156:159], v[204:207], v[88:91]
	v_mfma_f32_16x16x32_bf16 v[76:79], v[148:151], v[212:215], v[76:79]
	v_mfma_f32_16x16x32_bf16 v[72:75], v[156:159], v[212:215], v[72:75]
	v_mfma_f32_16x16x32_bf16 v[116:119], v[168:171], v[184:187], v[116:119]
	v_mfma_f32_16x16x32_bf16 v[112:115], v[176:179], v[184:187], v[112:115]
	v_mfma_f32_16x16x32_bf16 v[100:103], v[168:171], v[192:195], v[100:103]
	v_mfma_f32_16x16x32_bf16 v[96:99], v[176:179], v[192:195], v[96:99]
	v_mfma_f32_16x16x32_bf16 v[84:87], v[168:171], v[200:203], v[84:87]
	v_mfma_f32_16x16x32_bf16 v[80:83], v[176:179], v[200:203], v[80:83]
	v_mfma_f32_16x16x32_bf16 v[68:71], v[168:171], v[208:211], v[68:71]
	v_mfma_f32_16x16x32_bf16 v[64:67], v[176:179], v[208:211], v[64:67]
	v_mfma_f32_16x16x32_bf16 v[116:119], v[172:175], v[188:191], v[116:119]
	v_mfma_f32_16x16x32_bf16 v[112:115], v[180:183], v[188:191], v[112:115]
	v_mfma_f32_16x16x32_bf16 v[100:103], v[172:175], v[196:199], v[100:103]
	v_mfma_f32_16x16x32_bf16 v[96:99], v[180:183], v[196:199], v[96:99]
	s_setprio 2
	s_barrier
	v_mfma_f32_16x16x32_bf16 v[84:87], v[172:175], v[204:207], v[84:87]
	v_mfma_f32_16x16x32_bf16 v[80:83], v[180:183], v[204:207], v[80:83]
	v_mfma_f32_16x16x32_bf16 v[68:71], v[172:175], v[212:215], v[68:71]
	v_mfma_f32_16x16x32_bf16 v[64:67], v[180:183], v[212:215], v[64:67]
	s_setprio 2
	s_mov_b32 m0, s57
	v_lshl_add_u64 v[248:249], v[218:219], 0, s[16:17]
	global_load_lds_dwordx4 v[248:249], off
	s_mov_b32 m0, s58
	v_lshl_add_u64 v[248:249], v[220:221], 0, s[16:17]
	global_load_lds_dwordx4 v[248:249], off
	s_add_i32 s40, s66, s47
	v_lshl_add_u64 v[160:161], v[160:161], 0, s[16:17]
	s_mov_b32 m0, s40
	ds_read_b128 v[184:187], v165 offset:49152
	ds_read_b128 v[188:191], v165 offset:50176
	ds_read_b128 v[192:195], v165 offset:51200
	ds_read_b128 v[196:199], v165 offset:52224
	ds_read_b128 v[200:203], v165 offset:53248
	ds_read_b128 v[204:207], v165 offset:54272
	ds_read_b128 v[208:211], v165 offset:55296
	ds_read_b128 v[212:215], v165 offset:56320
	global_load_lds_dwordx4 v[160:161], off
	s_add_i32 m0, s40, 0x2000
	s_add_u32 s38, s38, 0x40080
	v_lshl_add_u64 v[160:161], v[216:217], 0, s[16:17]
	s_addc_u32 s39, s39, 0
	s_add_i32 s40, s67, s47
	global_load_lds_dwordx4 v[160:161], off
	s_mov_b32 m0, s40
	v_lshl_add_u64 v[160:161], s[38:39], 0, v[132:133]
	global_load_lds_dwordx4 v[160:161], off
	s_add_i32 m0, s40, 0x2000
	v_lshl_add_u64 v[160:161], s[38:39], 0, v[128:129]
	global_load_lds_dwordx4 v[160:161], off
	s_waitcnt vmcnt(8) lgkmcnt(0)
	s_barrier
	s_setprio 1
	v_mfma_f32_16x16x32_bf16 v[60:63], v[144:147], v[184:187], v[60:63]
	v_mfma_f32_16x16x32_bf16 v[56:59], v[152:155], v[184:187], v[56:59]
	v_mfma_f32_16x16x32_bf16 v[44:47], v[144:147], v[192:195], v[44:47]
	v_mfma_f32_16x16x32_bf16 v[40:43], v[152:155], v[192:195], v[40:43]
	v_mfma_f32_16x16x32_bf16 v[28:31], v[144:147], v[200:203], v[28:31]
	v_mfma_f32_16x16x32_bf16 v[24:27], v[152:155], v[200:203], v[24:27]
	v_mfma_f32_16x16x32_bf16 v[12:15], v[144:147], v[208:211], v[12:15]
	v_mfma_f32_16x16x32_bf16 v[8:11], v[152:155], v[208:211], v[8:11]
	v_mfma_f32_16x16x32_bf16 v[60:63], v[148:151], v[188:191], v[60:63]
	v_mfma_f32_16x16x32_bf16 v[56:59], v[156:159], v[188:191], v[56:59]
	v_mfma_f32_16x16x32_bf16 v[44:47], v[148:151], v[196:199], v[44:47]
	v_mfma_f32_16x16x32_bf16 v[40:43], v[156:159], v[196:199], v[40:43]
	v_mfma_f32_16x16x32_bf16 v[28:31], v[148:151], v[204:207], v[28:31]
	v_mfma_f32_16x16x32_bf16 v[24:27], v[156:159], v[204:207], v[24:27]
	v_mfma_f32_16x16x32_bf16 v[12:15], v[148:151], v[212:215], v[12:15]
	v_mfma_f32_16x16x32_bf16 v[8:11], v[156:159], v[212:215], v[8:11]
	v_mfma_f32_16x16x32_bf16 v[52:55], v[168:171], v[184:187], v[52:55]
	v_mfma_f32_16x16x32_bf16 v[48:51], v[176:179], v[184:187], v[48:51]
	v_mfma_f32_16x16x32_bf16 v[36:39], v[168:171], v[192:195], v[36:39]
	v_mfma_f32_16x16x32_bf16 v[32:35], v[176:179], v[192:195], v[32:35]
	v_mfma_f32_16x16x32_bf16 v[20:23], v[168:171], v[200:203], v[20:23]
	v_mfma_f32_16x16x32_bf16 v[16:19], v[176:179], v[200:203], v[16:19]
	v_mfma_f32_16x16x32_bf16 v[4:7], v[168:171], v[208:211], v[4:7]
	v_mfma_f32_16x16x32_bf16 v[0:3], v[176:179], v[208:211], v[0:3]
	v_mfma_f32_16x16x32_bf16 v[52:55], v[172:175], v[188:191], v[52:55]
	v_mfma_f32_16x16x32_bf16 v[48:51], v[180:183], v[188:191], v[48:51]
	v_mfma_f32_16x16x32_bf16 v[36:39], v[172:175], v[196:199], v[36:39]
	v_mfma_f32_16x16x32_bf16 v[32:35], v[180:183], v[196:199], v[32:35]
	s_setprio 2
	s_barrier
	v_mfma_f32_16x16x32_bf16 v[20:23], v[172:175], v[204:207], v[20:23]
	v_mfma_f32_16x16x32_bf16 v[16:19], v[180:183], v[204:207], v[16:19]
	v_mfma_f32_16x16x32_bf16 v[4:7], v[172:175], v[212:215], v[4:7]
	v_mfma_f32_16x16x32_bf16 v[0:3], v[180:183], v[212:215], v[0:3]
	s_setprio 0
	s_add_i32 s65, s65, 2
	s_add_u32 s36, s36, 0x100
	s_addc_u32 s37, s37, 0
	s_add_u32 s63, s63, 0x100
	s_addc_u32 s64, s64, 0
	s_cmp_gt_u32 s65, 13
	s_cbranch_scc0 .LBB0_784

.LBB0_865:
	s_add_u32 s62, s28, 0x100
	s_addc_u32 s63, s29, 0
	s_mov_b32 s64, -2
	ds_read_b128 v[120:123], v233
	ds_read_b128 v[124:127], v233 offset:1024
	ds_read_b128 v[136:139], v233 offset:2048
	ds_read_b128 v[140:143], v233 offset:3072
	ds_read_b128 v[144:147], v234
	ds_read_b128 v[148:151], v234 offset:1024
	ds_read_b128 v[152:155], v234 offset:2048
	ds_read_b128 v[156:159], v234 offset:3072
	s_add_u32 s28, s26, 0x100
	s_addc_u32 s29, s27, 0
	s_cmp_eq_u32 s64, 40
	s_cselect_b32 s37, s7, s29
	s_cselect_b32 s36, s6, s28
	s_cselect_b32 s31, s25, s63
	s_cselect_b32 s30, s24, s62
	v_lshl_add_u64 v[208:209], s[26:27], 0, v[192:193]
	s_add_i32 m0, s44, 0xc000
	ds_read_b128 v[160:163], v235
	ds_read_b128 v[164:167], v235 offset:1024
	ds_read_b128 v[168:171], v235 offset:2048
	ds_read_b128 v[172:175], v235 offset:3072
	ds_read_b128 v[176:179], v235 offset:4096
	ds_read_b128 v[180:183], v235 offset:5120
	ds_read_b128 v[200:203], v235 offset:6144
	ds_read_b128 v[204:207], v235 offset:7168
	global_load_lds_dwordx4 v[208:209], off
	s_add_i32 m0, s44, 0xe000
	v_lshl_add_u64 v[208:209], s[26:27], 0, v[194:195]
	global_load_lds_dwordx4 v[208:209], off
	s_waitcnt vmcnt(8) lgkmcnt(0)
	s_barrier
	s_setprio 1
	v_mfma_f32_16x16x32_bf16 v[132:135], v[120:123], v[160:163], 0
	v_mfma_f32_16x16x32_bf16 v[128:131], v[136:139], v[160:163], 0
	v_mfma_f32_16x16x32_bf16 v[108:111], v[120:123], v[168:171], 0
	v_mfma_f32_16x16x32_bf16 v[104:107], v[136:139], v[168:171], 0
	v_mfma_f32_16x16x32_bf16 v[92:95], v[120:123], v[176:179], 0
	v_mfma_f32_16x16x32_bf16 v[88:91], v[136:139], v[176:179], 0
	v_mfma_f32_16x16x32_bf16 v[76:79], v[120:123], v[200:203], 0
	v_mfma_f32_16x16x32_bf16 v[72:75], v[136:139], v[200:203], 0
	v_mfma_f32_16x16x32_bf16 v[132:135], v[124:127], v[164:167], v[132:135]
	v_mfma_f32_16x16x32_bf16 v[128:131], v[140:143], v[164:167], v[128:131]
	v_mfma_f32_16x16x32_bf16 v[108:111], v[124:127], v[172:175], v[108:111]
	v_mfma_f32_16x16x32_bf16 v[104:107], v[140:143], v[172:175], v[104:107]
	v_mfma_f32_16x16x32_bf16 v[92:95], v[124:127], v[180:183], v[92:95]
	v_mfma_f32_16x16x32_bf16 v[88:91], v[140:143], v[180:183], v[88:91]
	v_mfma_f32_16x16x32_bf16 v[76:79], v[124:127], v[204:207], v[76:79]
	v_mfma_f32_16x16x32_bf16 v[72:75], v[140:143], v[204:207], v[72:75]
	v_mfma_f32_16x16x32_bf16 v[116:119], v[144:147], v[160:163], 0
	v_mfma_f32_16x16x32_bf16 v[112:115], v[152:155], v[160:163], 0
	v_mfma_f32_16x16x32_bf16 v[100:103], v[144:147], v[168:171], 0
	v_mfma_f32_16x16x32_bf16 v[96:99], v[152:155], v[168:171], 0
	v_mfma_f32_16x16x32_bf16 v[84:87], v[144:147], v[176:179], 0
	v_mfma_f32_16x16x32_bf16 v[80:83], v[152:155], v[176:179], 0
	v_mfma_f32_16x16x32_bf16 v[68:71], v[144:147], v[200:203], 0
	v_mfma_f32_16x16x32_bf16 v[64:67], v[152:155], v[200:203], 0
	v_mfma_f32_16x16x32_bf16 v[116:119], v[148:151], v[164:167], v[116:119]
	v_mfma_f32_16x16x32_bf16 v[112:115], v[156:159], v[164:167], v[112:115]
	v_mfma_f32_16x16x32_bf16 v[100:103], v[148:151], v[172:175], v[100:103]
	v_mfma_f32_16x16x32_bf16 v[96:99], v[156:159], v[172:175], v[96:99]
	s_setprio 2
	s_barrier
	v_mfma_f32_16x16x32_bf16 v[84:87], v[148:151], v[180:183], v[84:87]
	v_mfma_f32_16x16x32_bf16 v[80:83], v[156:159], v[180:183], v[80:83]
	v_mfma_f32_16x16x32_bf16 v[68:71], v[148:151], v[204:207], v[68:71]
	v_mfma_f32_16x16x32_bf16 v[64:67], v[156:159], v[204:207], v[64:67]
	s_setprio 2
	s_mov_b32 m0, s44
	v_lshl_add_u64 v[212:213], s[36:37], 0, v[184:185]
	global_load_lds_dwordx4 v[212:213], off
	s_mov_b32 m0, s45
	v_lshl_add_u64 v[214:215], s[36:37], 0, v[188:189]
	global_load_lds_dwordx4 v[214:215], off
	s_add_i32 s26, s56, s43
	v_lshl_add_u64 v[208:209], s[30:31], 0, v[186:187]
	s_mov_b32 m0, s26
	ds_read_b128 v[160:163], v235 offset:16384
	ds_read_b128 v[164:167], v235 offset:17408
	ds_read_b128 v[168:171], v235 offset:18432
	ds_read_b128 v[172:175], v235 offset:19456
	ds_read_b128 v[176:179], v235 offset:20480
	ds_read_b128 v[180:183], v235 offset:21504
	ds_read_b128 v[200:203], v235 offset:22528
	ds_read_b128 v[204:207], v235 offset:23552
	global_load_lds_dwordx4 v[208:209], off
	s_add_i32 m0, s26, 0x2000
	s_add_u32 s26, s30, 0xb0000
	v_lshl_add_u64 v[210:211], s[30:31], 0, v[190:191]
	s_addc_u32 s27, s31, 0
	s_add_i32 s65, s57, s43
	global_load_lds_dwordx4 v[210:211], off
	v_lshl_add_u64 v[250:251], s[26:27], 0, v[186:187]
	s_mov_b32 m0, s65
	global_load_lds_dwordx4 v[250:251], off
	s_add_i32 m0, s65, 0x2000
	v_lshl_add_u64 v[250:251], s[26:27], 0, v[190:191]
	global_load_lds_dwordx4 v[250:251], off
	s_waitcnt vmcnt(8) lgkmcnt(0)
	s_barrier
	s_setprio 1
	v_mfma_f32_16x16x32_bf16 v[60:63], v[120:123], v[160:163], 0
	v_mfma_f32_16x16x32_bf16 v[56:59], v[136:139], v[160:163], 0
	v_mfma_f32_16x16x32_bf16 v[44:47], v[120:123], v[168:171], 0
	v_mfma_f32_16x16x32_bf16 v[40:43], v[136:139], v[168:171], 0
	v_mfma_f32_16x16x32_bf16 v[28:31], v[120:123], v[176:179], 0
	v_mfma_f32_16x16x32_bf16 v[24:27], v[136:139], v[176:179], 0
	v_mfma_f32_16x16x32_bf16 v[12:15], v[120:123], v[200:203], 0
	v_mfma_f32_16x16x32_bf16 v[8:11], v[136:139], v[200:203], 0
	v_mfma_f32_16x16x32_bf16 v[60:63], v[124:127], v[164:167], v[60:63]
	v_mfma_f32_16x16x32_bf16 v[56:59], v[140:143], v[164:167], v[56:59]
	v_mfma_f32_16x16x32_bf16 v[44:47], v[124:127], v[172:175], v[44:47]
	v_mfma_f32_16x16x32_bf16 v[40:43], v[140:143], v[172:175], v[40:43]
	v_mfma_f32_16x16x32_bf16 v[28:31], v[124:127], v[180:183], v[28:31]
	v_mfma_f32_16x16x32_bf16 v[24:27], v[140:143], v[180:183], v[24:27]
	v_mfma_f32_16x16x32_bf16 v[12:15], v[124:127], v[204:207], v[12:15]
	v_mfma_f32_16x16x32_bf16 v[8:11], v[140:143], v[204:207], v[8:11]
	v_mfma_f32_16x16x32_bf16 v[52:55], v[144:147], v[160:163], 0
	v_mfma_f32_16x16x32_bf16 v[48:51], v[152:155], v[160:163], 0
	v_mfma_f32_16x16x32_bf16 v[36:39], v[144:147], v[168:171], 0
	v_mfma_f32_16x16x32_bf16 v[32:35], v[152:155], v[168:171], 0
	v_mfma_f32_16x16x32_bf16 v[20:23], v[144:147], v[176:179], 0
	v_mfma_f32_16x16x32_bf16 v[16:19], v[152:155], v[176:179], 0
	v_mfma_f32_16x16x32_bf16 v[4:7], v[144:147], v[200:203], 0
	v_mfma_f32_16x16x32_bf16 v[0:3], v[152:155], v[200:203], 0
	v_mfma_f32_16x16x32_bf16 v[52:55], v[148:151], v[164:167], v[52:55]
	v_mfma_f32_16x16x32_bf16 v[48:51], v[156:159], v[164:167], v[48:51]
	v_mfma_f32_16x16x32_bf16 v[36:39], v[148:151], v[172:175], v[36:39]
	v_mfma_f32_16x16x32_bf16 v[32:35], v[156:159], v[172:175], v[32:35]
	s_setprio 2
	s_barrier
	v_mfma_f32_16x16x32_bf16 v[20:23], v[148:151], v[180:183], v[20:23]
	v_mfma_f32_16x16x32_bf16 v[16:19], v[156:159], v[180:183], v[16:19]
	v_mfma_f32_16x16x32_bf16 v[4:7], v[148:151], v[204:207], v[4:7]
	v_mfma_f32_16x16x32_bf16 v[0:3], v[156:159], v[204:207], v[0:3]
	s_setprio 0
	s_add_i32 s65, 0, 0x18000
	s_add_i32 s66, 0, 0x1c000
	v_add_u32_e32 v140, s65, v232
	v_add_u32_e32 v156, s66, v232
	ds_read_b128 v[120:123], v140
	ds_read_b128 v[124:127], v140 offset:1024
	ds_read_b128 v[136:139], v140 offset:2048
	ds_read_b128 v[140:143], v140 offset:3072
	ds_read_b128 v[144:147], v156
	ds_read_b128 v[148:151], v156 offset:1024
	ds_read_b128 v[152:155], v156 offset:2048
	ds_read_b128 v[156:159], v156 offset:3072
	s_add_u32 s26, s36, 0xb0000
	s_addc_u32 s27, s37, 0
	s_mov_b32 m0, s46
	v_lshl_add_u64 v[216:217], s[26:27], 0, v[184:185]
	ds_read_b128 v[160:163], v235 offset:32768
	ds_read_b128 v[164:167], v235 offset:33792
	ds_read_b128 v[168:171], v235 offset:34816
	ds_read_b128 v[172:175], v235 offset:35840
	ds_read_b128 v[176:179], v235 offset:36864
	ds_read_b128 v[180:183], v235 offset:37888
	ds_read_b128 v[200:203], v235 offset:38912
	ds_read_b128 v[204:207], v235 offset:39936
	global_load_lds_dwordx4 v[216:217], off
	s_mov_b32 m0, s47
	v_lshl_add_u64 v[216:217], s[26:27], 0, v[188:189]
	global_load_lds_dwordx4 v[216:217], off
	s_waitcnt vmcnt(8) lgkmcnt(0)
	s_barrier
	s_setprio 1
	v_mfma_f32_16x16x32_bf16 v[132:135], v[120:123], v[160:163], v[132:135]
	v_mfma_f32_16x16x32_bf16 v[128:131], v[136:139], v[160:163], v[128:131]
	v_mfma_f32_16x16x32_bf16 v[108:111], v[120:123], v[168:171], v[108:111]
	v_mfma_f32_16x16x32_bf16 v[104:107], v[136:139], v[168:171], v[104:107]
	v_mfma_f32_16x16x32_bf16 v[92:95], v[120:123], v[176:179], v[92:95]
	v_mfma_f32_16x16x32_bf16 v[88:91], v[136:139], v[176:179], v[88:91]
	v_mfma_f32_16x16x32_bf16 v[76:79], v[120:123], v[200:203], v[76:79]
	v_mfma_f32_16x16x32_bf16 v[72:75], v[136:139], v[200:203], v[72:75]
	v_mfma_f32_16x16x32_bf16 v[132:135], v[124:127], v[164:167], v[132:135]
	v_mfma_f32_16x16x32_bf16 v[128:131], v[140:143], v[164:167], v[128:131]
	v_mfma_f32_16x16x32_bf16 v[108:111], v[124:127], v[172:175], v[108:111]
	v_mfma_f32_16x16x32_bf16 v[104:107], v[140:143], v[172:175], v[104:107]
	v_mfma_f32_16x16x32_bf16 v[92:95], v[124:127], v[180:183], v[92:95]
	v_mfma_f32_16x16x32_bf16 v[88:91], v[140:143], v[180:183], v[88:91]
	v_mfma_f32_16x16x32_bf16 v[76:79], v[124:127], v[204:207], v[76:79]
	v_mfma_f32_16x16x32_bf16 v[72:75], v[140:143], v[204:207], v[72:75]
	v_mfma_f32_16x16x32_bf16 v[116:119], v[144:147], v[160:163], v[116:119]
	v_mfma_f32_16x16x32_bf16 v[112:115], v[152:155], v[160:163], v[112:115]
	v_mfma_f32_16x16x32_bf16 v[100:103], v[144:147], v[168:171], v[100:103]
	v_mfma_f32_16x16x32_bf16 v[96:99], v[152:155], v[168:171], v[96:99]
	v_mfma_f32_16x16x32_bf16 v[84:87], v[144:147], v[176:179], v[84:87]
	v_mfma_f32_16x16x32_bf16 v[80:83], v[152:155], v[176:179], v[80:83]
	v_mfma_f32_16x16x32_bf16 v[68:71], v[144:147], v[200:203], v[68:71]
	v_mfma_f32_16x16x32_bf16 v[64:67], v[152:155], v[200:203], v[64:67]
	v_mfma_f32_16x16x32_bf16 v[116:119], v[148:151], v[164:167], v[116:119]
	v_mfma_f32_16x16x32_bf16 v[112:115], v[156:159], v[164:167], v[112:115]
	v_mfma_f32_16x16x32_bf16 v[100:103], v[148:151], v[172:175], v[100:103]
	v_mfma_f32_16x16x32_bf16 v[96:99], v[156:159], v[172:175], v[96:99]
	s_setprio 2
	s_barrier
	v_mfma_f32_16x16x32_bf16 v[84:87], v[148:151], v[180:183], v[84:87]
	v_mfma_f32_16x16x32_bf16 v[80:83], v[156:159], v[180:183], v[80:83]
	v_mfma_f32_16x16x32_bf16 v[68:71], v[148:151], v[204:207], v[68:71]
	v_mfma_f32_16x16x32_bf16 v[64:67], v[156:159], v[204:207], v[64:67]
	s_setprio 2
	s_mov_b32 m0, s49
	v_lshl_add_u64 v[250:251], v[212:213], 0, s[20:21]
	global_load_lds_dwordx4 v[250:251], off
	s_mov_b32 m0, s50
	v_lshl_add_u64 v[250:251], v[214:215], 0, s[20:21]
	global_load_lds_dwordx4 v[250:251], off
	s_add_i32 s26, s65, s43
	v_lshl_add_u64 v[208:209], v[208:209], 0, s[20:21]
	s_mov_b32 m0, s26
	ds_read_b128 v[160:163], v235 offset:49152
	ds_read_b128 v[164:167], v235 offset:50176
	ds_read_b128 v[168:171], v235 offset:51200
	ds_read_b128 v[172:175], v235 offset:52224
	ds_read_b128 v[176:179], v235 offset:53248
	ds_read_b128 v[180:183], v235 offset:54272
	ds_read_b128 v[200:203], v235 offset:55296
	ds_read_b128 v[204:207], v235 offset:56320
	global_load_lds_dwordx4 v[208:209], off
	s_add_i32 m0, s26, 0x2000
	s_add_u32 s26, s30, 0xb0080
	v_lshl_add_u64 v[208:209], v[210:211], 0, s[20:21]
	s_addc_u32 s27, s31, 0
	s_add_i32 s30, s66, s43
	global_load_lds_dwordx4 v[208:209], off
	s_mov_b32 m0, s30
	v_lshl_add_u64 v[208:209], s[26:27], 0, v[186:187]
	global_load_lds_dwordx4 v[208:209], off
	s_add_i32 m0, s30, 0x2000
	v_lshl_add_u64 v[208:209], s[26:27], 0, v[190:191]
	global_load_lds_dwordx4 v[208:209], off
	s_waitcnt vmcnt(8) lgkmcnt(0)
	s_barrier
	s_setprio 1
	v_mfma_f32_16x16x32_bf16 v[60:63], v[120:123], v[160:163], v[60:63]
	v_mfma_f32_16x16x32_bf16 v[56:59], v[136:139], v[160:163], v[56:59]
	v_mfma_f32_16x16x32_bf16 v[44:47], v[120:123], v[168:171], v[44:47]
	v_mfma_f32_16x16x32_bf16 v[40:43], v[136:139], v[168:171], v[40:43]
	v_mfma_f32_16x16x32_bf16 v[28:31], v[120:123], v[176:179], v[28:31]
	v_mfma_f32_16x16x32_bf16 v[24:27], v[136:139], v[176:179], v[24:27]
	v_mfma_f32_16x16x32_bf16 v[12:15], v[120:123], v[200:203], v[12:15]
	v_mfma_f32_16x16x32_bf16 v[8:11], v[136:139], v[200:203], v[8:11]
	v_mfma_f32_16x16x32_bf16 v[60:63], v[124:127], v[164:167], v[60:63]
	v_mfma_f32_16x16x32_bf16 v[56:59], v[140:143], v[164:167], v[56:59]
	v_mfma_f32_16x16x32_bf16 v[44:47], v[124:127], v[172:175], v[44:47]
	v_mfma_f32_16x16x32_bf16 v[40:43], v[140:143], v[172:175], v[40:43]
	v_mfma_f32_16x16x32_bf16 v[28:31], v[124:127], v[180:183], v[28:31]
	v_mfma_f32_16x16x32_bf16 v[24:27], v[140:143], v[180:183], v[24:27]
	v_mfma_f32_16x16x32_bf16 v[12:15], v[124:127], v[204:207], v[12:15]
	v_mfma_f32_16x16x32_bf16 v[8:11], v[140:143], v[204:207], v[8:11]
	v_mfma_f32_16x16x32_bf16 v[52:55], v[144:147], v[160:163], v[52:55]
	v_mfma_f32_16x16x32_bf16 v[48:51], v[152:155], v[160:163], v[48:51]
	v_mfma_f32_16x16x32_bf16 v[36:39], v[144:147], v[168:171], v[36:39]
	v_mfma_f32_16x16x32_bf16 v[32:35], v[152:155], v[168:171], v[32:35]
	v_mfma_f32_16x16x32_bf16 v[20:23], v[144:147], v[176:179], v[20:23]
	v_mfma_f32_16x16x32_bf16 v[16:19], v[152:155], v[176:179], v[16:19]
	v_mfma_f32_16x16x32_bf16 v[4:7], v[144:147], v[200:203], v[4:7]
	v_mfma_f32_16x16x32_bf16 v[0:3], v[152:155], v[200:203], v[0:3]
	v_mfma_f32_16x16x32_bf16 v[52:55], v[148:151], v[164:167], v[52:55]
	v_mfma_f32_16x16x32_bf16 v[48:51], v[156:159], v[164:167], v[48:51]
	v_mfma_f32_16x16x32_bf16 v[36:39], v[148:151], v[172:175], v[36:39]
	v_mfma_f32_16x16x32_bf16 v[32:35], v[156:159], v[172:175], v[32:35]
	s_setprio 2
	s_barrier
	v_mfma_f32_16x16x32_bf16 v[20:23], v[148:151], v[180:183], v[20:23]
	v_mfma_f32_16x16x32_bf16 v[16:19], v[156:159], v[180:183], v[16:19]
	v_mfma_f32_16x16x32_bf16 v[4:7], v[148:151], v[204:207], v[4:7]
	v_mfma_f32_16x16x32_bf16 v[0:3], v[156:159], v[204:207], v[0:3]
	s_setprio 0
	s_add_i32 s64, s64, 2
	s_add_u32 s62, s62, 0x100
	s_addc_u32 s63, s63, 0
	s_cmp_gt_u32 s64, 41
	s_mov_b64 s[26:27], s[28:29]
.LBB0_866:
	ds_read_b128 v[120:123], v233
	ds_read_b128 v[124:127], v233 offset:1024
	ds_read_b128 v[136:139], v233 offset:2048
	ds_read_b128 v[140:143], v233 offset:3072
	ds_read_b128 v[144:147], v234
	ds_read_b128 v[148:151], v234 offset:1024
	ds_read_b128 v[152:155], v234 offset:2048
	ds_read_b128 v[156:159], v234 offset:3072
	s_add_u32 s28, s26, 0x100
	s_addc_u32 s29, s27, 0
	s_cmp_eq_u32 s64, 40
	s_cselect_b32 s37, s7, s29
	s_cselect_b32 s36, s6, s28
	s_cselect_b32 s31, s25, s63
	s_cselect_b32 s30, s24, s62
	v_lshl_add_u64 v[208:209], s[26:27], 0, v[192:193]
	s_add_i32 m0, s44, 0xc000
	ds_read_b128 v[160:163], v235
	ds_read_b128 v[164:167], v235 offset:1024
	ds_read_b128 v[168:171], v235 offset:2048
	ds_read_b128 v[172:175], v235 offset:3072
	ds_read_b128 v[176:179], v235 offset:4096
	ds_read_b128 v[180:183], v235 offset:5120
	ds_read_b128 v[200:203], v235 offset:6144
	ds_read_b128 v[204:207], v235 offset:7168
	global_load_lds_dwordx4 v[208:209], off
	s_add_i32 m0, s44, 0xe000
	v_lshl_add_u64 v[208:209], s[26:27], 0, v[194:195]
	global_load_lds_dwordx4 v[208:209], off
	s_waitcnt vmcnt(8) lgkmcnt(0)
	s_barrier
	s_setprio 1
	v_mfma_f32_16x16x32_bf16 v[132:135], v[120:123], v[160:163], v[132:135]
	v_mfma_f32_16x16x32_bf16 v[128:131], v[136:139], v[160:163], v[128:131]
	v_mfma_f32_16x16x32_bf16 v[108:111], v[120:123], v[168:171], v[108:111]
	v_mfma_f32_16x16x32_bf16 v[104:107], v[136:139], v[168:171], v[104:107]
	v_mfma_f32_16x16x32_bf16 v[92:95], v[120:123], v[176:179], v[92:95]
	v_mfma_f32_16x16x32_bf16 v[88:91], v[136:139], v[176:179], v[88:91]
	v_mfma_f32_16x16x32_bf16 v[76:79], v[120:123], v[200:203], v[76:79]
	v_mfma_f32_16x16x32_bf16 v[72:75], v[136:139], v[200:203], v[72:75]
	v_mfma_f32_16x16x32_bf16 v[132:135], v[124:127], v[164:167], v[132:135]
	v_mfma_f32_16x16x32_bf16 v[128:131], v[140:143], v[164:167], v[128:131]
	v_mfma_f32_16x16x32_bf16 v[108:111], v[124:127], v[172:175], v[108:111]
	v_mfma_f32_16x16x32_bf16 v[104:107], v[140:143], v[172:175], v[104:107]
	v_mfma_f32_16x16x32_bf16 v[92:95], v[124:127], v[180:183], v[92:95]
	v_mfma_f32_16x16x32_bf16 v[88:91], v[140:143], v[180:183], v[88:91]
	v_mfma_f32_16x16x32_bf16 v[76:79], v[124:127], v[204:207], v[76:79]
	v_mfma_f32_16x16x32_bf16 v[72:75], v[140:143], v[204:207], v[72:75]
	v_mfma_f32_16x16x32_bf16 v[116:119], v[144:147], v[160:163], v[116:119]
	v_mfma_f32_16x16x32_bf16 v[112:115], v[152:155], v[160:163], v[112:115]
	v_mfma_f32_16x16x32_bf16 v[100:103], v[144:147], v[168:171], v[100:103]
	v_mfma_f32_16x16x32_bf16 v[96:99], v[152:155], v[168:171], v[96:99]
	v_mfma_f32_16x16x32_bf16 v[84:87], v[144:147], v[176:179], v[84:87]
	v_mfma_f32_16x16x32_bf16 v[80:83], v[152:155], v[176:179], v[80:83]
	v_mfma_f32_16x16x32_bf16 v[68:71], v[144:147], v[200:203], v[68:71]
	v_mfma_f32_16x16x32_bf16 v[64:67], v[152:155], v[200:203], v[64:67]
	v_mfma_f32_16x16x32_bf16 v[116:119], v[148:151], v[164:167], v[116:119]
	v_mfma_f32_16x16x32_bf16 v[112:115], v[156:159], v[164:167], v[112:115]
	v_mfma_f32_16x16x32_bf16 v[100:103], v[148:151], v[172:175], v[100:103]
	v_mfma_f32_16x16x32_bf16 v[96:99], v[156:159], v[172:175], v[96:99]
	s_setprio 2
	s_barrier
	v_mfma_f32_16x16x32_bf16 v[84:87], v[148:151], v[180:183], v[84:87]
	v_mfma_f32_16x16x32_bf16 v[80:83], v[156:159], v[180:183], v[80:83]
	v_mfma_f32_16x16x32_bf16 v[68:71], v[148:151], v[204:207], v[68:71]
	v_mfma_f32_16x16x32_bf16 v[64:67], v[156:159], v[204:207], v[64:67]
	s_setprio 2
	s_mov_b32 m0, s44
	v_lshl_add_u64 v[212:213], s[36:37], 0, v[184:185]
	global_load_lds_dwordx4 v[212:213], off
	s_mov_b32 m0, s45
	v_lshl_add_u64 v[214:215], s[36:37], 0, v[188:189]
	global_load_lds_dwordx4 v[214:215], off
	s_add_i32 s26, s56, s43
	v_lshl_add_u64 v[208:209], s[30:31], 0, v[186:187]
	s_mov_b32 m0, s26
	ds_read_b128 v[160:163], v235 offset:16384
	ds_read_b128 v[164:167], v235 offset:17408
	ds_read_b128 v[168:171], v235 offset:18432
	ds_read_b128 v[172:175], v235 offset:19456
	ds_read_b128 v[176:179], v235 offset:20480
	ds_read_b128 v[180:183], v235 offset:21504
	ds_read_b128 v[200:203], v235 offset:22528
	ds_read_b128 v[204:207], v235 offset:23552
	global_load_lds_dwordx4 v[208:209], off
	s_add_i32 m0, s26, 0x2000
	s_add_u32 s26, s30, 0xb0000
	v_lshl_add_u64 v[210:211], s[30:31], 0, v[190:191]
	s_addc_u32 s27, s31, 0
	s_add_i32 s65, s57, s43
	global_load_lds_dwordx4 v[210:211], off
	v_lshl_add_u64 v[250:251], s[26:27], 0, v[186:187]
	s_mov_b32 m0, s65
	global_load_lds_dwordx4 v[250:251], off
	s_add_i32 m0, s65, 0x2000
	v_lshl_add_u64 v[250:251], s[26:27], 0, v[190:191]
	global_load_lds_dwordx4 v[250:251], off
	s_waitcnt vmcnt(8) lgkmcnt(0)
	s_barrier
	s_setprio 1
	v_mfma_f32_16x16x32_bf16 v[60:63], v[120:123], v[160:163], v[60:63]
	v_mfma_f32_16x16x32_bf16 v[56:59], v[136:139], v[160:163], v[56:59]
	v_mfma_f32_16x16x32_bf16 v[44:47], v[120:123], v[168:171], v[44:47]
	v_mfma_f32_16x16x32_bf16 v[40:43], v[136:139], v[168:171], v[40:43]
	v_mfma_f32_16x16x32_bf16 v[28:31], v[120:123], v[176:179], v[28:31]
	v_mfma_f32_16x16x32_bf16 v[24:27], v[136:139], v[176:179], v[24:27]
	v_mfma_f32_16x16x32_bf16 v[12:15], v[120:123], v[200:203], v[12:15]
	v_mfma_f32_16x16x32_bf16 v[8:11], v[136:139], v[200:203], v[8:11]
	v_mfma_f32_16x16x32_bf16 v[60:63], v[124:127], v[164:167], v[60:63]
	v_mfma_f32_16x16x32_bf16 v[56:59], v[140:143], v[164:167], v[56:59]
	v_mfma_f32_16x16x32_bf16 v[44:47], v[124:127], v[172:175], v[44:47]
	v_mfma_f32_16x16x32_bf16 v[40:43], v[140:143], v[172:175], v[40:43]
	v_mfma_f32_16x16x32_bf16 v[28:31], v[124:127], v[180:183], v[28:31]
	v_mfma_f32_16x16x32_bf16 v[24:27], v[140:143], v[180:183], v[24:27]
	v_mfma_f32_16x16x32_bf16 v[12:15], v[124:127], v[204:207], v[12:15]
	v_mfma_f32_16x16x32_bf16 v[8:11], v[140:143], v[204:207], v[8:11]
	v_mfma_f32_16x16x32_bf16 v[52:55], v[144:147], v[160:163], v[52:55]
	v_mfma_f32_16x16x32_bf16 v[48:51], v[152:155], v[160:163], v[48:51]
	v_mfma_f32_16x16x32_bf16 v[36:39], v[144:147], v[168:171], v[36:39]
	v_mfma_f32_16x16x32_bf16 v[32:35], v[152:155], v[168:171], v[32:35]
	v_mfma_f32_16x16x32_bf16 v[20:23], v[144:147], v[176:179], v[20:23]
	v_mfma_f32_16x16x32_bf16 v[16:19], v[152:155], v[176:179], v[16:19]
	v_mfma_f32_16x16x32_bf16 v[4:7], v[144:147], v[200:203], v[4:7]
	v_mfma_f32_16x16x32_bf16 v[0:3], v[152:155], v[200:203], v[0:3]
	v_mfma_f32_16x16x32_bf16 v[52:55], v[148:151], v[164:167], v[52:55]
	v_mfma_f32_16x16x32_bf16 v[48:51], v[156:159], v[164:167], v[48:51]
	v_mfma_f32_16x16x32_bf16 v[36:39], v[148:151], v[172:175], v[36:39]
	v_mfma_f32_16x16x32_bf16 v[32:35], v[156:159], v[172:175], v[32:35]
	s_setprio 2
	s_barrier
	v_mfma_f32_16x16x32_bf16 v[20:23], v[148:151], v[180:183], v[20:23]
	v_mfma_f32_16x16x32_bf16 v[16:19], v[156:159], v[180:183], v[16:19]
	v_mfma_f32_16x16x32_bf16 v[4:7], v[148:151], v[204:207], v[4:7]
	v_mfma_f32_16x16x32_bf16 v[0:3], v[156:159], v[204:207], v[0:3]
	s_setprio 0
	s_add_i32 s65, 0, 0x18000
	s_add_i32 s66, 0, 0x1c000
	v_add_u32_e32 v140, s65, v232
	v_add_u32_e32 v156, s66, v232
	ds_read_b128 v[120:123], v140
	ds_read_b128 v[124:127], v140 offset:1024
	ds_read_b128 v[136:139], v140 offset:2048
	ds_read_b128 v[140:143], v140 offset:3072
	ds_read_b128 v[144:147], v156
	ds_read_b128 v[148:151], v156 offset:1024
	ds_read_b128 v[152:155], v156 offset:2048
	ds_read_b128 v[156:159], v156 offset:3072
	s_add_u32 s26, s36, 0xb0000
	s_addc_u32 s27, s37, 0
	s_mov_b32 m0, s46
	v_lshl_add_u64 v[216:217], s[26:27], 0, v[184:185]
	ds_read_b128 v[160:163], v235 offset:32768
	ds_read_b128 v[164:167], v235 offset:33792
	ds_read_b128 v[168:171], v235 offset:34816
	ds_read_b128 v[172:175], v235 offset:35840
	ds_read_b128 v[176:179], v235 offset:36864
	ds_read_b128 v[180:183], v235 offset:37888
	ds_read_b128 v[200:203], v235 offset:38912
	ds_read_b128 v[204:207], v235 offset:39936
	global_load_lds_dwordx4 v[216:217], off
	s_mov_b32 m0, s47
	v_lshl_add_u64 v[216:217], s[26:27], 0, v[188:189]
	global_load_lds_dwordx4 v[216:217], off
	s_waitcnt vmcnt(8) lgkmcnt(0)
	s_barrier
	s_setprio 1
	v_mfma_f32_16x16x32_bf16 v[132:135], v[120:123], v[160:163], v[132:135]
	v_mfma_f32_16x16x32_bf16 v[128:131], v[136:139], v[160:163], v[128:131]
	v_mfma_f32_16x16x32_bf16 v[108:111], v[120:123], v[168:171], v[108:111]
	v_mfma_f32_16x16x32_bf16 v[104:107], v[136:139], v[168:171], v[104:107]
	v_mfma_f32_16x16x32_bf16 v[92:95], v[120:123], v[176:179], v[92:95]
	v_mfma_f32_16x16x32_bf16 v[88:91], v[136:139], v[176:179], v[88:91]
	v_mfma_f32_16x16x32_bf16 v[76:79], v[120:123], v[200:203], v[76:79]
	v_mfma_f32_16x16x32_bf16 v[72:75], v[136:139], v[200:203], v[72:75]
	v_mfma_f32_16x16x32_bf16 v[132:135], v[124:127], v[164:167], v[132:135]
	v_mfma_f32_16x16x32_bf16 v[128:131], v[140:143], v[164:167], v[128:131]
	v_mfma_f32_16x16x32_bf16 v[108:111], v[124:127], v[172:175], v[108:111]
	v_mfma_f32_16x16x32_bf16 v[104:107], v[140:143], v[172:175], v[104:107]
	v_mfma_f32_16x16x32_bf16 v[92:95], v[124:127], v[180:183], v[92:95]
	v_mfma_f32_16x16x32_bf16 v[88:91], v[140:143], v[180:183], v[88:91]
	v_mfma_f32_16x16x32_bf16 v[76:79], v[124:127], v[204:207], v[76:79]
	v_mfma_f32_16x16x32_bf16 v[72:75], v[140:143], v[204:207], v[72:75]
	v_mfma_f32_16x16x32_bf16 v[116:119], v[144:147], v[160:163], v[116:119]
	v_mfma_f32_16x16x32_bf16 v[112:115], v[152:155], v[160:163], v[112:115]
	v_mfma_f32_16x16x32_bf16 v[100:103], v[144:147], v[168:171], v[100:103]
	v_mfma_f32_16x16x32_bf16 v[96:99], v[152:155], v[168:171], v[96:99]
	v_mfma_f32_16x16x32_bf16 v[84:87], v[144:147], v[176:179], v[84:87]
	v_mfma_f32_16x16x32_bf16 v[80:83], v[152:155], v[176:179], v[80:83]
	v_mfma_f32_16x16x32_bf16 v[68:71], v[144:147], v[200:203], v[68:71]
	v_mfma_f32_16x16x32_bf16 v[64:67], v[152:155], v[200:203], v[64:67]
	v_mfma_f32_16x16x32_bf16 v[116:119], v[148:151], v[164:167], v[116:119]
	v_mfma_f32_16x16x32_bf16 v[112:115], v[156:159], v[164:167], v[112:115]
	v_mfma_f32_16x16x32_bf16 v[100:103], v[148:151], v[172:175], v[100:103]
	v_mfma_f32_16x16x32_bf16 v[96:99], v[156:159], v[172:175], v[96:99]
	s_setprio 2
	s_barrier
	v_mfma_f32_16x16x32_bf16 v[84:87], v[148:151], v[180:183], v[84:87]
	v_mfma_f32_16x16x32_bf16 v[80:83], v[156:159], v[180:183], v[80:83]
	v_mfma_f32_16x16x32_bf16 v[68:71], v[148:151], v[204:207], v[68:71]
	v_mfma_f32_16x16x32_bf16 v[64:67], v[156:159], v[204:207], v[64:67]
	s_setprio 2
	s_mov_b32 m0, s49
	v_lshl_add_u64 v[250:251], v[212:213], 0, s[20:21]
	global_load_lds_dwordx4 v[250:251], off
	s_mov_b32 m0, s50
	v_lshl_add_u64 v[250:251], v[214:215], 0, s[20:21]
	global_load_lds_dwordx4 v[250:251], off
	s_add_i32 s26, s65, s43
	v_lshl_add_u64 v[208:209], v[208:209], 0, s[20:21]
	s_mov_b32 m0, s26
	ds_read_b128 v[160:163], v235 offset:49152
	ds_read_b128 v[164:167], v235 offset:50176
	ds_read_b128 v[168:171], v235 offset:51200
	ds_read_b128 v[172:175], v235 offset:52224
	ds_read_b128 v[176:179], v235 offset:53248
	ds_read_b128 v[180:183], v235 offset:54272
	ds_read_b128 v[200:203], v235 offset:55296
	ds_read_b128 v[204:207], v235 offset:56320
	global_load_lds_dwordx4 v[208:209], off
	s_add_i32 m0, s26, 0x2000
	s_add_u32 s26, s30, 0xb0080
	v_lshl_add_u64 v[208:209], v[210:211], 0, s[20:21]
	s_addc_u32 s27, s31, 0
	s_add_i32 s30, s66, s43
	global_load_lds_dwordx4 v[208:209], off
	s_mov_b32 m0, s30
	v_lshl_add_u64 v[208:209], s[26:27], 0, v[186:187]
	global_load_lds_dwordx4 v[208:209], off
	s_add_i32 m0, s30, 0x2000
	v_lshl_add_u64 v[208:209], s[26:27], 0, v[190:191]
	global_load_lds_dwordx4 v[208:209], off
	s_waitcnt vmcnt(8) lgkmcnt(0)
	s_barrier
	s_setprio 1
	v_mfma_f32_16x16x32_bf16 v[60:63], v[120:123], v[160:163], v[60:63]
	v_mfma_f32_16x16x32_bf16 v[56:59], v[136:139], v[160:163], v[56:59]
	v_mfma_f32_16x16x32_bf16 v[44:47], v[120:123], v[168:171], v[44:47]
	v_mfma_f32_16x16x32_bf16 v[40:43], v[136:139], v[168:171], v[40:43]
	v_mfma_f32_16x16x32_bf16 v[28:31], v[120:123], v[176:179], v[28:31]
	v_mfma_f32_16x16x32_bf16 v[24:27], v[136:139], v[176:179], v[24:27]
	v_mfma_f32_16x16x32_bf16 v[12:15], v[120:123], v[200:203], v[12:15]
	v_mfma_f32_16x16x32_bf16 v[8:11], v[136:139], v[200:203], v[8:11]
	v_mfma_f32_16x16x32_bf16 v[60:63], v[124:127], v[164:167], v[60:63]
	v_mfma_f32_16x16x32_bf16 v[56:59], v[140:143], v[164:167], v[56:59]
	v_mfma_f32_16x16x32_bf16 v[44:47], v[124:127], v[172:175], v[44:47]
	v_mfma_f32_16x16x32_bf16 v[40:43], v[140:143], v[172:175], v[40:43]
	v_mfma_f32_16x16x32_bf16 v[28:31], v[124:127], v[180:183], v[28:31]
	v_mfma_f32_16x16x32_bf16 v[24:27], v[140:143], v[180:183], v[24:27]
	v_mfma_f32_16x16x32_bf16 v[12:15], v[124:127], v[204:207], v[12:15]
	v_mfma_f32_16x16x32_bf16 v[8:11], v[140:143], v[204:207], v[8:11]
	v_mfma_f32_16x16x32_bf16 v[52:55], v[144:147], v[160:163], v[52:55]
	v_mfma_f32_16x16x32_bf16 v[48:51], v[152:155], v[160:163], v[48:51]
	v_mfma_f32_16x16x32_bf16 v[36:39], v[144:147], v[168:171], v[36:39]
	v_mfma_f32_16x16x32_bf16 v[32:35], v[152:155], v[168:171], v[32:35]
	v_mfma_f32_16x16x32_bf16 v[20:23], v[144:147], v[176:179], v[20:23]
	v_mfma_f32_16x16x32_bf16 v[16:19], v[152:155], v[176:179], v[16:19]
	v_mfma_f32_16x16x32_bf16 v[4:7], v[144:147], v[200:203], v[4:7]
	v_mfma_f32_16x16x32_bf16 v[0:3], v[152:155], v[200:203], v[0:3]
	v_mfma_f32_16x16x32_bf16 v[52:55], v[148:151], v[164:167], v[52:55]
	v_mfma_f32_16x16x32_bf16 v[48:51], v[156:159], v[164:167], v[48:51]
	v_mfma_f32_16x16x32_bf16 v[36:39], v[148:151], v[172:175], v[36:39]
	v_mfma_f32_16x16x32_bf16 v[32:35], v[156:159], v[172:175], v[32:35]
	s_setprio 2
	s_barrier
	v_mfma_f32_16x16x32_bf16 v[20:23], v[148:151], v[180:183], v[20:23]
	v_mfma_f32_16x16x32_bf16 v[16:19], v[156:159], v[180:183], v[16:19]
	v_mfma_f32_16x16x32_bf16 v[4:7], v[148:151], v[204:207], v[4:7]
	v_mfma_f32_16x16x32_bf16 v[0:3], v[156:159], v[204:207], v[0:3]
	s_setprio 0
	s_add_i32 s64, s64, 2
	s_add_u32 s62, s62, 0x100
	s_addc_u32 s63, s63, 0
	s_cmp_gt_u32 s64, 41
	s_mov_b64 s[26:27], s[28:29]
	s_cbranch_scc0 .LBB0_866

.LBB0_951:
	s_ashr_i32 s27, s26, 31
	s_lshl_b64 s[30:31], s[26:27], 19
	s_add_u32 s30, s47, s30
	s_addc_u32 s31, s48, s31
	s_and_b64 s[36:37], s[4:5], exec
	s_cselect_b32 s27, s31, s7
	s_cselect_b32 s39, s30, s6
	s_ashr_i32 s29, s28, 31
	s_lshl_b64 s[36:37], s[28:29], 19
	s_add_u32 s36, s49, s36
	s_addc_u32 s37, s50, s37
	s_and_b64 s[44:45], s[4:5], exec
	s_cselect_b32 s29, s37, s41
	s_cselect_b32 s43, s36, s40
	s_add_u32 s6, s6, 0x40080
	s_addc_u32 s7, s7, 0
	s_add_u32 s71, s40, 0x100
	s_addc_u32 s72, s41, 0
	s_mov_b32 s73, -2
	ds_read_b128 v[144:147], v179
	ds_read_b128 v[148:151], v179 offset:1024
	ds_read_b128 v[152:155], v179 offset:2048
	ds_read_b128 v[156:159], v179 offset:3072
	ds_read_b128 v[160:163], v180
	ds_read_b128 v[164:167], v180 offset:1024
	ds_read_b128 v[168:171], v180 offset:2048
	ds_read_b128 v[172:175], v180 offset:3072
	s_add_u32 s40, s6, 0xfffc0080
	s_addc_u32 s41, s7, -1
	s_cmp_eq_u32 s73, 12
	s_cselect_b32 s45, s27, s41
	s_cselect_b32 s44, s39, s40
	s_cselect_b32 s41, s29, s72
	s_cselect_b32 s40, s43, s71
	v_lshl_add_u64 v[176:177], s[6:7], 0, v[136:137]
	s_add_i32 m0, s54, 0xc000
	ds_read_b128 v[184:187], v181
	ds_read_b128 v[188:191], v181 offset:1024
	ds_read_b128 v[192:195], v181 offset:2048
	ds_read_b128 v[196:199], v181 offset:3072
	ds_read_b128 v[200:203], v181 offset:4096
	ds_read_b128 v[204:207], v181 offset:5120
	ds_read_b128 v[208:211], v181 offset:6144
	ds_read_b128 v[212:215], v181 offset:7168
	global_load_lds_dwordx4 v[176:177], off
	s_add_i32 m0, s54, 0xe000
	v_lshl_add_u64 v[176:177], s[6:7], 0, v[138:139]
	global_load_lds_dwordx4 v[176:177], off
	s_waitcnt vmcnt(8) lgkmcnt(0)
	s_barrier
	s_setprio 1
	v_mfma_f32_16x16x32_bf16 v[124:127], v[144:147], v[184:187], 0
	v_mfma_f32_16x16x32_bf16 v[120:123], v[152:155], v[184:187], 0
	v_mfma_f32_16x16x32_bf16 v[108:111], v[144:147], v[192:195], 0
	v_mfma_f32_16x16x32_bf16 v[104:107], v[152:155], v[192:195], 0
	v_mfma_f32_16x16x32_bf16 v[92:95], v[144:147], v[200:203], 0
	v_mfma_f32_16x16x32_bf16 v[88:91], v[152:155], v[200:203], 0
	v_mfma_f32_16x16x32_bf16 v[76:79], v[144:147], v[208:211], 0
	v_mfma_f32_16x16x32_bf16 v[72:75], v[152:155], v[208:211], 0
	v_mfma_f32_16x16x32_bf16 v[124:127], v[148:151], v[188:191], v[124:127]
	v_mfma_f32_16x16x32_bf16 v[120:123], v[156:159], v[188:191], v[120:123]
	v_mfma_f32_16x16x32_bf16 v[108:111], v[148:151], v[196:199], v[108:111]
	v_mfma_f32_16x16x32_bf16 v[104:107], v[156:159], v[196:199], v[104:107]
	v_mfma_f32_16x16x32_bf16 v[92:95], v[148:151], v[204:207], v[92:95]
	v_mfma_f32_16x16x32_bf16 v[88:91], v[156:159], v[204:207], v[88:91]
	v_mfma_f32_16x16x32_bf16 v[76:79], v[148:151], v[212:215], v[76:79]
	v_mfma_f32_16x16x32_bf16 v[72:75], v[156:159], v[212:215], v[72:75]
	v_mfma_f32_16x16x32_bf16 v[116:119], v[160:163], v[184:187], 0
	v_mfma_f32_16x16x32_bf16 v[112:115], v[168:171], v[184:187], 0
	v_mfma_f32_16x16x32_bf16 v[100:103], v[160:163], v[192:195], 0
	v_mfma_f32_16x16x32_bf16 v[96:99], v[168:171], v[192:195], 0
	v_mfma_f32_16x16x32_bf16 v[84:87], v[160:163], v[200:203], 0
	v_mfma_f32_16x16x32_bf16 v[80:83], v[168:171], v[200:203], 0
	v_mfma_f32_16x16x32_bf16 v[68:71], v[160:163], v[208:211], 0
	v_mfma_f32_16x16x32_bf16 v[64:67], v[168:171], v[208:211], 0
	v_mfma_f32_16x16x32_bf16 v[116:119], v[164:167], v[188:191], v[116:119]
	v_mfma_f32_16x16x32_bf16 v[112:115], v[172:175], v[188:191], v[112:115]
	v_mfma_f32_16x16x32_bf16 v[100:103], v[164:167], v[196:199], v[100:103]
	v_mfma_f32_16x16x32_bf16 v[96:99], v[172:175], v[196:199], v[96:99]
	s_setprio 2
	s_barrier
	v_mfma_f32_16x16x32_bf16 v[84:87], v[164:167], v[204:207], v[84:87]
	v_mfma_f32_16x16x32_bf16 v[80:83], v[172:175], v[204:207], v[80:83]
	v_mfma_f32_16x16x32_bf16 v[68:71], v[164:167], v[212:215], v[68:71]
	v_mfma_f32_16x16x32_bf16 v[64:67], v[172:175], v[212:215], v[64:67]
	s_setprio 2
	s_mov_b32 m0, s54
	v_lshl_add_u64 v[218:219], s[44:45], 0, v[128:129]
	global_load_lds_dwordx4 v[218:219], off
	s_mov_b32 m0, s55
	v_lshl_add_u64 v[220:221], s[44:45], 0, v[132:133]
	global_load_lds_dwordx4 v[220:221], off
	s_add_i32 s74, s69, s51
	v_lshl_add_u64 v[176:177], s[40:41], 0, v[130:131]
	s_mov_b32 m0, s74
	ds_read_b128 v[184:187], v181 offset:16384
	ds_read_b128 v[188:191], v181 offset:17408
	ds_read_b128 v[192:195], v181 offset:18432
	ds_read_b128 v[196:199], v181 offset:19456
	ds_read_b128 v[200:203], v181 offset:20480
	ds_read_b128 v[204:207], v181 offset:21504
	ds_read_b128 v[208:211], v181 offset:22528
	ds_read_b128 v[212:215], v181 offset:23552
	global_load_lds_dwordx4 v[176:177], off
	s_add_i32 m0, s74, 0x2000
	s_add_u32 s74, s40, 0x40000
	v_lshl_add_u64 v[216:217], s[40:41], 0, v[134:135]
	s_addc_u32 s75, s41, 0
	s_add_i32 s76, s70, s51
	global_load_lds_dwordx4 v[216:217], off
	v_lshl_add_u64 v[250:251], s[74:75], 0, v[130:131]
	s_mov_b32 m0, s76
	global_load_lds_dwordx4 v[250:251], off
	s_add_i32 m0, s76, 0x2000
	v_lshl_add_u64 v[250:251], s[74:75], 0, v[134:135]
	global_load_lds_dwordx4 v[250:251], off
	s_waitcnt vmcnt(8) lgkmcnt(0)
	s_barrier
	s_setprio 1
	v_mfma_f32_16x16x32_bf16 v[60:63], v[144:147], v[184:187], 0
	v_mfma_f32_16x16x32_bf16 v[56:59], v[152:155], v[184:187], 0
	v_mfma_f32_16x16x32_bf16 v[44:47], v[144:147], v[192:195], 0
	v_mfma_f32_16x16x32_bf16 v[40:43], v[152:155], v[192:195], 0
	v_mfma_f32_16x16x32_bf16 v[28:31], v[144:147], v[200:203], 0
	v_mfma_f32_16x16x32_bf16 v[24:27], v[152:155], v[200:203], 0
	v_mfma_f32_16x16x32_bf16 v[12:15], v[144:147], v[208:211], 0
	v_mfma_f32_16x16x32_bf16 v[8:11], v[152:155], v[208:211], 0
	v_mfma_f32_16x16x32_bf16 v[60:63], v[148:151], v[188:191], v[60:63]
	v_mfma_f32_16x16x32_bf16 v[56:59], v[156:159], v[188:191], v[56:59]
	v_mfma_f32_16x16x32_bf16 v[44:47], v[148:151], v[196:199], v[44:47]
	v_mfma_f32_16x16x32_bf16 v[40:43], v[156:159], v[196:199], v[40:43]
	v_mfma_f32_16x16x32_bf16 v[28:31], v[148:151], v[204:207], v[28:31]
	v_mfma_f32_16x16x32_bf16 v[24:27], v[156:159], v[204:207], v[24:27]
	v_mfma_f32_16x16x32_bf16 v[12:15], v[148:151], v[212:215], v[12:15]
	v_mfma_f32_16x16x32_bf16 v[8:11], v[156:159], v[212:215], v[8:11]
	v_mfma_f32_16x16x32_bf16 v[52:55], v[160:163], v[184:187], 0
	v_mfma_f32_16x16x32_bf16 v[48:51], v[168:171], v[184:187], 0
	v_mfma_f32_16x16x32_bf16 v[36:39], v[160:163], v[192:195], 0
	v_mfma_f32_16x16x32_bf16 v[32:35], v[168:171], v[192:195], 0
	v_mfma_f32_16x16x32_bf16 v[20:23], v[160:163], v[200:203], 0
	v_mfma_f32_16x16x32_bf16 v[16:19], v[168:171], v[200:203], 0
	v_mfma_f32_16x16x32_bf16 v[4:7], v[160:163], v[208:211], 0
	v_mfma_f32_16x16x32_bf16 v[0:3], v[168:171], v[208:211], 0
	v_mfma_f32_16x16x32_bf16 v[52:55], v[164:167], v[188:191], v[52:55]
	v_mfma_f32_16x16x32_bf16 v[48:51], v[172:175], v[188:191], v[48:51]
	v_mfma_f32_16x16x32_bf16 v[36:39], v[164:167], v[196:199], v[36:39]
	v_mfma_f32_16x16x32_bf16 v[32:35], v[172:175], v[196:199], v[32:35]
	s_setprio 2
	s_barrier
	v_mfma_f32_16x16x32_bf16 v[20:23], v[164:167], v[204:207], v[20:23]
	v_mfma_f32_16x16x32_bf16 v[16:19], v[172:175], v[204:207], v[16:19]
	v_mfma_f32_16x16x32_bf16 v[4:7], v[164:167], v[212:215], v[4:7]
	v_mfma_f32_16x16x32_bf16 v[0:3], v[172:175], v[212:215], v[0:3]
	s_setprio 0
	s_add_i32 s74, 0, 0x18000
	s_add_i32 s75, 0, 0x1c000
	v_add_u32_e32 v156, s74, v178
	v_add_u32_e32 v172, s75, v178
	ds_read_b128 v[144:147], v156
	ds_read_b128 v[148:151], v156 offset:1024
	ds_read_b128 v[152:155], v156 offset:2048
	ds_read_b128 v[156:159], v156 offset:3072
	ds_read_b128 v[160:163], v172
	ds_read_b128 v[164:167], v172 offset:1024
	ds_read_b128 v[168:171], v172 offset:2048
	ds_read_b128 v[172:175], v172 offset:3072
	s_add_u32 s44, s44, 0x40000
	s_addc_u32 s45, s45, 0
	s_mov_b32 m0, s56
	v_lshl_add_u64 v[222:223], s[44:45], 0, v[128:129]
	ds_read_b128 v[184:187], v181 offset:32768
	ds_read_b128 v[188:191], v181 offset:33792
	ds_read_b128 v[192:195], v181 offset:34816
	ds_read_b128 v[196:199], v181 offset:35840
	ds_read_b128 v[200:203], v181 offset:36864
	ds_read_b128 v[204:207], v181 offset:37888
	ds_read_b128 v[208:211], v181 offset:38912
	ds_read_b128 v[212:215], v181 offset:39936
	global_load_lds_dwordx4 v[222:223], off
	s_mov_b32 m0, s57
	v_lshl_add_u64 v[222:223], s[44:45], 0, v[132:133]
	global_load_lds_dwordx4 v[222:223], off
	s_waitcnt vmcnt(8) lgkmcnt(0)
	s_barrier
	s_setprio 1
	v_mfma_f32_16x16x32_bf16 v[124:127], v[144:147], v[184:187], v[124:127]
	v_mfma_f32_16x16x32_bf16 v[120:123], v[152:155], v[184:187], v[120:123]
	v_mfma_f32_16x16x32_bf16 v[108:111], v[144:147], v[192:195], v[108:111]
	v_mfma_f32_16x16x32_bf16 v[104:107], v[152:155], v[192:195], v[104:107]
	v_mfma_f32_16x16x32_bf16 v[92:95], v[144:147], v[200:203], v[92:95]
	v_mfma_f32_16x16x32_bf16 v[88:91], v[152:155], v[200:203], v[88:91]
	v_mfma_f32_16x16x32_bf16 v[76:79], v[144:147], v[208:211], v[76:79]
	v_mfma_f32_16x16x32_bf16 v[72:75], v[152:155], v[208:211], v[72:75]
	v_mfma_f32_16x16x32_bf16 v[124:127], v[148:151], v[188:191], v[124:127]
	v_mfma_f32_16x16x32_bf16 v[120:123], v[156:159], v[188:191], v[120:123]
	v_mfma_f32_16x16x32_bf16 v[108:111], v[148:151], v[196:199], v[108:111]
	v_mfma_f32_16x16x32_bf16 v[104:107], v[156:159], v[196:199], v[104:107]
	v_mfma_f32_16x16x32_bf16 v[92:95], v[148:151], v[204:207], v[92:95]
	v_mfma_f32_16x16x32_bf16 v[88:91], v[156:159], v[204:207], v[88:91]
	v_mfma_f32_16x16x32_bf16 v[76:79], v[148:151], v[212:215], v[76:79]
	v_mfma_f32_16x16x32_bf16 v[72:75], v[156:159], v[212:215], v[72:75]
	v_mfma_f32_16x16x32_bf16 v[116:119], v[160:163], v[184:187], v[116:119]
	v_mfma_f32_16x16x32_bf16 v[112:115], v[168:171], v[184:187], v[112:115]
	v_mfma_f32_16x16x32_bf16 v[100:103], v[160:163], v[192:195], v[100:103]
	v_mfma_f32_16x16x32_bf16 v[96:99], v[168:171], v[192:195], v[96:99]
	v_mfma_f32_16x16x32_bf16 v[84:87], v[160:163], v[200:203], v[84:87]
	v_mfma_f32_16x16x32_bf16 v[80:83], v[168:171], v[200:203], v[80:83]
	v_mfma_f32_16x16x32_bf16 v[68:71], v[160:163], v[208:211], v[68:71]
	v_mfma_f32_16x16x32_bf16 v[64:67], v[168:171], v[208:211], v[64:67]
	v_mfma_f32_16x16x32_bf16 v[116:119], v[164:167], v[188:191], v[116:119]
	v_mfma_f32_16x16x32_bf16 v[112:115], v[172:175], v[188:191], v[112:115]
	v_mfma_f32_16x16x32_bf16 v[100:103], v[164:167], v[196:199], v[100:103]
	v_mfma_f32_16x16x32_bf16 v[96:99], v[172:175], v[196:199], v[96:99]
	s_setprio 2
	s_barrier
	v_mfma_f32_16x16x32_bf16 v[84:87], v[164:167], v[204:207], v[84:87]
	v_mfma_f32_16x16x32_bf16 v[80:83], v[172:175], v[204:207], v[80:83]
	v_mfma_f32_16x16x32_bf16 v[68:71], v[164:167], v[212:215], v[68:71]
	v_mfma_f32_16x16x32_bf16 v[64:67], v[172:175], v[212:215], v[64:67]
	s_setprio 2
	s_mov_b32 m0, s64
	v_lshl_add_u64 v[250:251], v[218:219], 0, s[22:23]
	global_load_lds_dwordx4 v[250:251], off
	s_mov_b32 m0, s65
	v_lshl_add_u64 v[250:251], v[220:221], 0, s[22:23]
	global_load_lds_dwordx4 v[250:251], off
	s_add_i32 s44, s74, s51
	v_lshl_add_u64 v[176:177], v[176:177], 0, s[22:23]
	s_mov_b32 m0, s44
	ds_read_b128 v[184:187], v181 offset:49152
	ds_read_b128 v[188:191], v181 offset:50176
	ds_read_b128 v[192:195], v181 offset:51200
	ds_read_b128 v[196:199], v181 offset:52224
	ds_read_b128 v[200:203], v181 offset:53248
	ds_read_b128 v[204:207], v181 offset:54272
	ds_read_b128 v[208:211], v181 offset:55296
	ds_read_b128 v[212:215], v181 offset:56320
	global_load_lds_dwordx4 v[176:177], off
	s_add_i32 m0, s44, 0x2000
	s_add_u32 s40, s40, 0x40080
	v_lshl_add_u64 v[176:177], v[216:217], 0, s[22:23]
	s_addc_u32 s41, s41, 0
	s_add_i32 s44, s75, s51
	global_load_lds_dwordx4 v[176:177], off
	s_mov_b32 m0, s44
	v_lshl_add_u64 v[176:177], s[40:41], 0, v[130:131]
	global_load_lds_dwordx4 v[176:177], off
	s_add_i32 m0, s44, 0x2000
	v_lshl_add_u64 v[176:177], s[40:41], 0, v[134:135]
	global_load_lds_dwordx4 v[176:177], off
	s_waitcnt vmcnt(8) lgkmcnt(0)
	s_barrier
	s_setprio 1
	v_mfma_f32_16x16x32_bf16 v[60:63], v[144:147], v[184:187], v[60:63]
	v_mfma_f32_16x16x32_bf16 v[56:59], v[152:155], v[184:187], v[56:59]
	v_mfma_f32_16x16x32_bf16 v[44:47], v[144:147], v[192:195], v[44:47]
	v_mfma_f32_16x16x32_bf16 v[40:43], v[152:155], v[192:195], v[40:43]
	v_mfma_f32_16x16x32_bf16 v[28:31], v[144:147], v[200:203], v[28:31]
	v_mfma_f32_16x16x32_bf16 v[24:27], v[152:155], v[200:203], v[24:27]
	v_mfma_f32_16x16x32_bf16 v[12:15], v[144:147], v[208:211], v[12:15]
	v_mfma_f32_16x16x32_bf16 v[8:11], v[152:155], v[208:211], v[8:11]
	v_mfma_f32_16x16x32_bf16 v[60:63], v[148:151], v[188:191], v[60:63]
	v_mfma_f32_16x16x32_bf16 v[56:59], v[156:159], v[188:191], v[56:59]
	v_mfma_f32_16x16x32_bf16 v[44:47], v[148:151], v[196:199], v[44:47]
	v_mfma_f32_16x16x32_bf16 v[40:43], v[156:159], v[196:199], v[40:43]
	v_mfma_f32_16x16x32_bf16 v[28:31], v[148:151], v[204:207], v[28:31]
	v_mfma_f32_16x16x32_bf16 v[24:27], v[156:159], v[204:207], v[24:27]
	v_mfma_f32_16x16x32_bf16 v[12:15], v[148:151], v[212:215], v[12:15]
	v_mfma_f32_16x16x32_bf16 v[8:11], v[156:159], v[212:215], v[8:11]
	v_mfma_f32_16x16x32_bf16 v[52:55], v[160:163], v[184:187], v[52:55]
	v_mfma_f32_16x16x32_bf16 v[48:51], v[168:171], v[184:187], v[48:51]
	v_mfma_f32_16x16x32_bf16 v[36:39], v[160:163], v[192:195], v[36:39]
	v_mfma_f32_16x16x32_bf16 v[32:35], v[168:171], v[192:195], v[32:35]
	v_mfma_f32_16x16x32_bf16 v[20:23], v[160:163], v[200:203], v[20:23]
	v_mfma_f32_16x16x32_bf16 v[16:19], v[168:171], v[200:203], v[16:19]
	v_mfma_f32_16x16x32_bf16 v[4:7], v[160:163], v[208:211], v[4:7]
	v_mfma_f32_16x16x32_bf16 v[0:3], v[168:171], v[208:211], v[0:3]
	v_mfma_f32_16x16x32_bf16 v[52:55], v[164:167], v[188:191], v[52:55]
	v_mfma_f32_16x16x32_bf16 v[48:51], v[172:175], v[188:191], v[48:51]
	v_mfma_f32_16x16x32_bf16 v[36:39], v[164:167], v[196:199], v[36:39]
	v_mfma_f32_16x16x32_bf16 v[32:35], v[172:175], v[196:199], v[32:35]
	s_setprio 2
	s_barrier
	v_mfma_f32_16x16x32_bf16 v[20:23], v[164:167], v[204:207], v[20:23]
	v_mfma_f32_16x16x32_bf16 v[16:19], v[172:175], v[204:207], v[16:19]
	v_mfma_f32_16x16x32_bf16 v[4:7], v[164:167], v[212:215], v[4:7]
	v_mfma_f32_16x16x32_bf16 v[0:3], v[172:175], v[212:215], v[0:3]
	s_setprio 0
	s_add_i32 s73, s73, 2
	s_add_u32 s6, s6, 0x100
	s_addc_u32 s7, s7, 0
	s_add_u32 s71, s71, 0x100
	s_addc_u32 s72, s72, 0
	s_cmp_gt_u32 s73, 13
.LBB0_952:
	ds_read_b128 v[144:147], v179
	ds_read_b128 v[148:151], v179 offset:1024
	ds_read_b128 v[152:155], v179 offset:2048
	ds_read_b128 v[156:159], v179 offset:3072
	ds_read_b128 v[160:163], v180
	ds_read_b128 v[164:167], v180 offset:1024
	ds_read_b128 v[168:171], v180 offset:2048
	ds_read_b128 v[172:175], v180 offset:3072
	s_add_u32 s40, s6, 0xfffc0080
	s_addc_u32 s41, s7, -1
	s_cmp_eq_u32 s73, 12
	s_cselect_b32 s45, s27, s41
	s_cselect_b32 s44, s39, s40
	s_cselect_b32 s41, s29, s72
	s_cselect_b32 s40, s43, s71
	v_lshl_add_u64 v[176:177], s[6:7], 0, v[136:137]
	s_add_i32 m0, s54, 0xc000
	ds_read_b128 v[184:187], v181
	ds_read_b128 v[188:191], v181 offset:1024
	ds_read_b128 v[192:195], v181 offset:2048
	ds_read_b128 v[196:199], v181 offset:3072
	ds_read_b128 v[200:203], v181 offset:4096
	ds_read_b128 v[204:207], v181 offset:5120
	ds_read_b128 v[208:211], v181 offset:6144
	ds_read_b128 v[212:215], v181 offset:7168
	global_load_lds_dwordx4 v[176:177], off
	s_add_i32 m0, s54, 0xe000
	v_lshl_add_u64 v[176:177], s[6:7], 0, v[138:139]
	global_load_lds_dwordx4 v[176:177], off
	s_waitcnt vmcnt(8) lgkmcnt(0)
	s_barrier
	s_setprio 1
	v_mfma_f32_16x16x32_bf16 v[124:127], v[144:147], v[184:187], v[124:127]
	v_mfma_f32_16x16x32_bf16 v[120:123], v[152:155], v[184:187], v[120:123]
	v_mfma_f32_16x16x32_bf16 v[108:111], v[144:147], v[192:195], v[108:111]
	v_mfma_f32_16x16x32_bf16 v[104:107], v[152:155], v[192:195], v[104:107]
	v_mfma_f32_16x16x32_bf16 v[92:95], v[144:147], v[200:203], v[92:95]
	v_mfma_f32_16x16x32_bf16 v[88:91], v[152:155], v[200:203], v[88:91]
	v_mfma_f32_16x16x32_bf16 v[76:79], v[144:147], v[208:211], v[76:79]
	v_mfma_f32_16x16x32_bf16 v[72:75], v[152:155], v[208:211], v[72:75]
	v_mfma_f32_16x16x32_bf16 v[124:127], v[148:151], v[188:191], v[124:127]
	v_mfma_f32_16x16x32_bf16 v[120:123], v[156:159], v[188:191], v[120:123]
	v_mfma_f32_16x16x32_bf16 v[108:111], v[148:151], v[196:199], v[108:111]
	v_mfma_f32_16x16x32_bf16 v[104:107], v[156:159], v[196:199], v[104:107]
	v_mfma_f32_16x16x32_bf16 v[92:95], v[148:151], v[204:207], v[92:95]
	v_mfma_f32_16x16x32_bf16 v[88:91], v[156:159], v[204:207], v[88:91]
	v_mfma_f32_16x16x32_bf16 v[76:79], v[148:151], v[212:215], v[76:79]
	v_mfma_f32_16x16x32_bf16 v[72:75], v[156:159], v[212:215], v[72:75]
	v_mfma_f32_16x16x32_bf16 v[116:119], v[160:163], v[184:187], v[116:119]
	v_mfma_f32_16x16x32_bf16 v[112:115], v[168:171], v[184:187], v[112:115]
	v_mfma_f32_16x16x32_bf16 v[100:103], v[160:163], v[192:195], v[100:103]
	v_mfma_f32_16x16x32_bf16 v[96:99], v[168:171], v[192:195], v[96:99]
	v_mfma_f32_16x16x32_bf16 v[84:87], v[160:163], v[200:203], v[84:87]
	v_mfma_f32_16x16x32_bf16 v[80:83], v[168:171], v[200:203], v[80:83]
	v_mfma_f32_16x16x32_bf16 v[68:71], v[160:163], v[208:211], v[68:71]
	v_mfma_f32_16x16x32_bf16 v[64:67], v[168:171], v[208:211], v[64:67]
	v_mfma_f32_16x16x32_bf16 v[116:119], v[164:167], v[188:191], v[116:119]
	v_mfma_f32_16x16x32_bf16 v[112:115], v[172:175], v[188:191], v[112:115]
	v_mfma_f32_16x16x32_bf16 v[100:103], v[164:167], v[196:199], v[100:103]
	v_mfma_f32_16x16x32_bf16 v[96:99], v[172:175], v[196:199], v[96:99]
	s_setprio 2
	s_barrier
	v_mfma_f32_16x16x32_bf16 v[84:87], v[164:167], v[204:207], v[84:87]
	v_mfma_f32_16x16x32_bf16 v[80:83], v[172:175], v[204:207], v[80:83]
	v_mfma_f32_16x16x32_bf16 v[68:71], v[164:167], v[212:215], v[68:71]
	v_mfma_f32_16x16x32_bf16 v[64:67], v[172:175], v[212:215], v[64:67]
	s_setprio 2
	s_mov_b32 m0, s54
	v_lshl_add_u64 v[218:219], s[44:45], 0, v[128:129]
	global_load_lds_dwordx4 v[218:219], off
	s_mov_b32 m0, s55
	v_lshl_add_u64 v[220:221], s[44:45], 0, v[132:133]
	global_load_lds_dwordx4 v[220:221], off
	s_add_i32 s74, s69, s51
	v_lshl_add_u64 v[176:177], s[40:41], 0, v[130:131]
	s_mov_b32 m0, s74
	ds_read_b128 v[184:187], v181 offset:16384
	ds_read_b128 v[188:191], v181 offset:17408
	ds_read_b128 v[192:195], v181 offset:18432
	ds_read_b128 v[196:199], v181 offset:19456
	ds_read_b128 v[200:203], v181 offset:20480
	ds_read_b128 v[204:207], v181 offset:21504
	ds_read_b128 v[208:211], v181 offset:22528
	ds_read_b128 v[212:215], v181 offset:23552
	global_load_lds_dwordx4 v[176:177], off
	s_add_i32 m0, s74, 0x2000
	s_add_u32 s74, s40, 0x40000
	v_lshl_add_u64 v[216:217], s[40:41], 0, v[134:135]
	s_addc_u32 s75, s41, 0
	s_add_i32 s76, s70, s51
	global_load_lds_dwordx4 v[216:217], off
	v_lshl_add_u64 v[250:251], s[74:75], 0, v[130:131]
	s_mov_b32 m0, s76
	global_load_lds_dwordx4 v[250:251], off
	s_add_i32 m0, s76, 0x2000
	v_lshl_add_u64 v[250:251], s[74:75], 0, v[134:135]
	global_load_lds_dwordx4 v[250:251], off
	s_waitcnt vmcnt(8) lgkmcnt(0)
	s_barrier
	s_setprio 1
	v_mfma_f32_16x16x32_bf16 v[60:63], v[144:147], v[184:187], v[60:63]
	v_mfma_f32_16x16x32_bf16 v[56:59], v[152:155], v[184:187], v[56:59]
	v_mfma_f32_16x16x32_bf16 v[44:47], v[144:147], v[192:195], v[44:47]
	v_mfma_f32_16x16x32_bf16 v[40:43], v[152:155], v[192:195], v[40:43]
	v_mfma_f32_16x16x32_bf16 v[28:31], v[144:147], v[200:203], v[28:31]
	v_mfma_f32_16x16x32_bf16 v[24:27], v[152:155], v[200:203], v[24:27]
	v_mfma_f32_16x16x32_bf16 v[12:15], v[144:147], v[208:211], v[12:15]
	v_mfma_f32_16x16x32_bf16 v[8:11], v[152:155], v[208:211], v[8:11]
	v_mfma_f32_16x16x32_bf16 v[60:63], v[148:151], v[188:191], v[60:63]
	v_mfma_f32_16x16x32_bf16 v[56:59], v[156:159], v[188:191], v[56:59]
	v_mfma_f32_16x16x32_bf16 v[44:47], v[148:151], v[196:199], v[44:47]
	v_mfma_f32_16x16x32_bf16 v[40:43], v[156:159], v[196:199], v[40:43]
	v_mfma_f32_16x16x32_bf16 v[28:31], v[148:151], v[204:207], v[28:31]
	v_mfma_f32_16x16x32_bf16 v[24:27], v[156:159], v[204:207], v[24:27]
	v_mfma_f32_16x16x32_bf16 v[12:15], v[148:151], v[212:215], v[12:15]
	v_mfma_f32_16x16x32_bf16 v[8:11], v[156:159], v[212:215], v[8:11]
	v_mfma_f32_16x16x32_bf16 v[52:55], v[160:163], v[184:187], v[52:55]
	v_mfma_f32_16x16x32_bf16 v[48:51], v[168:171], v[184:187], v[48:51]
	v_mfma_f32_16x16x32_bf16 v[36:39], v[160:163], v[192:195], v[36:39]
	v_mfma_f32_16x16x32_bf16 v[32:35], v[168:171], v[192:195], v[32:35]
	v_mfma_f32_16x16x32_bf16 v[20:23], v[160:163], v[200:203], v[20:23]
	v_mfma_f32_16x16x32_bf16 v[16:19], v[168:171], v[200:203], v[16:19]
	v_mfma_f32_16x16x32_bf16 v[4:7], v[160:163], v[208:211], v[4:7]
	v_mfma_f32_16x16x32_bf16 v[0:3], v[168:171], v[208:211], v[0:3]
	v_mfma_f32_16x16x32_bf16 v[52:55], v[164:167], v[188:191], v[52:55]
	v_mfma_f32_16x16x32_bf16 v[48:51], v[172:175], v[188:191], v[48:51]
	v_mfma_f32_16x16x32_bf16 v[36:39], v[164:167], v[196:199], v[36:39]
	v_mfma_f32_16x16x32_bf16 v[32:35], v[172:175], v[196:199], v[32:35]
	s_setprio 2
	s_barrier
	v_mfma_f32_16x16x32_bf16 v[20:23], v[164:167], v[204:207], v[20:23]
	v_mfma_f32_16x16x32_bf16 v[16:19], v[172:175], v[204:207], v[16:19]
	v_mfma_f32_16x16x32_bf16 v[4:7], v[164:167], v[212:215], v[4:7]
	v_mfma_f32_16x16x32_bf16 v[0:3], v[172:175], v[212:215], v[0:3]
	s_setprio 0
	s_add_i32 s74, 0, 0x18000
	s_add_i32 s75, 0, 0x1c000
	v_add_u32_e32 v156, s74, v178
	v_add_u32_e32 v172, s75, v178
	ds_read_b128 v[144:147], v156
	ds_read_b128 v[148:151], v156 offset:1024
	ds_read_b128 v[152:155], v156 offset:2048
	ds_read_b128 v[156:159], v156 offset:3072
	ds_read_b128 v[160:163], v172
	ds_read_b128 v[164:167], v172 offset:1024
	ds_read_b128 v[168:171], v172 offset:2048
	ds_read_b128 v[172:175], v172 offset:3072
	s_add_u32 s44, s44, 0x40000
	s_addc_u32 s45, s45, 0
	s_mov_b32 m0, s56
	v_lshl_add_u64 v[222:223], s[44:45], 0, v[128:129]
	ds_read_b128 v[184:187], v181 offset:32768
	ds_read_b128 v[188:191], v181 offset:33792
	ds_read_b128 v[192:195], v181 offset:34816
	ds_read_b128 v[196:199], v181 offset:35840
	ds_read_b128 v[200:203], v181 offset:36864
	ds_read_b128 v[204:207], v181 offset:37888
	ds_read_b128 v[208:211], v181 offset:38912
	ds_read_b128 v[212:215], v181 offset:39936
	global_load_lds_dwordx4 v[222:223], off
	s_mov_b32 m0, s57
	v_lshl_add_u64 v[222:223], s[44:45], 0, v[132:133]
	global_load_lds_dwordx4 v[222:223], off
	s_waitcnt vmcnt(8) lgkmcnt(0)
	s_barrier
	s_setprio 1
	v_mfma_f32_16x16x32_bf16 v[124:127], v[144:147], v[184:187], v[124:127]
	v_mfma_f32_16x16x32_bf16 v[120:123], v[152:155], v[184:187], v[120:123]
	v_mfma_f32_16x16x32_bf16 v[108:111], v[144:147], v[192:195], v[108:111]
	v_mfma_f32_16x16x32_bf16 v[104:107], v[152:155], v[192:195], v[104:107]
	v_mfma_f32_16x16x32_bf16 v[92:95], v[144:147], v[200:203], v[92:95]
	v_mfma_f32_16x16x32_bf16 v[88:91], v[152:155], v[200:203], v[88:91]
	v_mfma_f32_16x16x32_bf16 v[76:79], v[144:147], v[208:211], v[76:79]
	v_mfma_f32_16x16x32_bf16 v[72:75], v[152:155], v[208:211], v[72:75]
	v_mfma_f32_16x16x32_bf16 v[124:127], v[148:151], v[188:191], v[124:127]
	v_mfma_f32_16x16x32_bf16 v[120:123], v[156:159], v[188:191], v[120:123]
	v_mfma_f32_16x16x32_bf16 v[108:111], v[148:151], v[196:199], v[108:111]
	v_mfma_f32_16x16x32_bf16 v[104:107], v[156:159], v[196:199], v[104:107]
	v_mfma_f32_16x16x32_bf16 v[92:95], v[148:151], v[204:207], v[92:95]
	v_mfma_f32_16x16x32_bf16 v[88:91], v[156:159], v[204:207], v[88:91]
	v_mfma_f32_16x16x32_bf16 v[76:79], v[148:151], v[212:215], v[76:79]
	v_mfma_f32_16x16x32_bf16 v[72:75], v[156:159], v[212:215], v[72:75]
	v_mfma_f32_16x16x32_bf16 v[116:119], v[160:163], v[184:187], v[116:119]
	v_mfma_f32_16x16x32_bf16 v[112:115], v[168:171], v[184:187], v[112:115]
	v_mfma_f32_16x16x32_bf16 v[100:103], v[160:163], v[192:195], v[100:103]
	v_mfma_f32_16x16x32_bf16 v[96:99], v[168:171], v[192:195], v[96:99]
	v_mfma_f32_16x16x32_bf16 v[84:87], v[160:163], v[200:203], v[84:87]
	v_mfma_f32_16x16x32_bf16 v[80:83], v[168:171], v[200:203], v[80:83]
	v_mfma_f32_16x16x32_bf16 v[68:71], v[160:163], v[208:211], v[68:71]
	v_mfma_f32_16x16x32_bf16 v[64:67], v[168:171], v[208:211], v[64:67]
	v_mfma_f32_16x16x32_bf16 v[116:119], v[164:167], v[188:191], v[116:119]
	v_mfma_f32_16x16x32_bf16 v[112:115], v[172:175], v[188:191], v[112:115]
	v_mfma_f32_16x16x32_bf16 v[100:103], v[164:167], v[196:199], v[100:103]
	v_mfma_f32_16x16x32_bf16 v[96:99], v[172:175], v[196:199], v[96:99]
	s_setprio 2
	s_barrier
	v_mfma_f32_16x16x32_bf16 v[84:87], v[164:167], v[204:207], v[84:87]
	v_mfma_f32_16x16x32_bf16 v[80:83], v[172:175], v[204:207], v[80:83]
	v_mfma_f32_16x16x32_bf16 v[68:71], v[164:167], v[212:215], v[68:71]
	v_mfma_f32_16x16x32_bf16 v[64:67], v[172:175], v[212:215], v[64:67]
	s_setprio 2
	s_mov_b32 m0, s64
	v_lshl_add_u64 v[250:251], v[218:219], 0, s[22:23]
	global_load_lds_dwordx4 v[250:251], off
	s_mov_b32 m0, s65
	v_lshl_add_u64 v[250:251], v[220:221], 0, s[22:23]
	global_load_lds_dwordx4 v[250:251], off
	s_add_i32 s44, s74, s51
	v_lshl_add_u64 v[176:177], v[176:177], 0, s[22:23]
	s_mov_b32 m0, s44
	ds_read_b128 v[184:187], v181 offset:49152
	ds_read_b128 v[188:191], v181 offset:50176
	ds_read_b128 v[192:195], v181 offset:51200
	ds_read_b128 v[196:199], v181 offset:52224
	ds_read_b128 v[200:203], v181 offset:53248
	ds_read_b128 v[204:207], v181 offset:54272
	ds_read_b128 v[208:211], v181 offset:55296
	ds_read_b128 v[212:215], v181 offset:56320
	global_load_lds_dwordx4 v[176:177], off
	s_add_i32 m0, s44, 0x2000
	s_add_u32 s40, s40, 0x40080
	v_lshl_add_u64 v[176:177], v[216:217], 0, s[22:23]
	s_addc_u32 s41, s41, 0
	s_add_i32 s44, s75, s51
	global_load_lds_dwordx4 v[176:177], off
	s_mov_b32 m0, s44
	v_lshl_add_u64 v[176:177], s[40:41], 0, v[130:131]
	global_load_lds_dwordx4 v[176:177], off
	s_add_i32 m0, s44, 0x2000
	v_lshl_add_u64 v[176:177], s[40:41], 0, v[134:135]
	global_load_lds_dwordx4 v[176:177], off
	s_waitcnt vmcnt(8) lgkmcnt(0)
	s_barrier
	s_setprio 1
	v_mfma_f32_16x16x32_bf16 v[60:63], v[144:147], v[184:187], v[60:63]
	v_mfma_f32_16x16x32_bf16 v[56:59], v[152:155], v[184:187], v[56:59]
	v_mfma_f32_16x16x32_bf16 v[44:47], v[144:147], v[192:195], v[44:47]
	v_mfma_f32_16x16x32_bf16 v[40:43], v[152:155], v[192:195], v[40:43]
	v_mfma_f32_16x16x32_bf16 v[28:31], v[144:147], v[200:203], v[28:31]
	v_mfma_f32_16x16x32_bf16 v[24:27], v[152:155], v[200:203], v[24:27]
	v_mfma_f32_16x16x32_bf16 v[12:15], v[144:147], v[208:211], v[12:15]
	v_mfma_f32_16x16x32_bf16 v[8:11], v[152:155], v[208:211], v[8:11]
	v_mfma_f32_16x16x32_bf16 v[60:63], v[148:151], v[188:191], v[60:63]
	v_mfma_f32_16x16x32_bf16 v[56:59], v[156:159], v[188:191], v[56:59]
	v_mfma_f32_16x16x32_bf16 v[44:47], v[148:151], v[196:199], v[44:47]
	v_mfma_f32_16x16x32_bf16 v[40:43], v[156:159], v[196:199], v[40:43]
	v_mfma_f32_16x16x32_bf16 v[28:31], v[148:151], v[204:207], v[28:31]
	v_mfma_f32_16x16x32_bf16 v[24:27], v[156:159], v[204:207], v[24:27]
	v_mfma_f32_16x16x32_bf16 v[12:15], v[148:151], v[212:215], v[12:15]
	v_mfma_f32_16x16x32_bf16 v[8:11], v[156:159], v[212:215], v[8:11]
	v_mfma_f32_16x16x32_bf16 v[52:55], v[160:163], v[184:187], v[52:55]
	v_mfma_f32_16x16x32_bf16 v[48:51], v[168:171], v[184:187], v[48:51]
	v_mfma_f32_16x16x32_bf16 v[36:39], v[160:163], v[192:195], v[36:39]
	v_mfma_f32_16x16x32_bf16 v[32:35], v[168:171], v[192:195], v[32:35]
	v_mfma_f32_16x16x32_bf16 v[20:23], v[160:163], v[200:203], v[20:23]
	v_mfma_f32_16x16x32_bf16 v[16:19], v[168:171], v[200:203], v[16:19]
	v_mfma_f32_16x16x32_bf16 v[4:7], v[160:163], v[208:211], v[4:7]
	v_mfma_f32_16x16x32_bf16 v[0:3], v[168:171], v[208:211], v[0:3]
	v_mfma_f32_16x16x32_bf16 v[52:55], v[164:167], v[188:191], v[52:55]
	v_mfma_f32_16x16x32_bf16 v[48:51], v[172:175], v[188:191], v[48:51]
	v_mfma_f32_16x16x32_bf16 v[36:39], v[164:167], v[196:199], v[36:39]
	v_mfma_f32_16x16x32_bf16 v[32:35], v[172:175], v[196:199], v[32:35]
	s_setprio 2
	s_barrier
	v_mfma_f32_16x16x32_bf16 v[20:23], v[164:167], v[204:207], v[20:23]
	v_mfma_f32_16x16x32_bf16 v[16:19], v[172:175], v[204:207], v[16:19]
	v_mfma_f32_16x16x32_bf16 v[4:7], v[164:167], v[212:215], v[4:7]
	v_mfma_f32_16x16x32_bf16 v[0:3], v[172:175], v[212:215], v[0:3]
	s_setprio 0
	s_add_i32 s73, s73, 2
	s_add_u32 s6, s6, 0x100
	s_addc_u32 s7, s7, 0
	s_add_u32 s71, s71, 0x100
	s_addc_u32 s72, s72, 0
	s_cmp_gt_u32 s73, 13
	s_cbranch_scc0 .LBB0_952

.LBB0_1145:
	s_ashr_i32 s23, s22, 31
	s_lshl_b64 s[26:27], s[22:23], 19
	s_add_u32 s26, s45, s26
	s_addc_u32 s27, s46, s27
	s_and_b64 s[28:29], s[4:5], exec
	s_cselect_b32 s23, s27, s39
	s_cselect_b32 s31, s26, s38
	s_ashr_i32 s25, s24, 31
	s_lshl_b64 s[28:29], s[24:25], 19
	s_add_u32 s28, s47, s28
	s_addc_u32 s29, s48, s29
	s_and_b64 s[42:43], s[4:5], exec
	s_cselect_b32 s25, s29, s41
	s_cselect_b32 s37, s28, s40
	s_add_u32 s38, s38, 0x40080
	s_addc_u32 s39, s39, 0
	s_add_u32 s64, s40, 0x100
	s_addc_u32 s65, s41, 0
	s_mov_b32 s66, -2
	ds_read_b128 v[120:123], v233
	ds_read_b128 v[132:135], v233 offset:1024
	ds_read_b128 v[136:139], v233 offset:2048
	ds_read_b128 v[140:143], v233 offset:3072
	ds_read_b128 v[144:147], v234
	ds_read_b128 v[148:151], v234 offset:1024
	ds_read_b128 v[152:155], v234 offset:2048
	ds_read_b128 v[156:159], v234 offset:3072
	s_add_u32 s40, s38, 0xfffc0080
	s_addc_u32 s41, s39, -1
	s_cmp_eq_u32 s66, 12
	s_cselect_b32 s43, s23, s41
	s_cselect_b32 s42, s31, s40
	s_cselect_b32 s41, s25, s65
	s_cselect_b32 s40, s37, s64
	v_lshl_add_u64 v[208:209], s[38:39], 0, v[192:193]
	s_add_i32 m0, s50, 0xc000
	ds_read_b128 v[160:163], v235
	ds_read_b128 v[164:167], v235 offset:1024
	ds_read_b128 v[168:171], v235 offset:2048
	ds_read_b128 v[172:175], v235 offset:3072
	ds_read_b128 v[176:179], v235 offset:4096
	ds_read_b128 v[180:183], v235 offset:5120
	ds_read_b128 v[200:203], v235 offset:6144
	ds_read_b128 v[204:207], v235 offset:7168
	global_load_lds_dwordx4 v[208:209], off
	s_add_i32 m0, s50, 0xe000
	v_lshl_add_u64 v[208:209], s[38:39], 0, v[194:195]
	global_load_lds_dwordx4 v[208:209], off
	s_waitcnt vmcnt(8) lgkmcnt(0)
	s_barrier
	s_setprio 1
	v_mfma_f32_16x16x32_bf16 v[128:131], v[120:123], v[160:163], 0
	v_mfma_f32_16x16x32_bf16 v[124:127], v[136:139], v[160:163], 0
	v_mfma_f32_16x16x32_bf16 v[108:111], v[120:123], v[168:171], 0
	v_mfma_f32_16x16x32_bf16 v[104:107], v[136:139], v[168:171], 0
	v_mfma_f32_16x16x32_bf16 v[92:95], v[120:123], v[176:179], 0
	v_mfma_f32_16x16x32_bf16 v[88:91], v[136:139], v[176:179], 0
	v_mfma_f32_16x16x32_bf16 v[76:79], v[120:123], v[200:203], 0
	v_mfma_f32_16x16x32_bf16 v[72:75], v[136:139], v[200:203], 0
	v_mfma_f32_16x16x32_bf16 v[128:131], v[132:135], v[164:167], v[128:131]
	v_mfma_f32_16x16x32_bf16 v[124:127], v[140:143], v[164:167], v[124:127]
	v_mfma_f32_16x16x32_bf16 v[108:111], v[132:135], v[172:175], v[108:111]
	v_mfma_f32_16x16x32_bf16 v[104:107], v[140:143], v[172:175], v[104:107]
	v_mfma_f32_16x16x32_bf16 v[92:95], v[132:135], v[180:183], v[92:95]
	v_mfma_f32_16x16x32_bf16 v[88:91], v[140:143], v[180:183], v[88:91]
	v_mfma_f32_16x16x32_bf16 v[76:79], v[132:135], v[204:207], v[76:79]
	v_mfma_f32_16x16x32_bf16 v[72:75], v[140:143], v[204:207], v[72:75]
	v_mfma_f32_16x16x32_bf16 v[116:119], v[144:147], v[160:163], 0
	v_mfma_f32_16x16x32_bf16 v[112:115], v[152:155], v[160:163], 0
	v_mfma_f32_16x16x32_bf16 v[100:103], v[144:147], v[168:171], 0
	v_mfma_f32_16x16x32_bf16 v[96:99], v[152:155], v[168:171], 0
	v_mfma_f32_16x16x32_bf16 v[84:87], v[144:147], v[176:179], 0
	v_mfma_f32_16x16x32_bf16 v[80:83], v[152:155], v[176:179], 0
	v_mfma_f32_16x16x32_bf16 v[68:71], v[144:147], v[200:203], 0
	v_mfma_f32_16x16x32_bf16 v[64:67], v[152:155], v[200:203], 0
	v_mfma_f32_16x16x32_bf16 v[116:119], v[148:151], v[164:167], v[116:119]
	v_mfma_f32_16x16x32_bf16 v[112:115], v[156:159], v[164:167], v[112:115]
	v_mfma_f32_16x16x32_bf16 v[100:103], v[148:151], v[172:175], v[100:103]
	v_mfma_f32_16x16x32_bf16 v[96:99], v[156:159], v[172:175], v[96:99]
	s_setprio 2
	s_barrier
	v_mfma_f32_16x16x32_bf16 v[84:87], v[148:151], v[180:183], v[84:87]
	v_mfma_f32_16x16x32_bf16 v[80:83], v[156:159], v[180:183], v[80:83]
	v_mfma_f32_16x16x32_bf16 v[68:71], v[148:151], v[204:207], v[68:71]
	v_mfma_f32_16x16x32_bf16 v[64:67], v[156:159], v[204:207], v[64:67]
	s_setprio 2
	s_mov_b32 m0, s50
	v_lshl_add_u64 v[212:213], s[42:43], 0, v[184:185]
	global_load_lds_dwordx4 v[212:213], off
	s_mov_b32 m0, s51
	v_lshl_add_u64 v[214:215], s[42:43], 0, v[188:189]
	global_load_lds_dwordx4 v[214:215], off
	s_add_i32 s67, s62, s49
	v_lshl_add_u64 v[208:209], s[40:41], 0, v[186:187]
	s_mov_b32 m0, s67
	ds_read_b128 v[160:163], v235 offset:16384
	ds_read_b128 v[164:167], v235 offset:17408
	ds_read_b128 v[168:171], v235 offset:18432
	ds_read_b128 v[172:175], v235 offset:19456
	ds_read_b128 v[176:179], v235 offset:20480
	ds_read_b128 v[180:183], v235 offset:21504
	ds_read_b128 v[200:203], v235 offset:22528
	ds_read_b128 v[204:207], v235 offset:23552
	global_load_lds_dwordx4 v[208:209], off
	s_add_i32 m0, s67, 0x2000
	s_add_u32 s68, s40, 0x40000
	v_lshl_add_u64 v[210:211], s[40:41], 0, v[190:191]
	s_addc_u32 s69, s41, 0
	s_add_i32 s67, s63, s49
	global_load_lds_dwordx4 v[210:211], off
	v_lshl_add_u64 v[252:253], s[68:69], 0, v[186:187]
	s_mov_b32 m0, s67
	global_load_lds_dwordx4 v[252:253], off
	s_add_i32 m0, s67, 0x2000
	v_lshl_add_u64 v[252:253], s[68:69], 0, v[190:191]
	global_load_lds_dwordx4 v[252:253], off
	s_waitcnt vmcnt(8) lgkmcnt(0)
	s_barrier
	s_setprio 1
	v_mfma_f32_16x16x32_bf16 v[60:63], v[120:123], v[160:163], 0
	v_mfma_f32_16x16x32_bf16 v[56:59], v[136:139], v[160:163], 0
	v_mfma_f32_16x16x32_bf16 v[44:47], v[120:123], v[168:171], 0
	v_mfma_f32_16x16x32_bf16 v[40:43], v[136:139], v[168:171], 0
	v_mfma_f32_16x16x32_bf16 v[28:31], v[120:123], v[176:179], 0
	v_mfma_f32_16x16x32_bf16 v[24:27], v[136:139], v[176:179], 0
	v_mfma_f32_16x16x32_bf16 v[12:15], v[120:123], v[200:203], 0
	v_mfma_f32_16x16x32_bf16 v[8:11], v[136:139], v[200:203], 0
	v_mfma_f32_16x16x32_bf16 v[60:63], v[132:135], v[164:167], v[60:63]
	v_mfma_f32_16x16x32_bf16 v[56:59], v[140:143], v[164:167], v[56:59]
	v_mfma_f32_16x16x32_bf16 v[44:47], v[132:135], v[172:175], v[44:47]
	v_mfma_f32_16x16x32_bf16 v[40:43], v[140:143], v[172:175], v[40:43]
	v_mfma_f32_16x16x32_bf16 v[28:31], v[132:135], v[180:183], v[28:31]
	v_mfma_f32_16x16x32_bf16 v[24:27], v[140:143], v[180:183], v[24:27]
	v_mfma_f32_16x16x32_bf16 v[12:15], v[132:135], v[204:207], v[12:15]
	v_mfma_f32_16x16x32_bf16 v[8:11], v[140:143], v[204:207], v[8:11]
	v_mfma_f32_16x16x32_bf16 v[52:55], v[144:147], v[160:163], 0
	v_mfma_f32_16x16x32_bf16 v[48:51], v[152:155], v[160:163], 0
	v_mfma_f32_16x16x32_bf16 v[36:39], v[144:147], v[168:171], 0
	v_mfma_f32_16x16x32_bf16 v[32:35], v[152:155], v[168:171], 0
	v_mfma_f32_16x16x32_bf16 v[20:23], v[144:147], v[176:179], 0
	v_mfma_f32_16x16x32_bf16 v[16:19], v[152:155], v[176:179], 0
	v_mfma_f32_16x16x32_bf16 v[4:7], v[144:147], v[200:203], 0
	v_mfma_f32_16x16x32_bf16 v[0:3], v[152:155], v[200:203], 0
	v_mfma_f32_16x16x32_bf16 v[52:55], v[148:151], v[164:167], v[52:55]
	v_mfma_f32_16x16x32_bf16 v[48:51], v[156:159], v[164:167], v[48:51]
	v_mfma_f32_16x16x32_bf16 v[36:39], v[148:151], v[172:175], v[36:39]
	v_mfma_f32_16x16x32_bf16 v[32:35], v[156:159], v[172:175], v[32:35]
	s_setprio 2
	s_barrier
	v_mfma_f32_16x16x32_bf16 v[20:23], v[148:151], v[180:183], v[20:23]
	v_mfma_f32_16x16x32_bf16 v[16:19], v[156:159], v[180:183], v[16:19]
	v_mfma_f32_16x16x32_bf16 v[4:7], v[148:151], v[204:207], v[4:7]
	v_mfma_f32_16x16x32_bf16 v[0:3], v[156:159], v[204:207], v[0:3]
	s_setprio 0
	s_add_i32 s67, 0, 0x18000
	s_add_i32 s68, 0, 0x1c000
	v_add_u32_e32 v140, s67, v232
	v_add_u32_e32 v156, s68, v232
	ds_read_b128 v[120:123], v140
	ds_read_b128 v[132:135], v140 offset:1024
	ds_read_b128 v[136:139], v140 offset:2048
	ds_read_b128 v[140:143], v140 offset:3072
	ds_read_b128 v[144:147], v156
	ds_read_b128 v[148:151], v156 offset:1024
	ds_read_b128 v[152:155], v156 offset:2048
	ds_read_b128 v[156:159], v156 offset:3072
	s_add_u32 s42, s42, 0x40000
	s_addc_u32 s43, s43, 0
	s_mov_b32 m0, s54
	v_lshl_add_u64 v[216:217], s[42:43], 0, v[184:185]
	ds_read_b128 v[160:163], v235 offset:32768
	ds_read_b128 v[164:167], v235 offset:33792
	ds_read_b128 v[168:171], v235 offset:34816
	ds_read_b128 v[172:175], v235 offset:35840
	ds_read_b128 v[176:179], v235 offset:36864
	ds_read_b128 v[180:183], v235 offset:37888
	ds_read_b128 v[200:203], v235 offset:38912
	ds_read_b128 v[204:207], v235 offset:39936
	global_load_lds_dwordx4 v[216:217], off
	s_mov_b32 m0, s55
	v_lshl_add_u64 v[216:217], s[42:43], 0, v[188:189]
	global_load_lds_dwordx4 v[216:217], off
	s_waitcnt vmcnt(8) lgkmcnt(0)
	s_barrier
	s_setprio 1
	v_mfma_f32_16x16x32_bf16 v[128:131], v[120:123], v[160:163], v[128:131]
	v_mfma_f32_16x16x32_bf16 v[124:127], v[136:139], v[160:163], v[124:127]
	v_mfma_f32_16x16x32_bf16 v[108:111], v[120:123], v[168:171], v[108:111]
	v_mfma_f32_16x16x32_bf16 v[104:107], v[136:139], v[168:171], v[104:107]
	v_mfma_f32_16x16x32_bf16 v[92:95], v[120:123], v[176:179], v[92:95]
	v_mfma_f32_16x16x32_bf16 v[88:91], v[136:139], v[176:179], v[88:91]
	v_mfma_f32_16x16x32_bf16 v[76:79], v[120:123], v[200:203], v[76:79]
	v_mfma_f32_16x16x32_bf16 v[72:75], v[136:139], v[200:203], v[72:75]
	v_mfma_f32_16x16x32_bf16 v[128:131], v[132:135], v[164:167], v[128:131]
	v_mfma_f32_16x16x32_bf16 v[124:127], v[140:143], v[164:167], v[124:127]
	v_mfma_f32_16x16x32_bf16 v[108:111], v[132:135], v[172:175], v[108:111]
	v_mfma_f32_16x16x32_bf16 v[104:107], v[140:143], v[172:175], v[104:107]
	v_mfma_f32_16x16x32_bf16 v[92:95], v[132:135], v[180:183], v[92:95]
	v_mfma_f32_16x16x32_bf16 v[88:91], v[140:143], v[180:183], v[88:91]
	v_mfma_f32_16x16x32_bf16 v[76:79], v[132:135], v[204:207], v[76:79]
	v_mfma_f32_16x16x32_bf16 v[72:75], v[140:143], v[204:207], v[72:75]
	v_mfma_f32_16x16x32_bf16 v[116:119], v[144:147], v[160:163], v[116:119]
	v_mfma_f32_16x16x32_bf16 v[112:115], v[152:155], v[160:163], v[112:115]
	v_mfma_f32_16x16x32_bf16 v[100:103], v[144:147], v[168:171], v[100:103]
	v_mfma_f32_16x16x32_bf16 v[96:99], v[152:155], v[168:171], v[96:99]
	v_mfma_f32_16x16x32_bf16 v[84:87], v[144:147], v[176:179], v[84:87]
	v_mfma_f32_16x16x32_bf16 v[80:83], v[152:155], v[176:179], v[80:83]
	v_mfma_f32_16x16x32_bf16 v[68:71], v[144:147], v[200:203], v[68:71]
	v_mfma_f32_16x16x32_bf16 v[64:67], v[152:155], v[200:203], v[64:67]
	v_mfma_f32_16x16x32_bf16 v[116:119], v[148:151], v[164:167], v[116:119]
	v_mfma_f32_16x16x32_bf16 v[112:115], v[156:159], v[164:167], v[112:115]
	v_mfma_f32_16x16x32_bf16 v[100:103], v[148:151], v[172:175], v[100:103]
	v_mfma_f32_16x16x32_bf16 v[96:99], v[156:159], v[172:175], v[96:99]
	s_setprio 2
	s_barrier
	v_mfma_f32_16x16x32_bf16 v[84:87], v[148:151], v[180:183], v[84:87]
	v_mfma_f32_16x16x32_bf16 v[80:83], v[156:159], v[180:183], v[80:83]
	v_mfma_f32_16x16x32_bf16 v[68:71], v[148:151], v[204:207], v[68:71]
	v_mfma_f32_16x16x32_bf16 v[64:67], v[156:159], v[204:207], v[64:67]
	s_setprio 2
	s_mov_b32 m0, s57
	v_lshl_add_u64 v[252:253], v[212:213], 0, s[18:19]
	global_load_lds_dwordx4 v[252:253], off
	s_mov_b32 m0, s58
	v_lshl_add_u64 v[252:253], v[214:215], 0, s[18:19]
	global_load_lds_dwordx4 v[252:253], off
	s_add_i32 s42, s67, s49
	v_lshl_add_u64 v[208:209], v[208:209], 0, s[18:19]
	s_mov_b32 m0, s42
	ds_read_b128 v[160:163], v235 offset:49152
	ds_read_b128 v[164:167], v235 offset:50176
	ds_read_b128 v[168:171], v235 offset:51200
	ds_read_b128 v[172:175], v235 offset:52224
	ds_read_b128 v[176:179], v235 offset:53248
	ds_read_b128 v[180:183], v235 offset:54272
	ds_read_b128 v[200:203], v235 offset:55296
	ds_read_b128 v[204:207], v235 offset:56320
	global_load_lds_dwordx4 v[208:209], off
	s_add_i32 m0, s42, 0x2000
	s_add_u32 s40, s40, 0x40080
	v_lshl_add_u64 v[208:209], v[210:211], 0, s[18:19]
	s_addc_u32 s41, s41, 0
	s_add_i32 s42, s68, s49
	global_load_lds_dwordx4 v[208:209], off
	s_mov_b32 m0, s42
	v_lshl_add_u64 v[208:209], s[40:41], 0, v[186:187]
	global_load_lds_dwordx4 v[208:209], off
	s_add_i32 m0, s42, 0x2000
	v_lshl_add_u64 v[208:209], s[40:41], 0, v[190:191]
	global_load_lds_dwordx4 v[208:209], off
	s_waitcnt vmcnt(8) lgkmcnt(0)
	s_barrier
	s_setprio 1
	v_mfma_f32_16x16x32_bf16 v[60:63], v[120:123], v[160:163], v[60:63]
	v_mfma_f32_16x16x32_bf16 v[56:59], v[136:139], v[160:163], v[56:59]
	v_mfma_f32_16x16x32_bf16 v[44:47], v[120:123], v[168:171], v[44:47]
	v_mfma_f32_16x16x32_bf16 v[40:43], v[136:139], v[168:171], v[40:43]
	v_mfma_f32_16x16x32_bf16 v[28:31], v[120:123], v[176:179], v[28:31]
	v_mfma_f32_16x16x32_bf16 v[24:27], v[136:139], v[176:179], v[24:27]
	v_mfma_f32_16x16x32_bf16 v[12:15], v[120:123], v[200:203], v[12:15]
	v_mfma_f32_16x16x32_bf16 v[8:11], v[136:139], v[200:203], v[8:11]
	v_mfma_f32_16x16x32_bf16 v[60:63], v[132:135], v[164:167], v[60:63]
	v_mfma_f32_16x16x32_bf16 v[56:59], v[140:143], v[164:167], v[56:59]
	v_mfma_f32_16x16x32_bf16 v[44:47], v[132:135], v[172:175], v[44:47]
	v_mfma_f32_16x16x32_bf16 v[40:43], v[140:143], v[172:175], v[40:43]
	v_mfma_f32_16x16x32_bf16 v[28:31], v[132:135], v[180:183], v[28:31]
	v_mfma_f32_16x16x32_bf16 v[24:27], v[140:143], v[180:183], v[24:27]
	v_mfma_f32_16x16x32_bf16 v[12:15], v[132:135], v[204:207], v[12:15]
	v_mfma_f32_16x16x32_bf16 v[8:11], v[140:143], v[204:207], v[8:11]
	v_mfma_f32_16x16x32_bf16 v[52:55], v[144:147], v[160:163], v[52:55]
	v_mfma_f32_16x16x32_bf16 v[48:51], v[152:155], v[160:163], v[48:51]
	v_mfma_f32_16x16x32_bf16 v[36:39], v[144:147], v[168:171], v[36:39]
	v_mfma_f32_16x16x32_bf16 v[32:35], v[152:155], v[168:171], v[32:35]
	v_mfma_f32_16x16x32_bf16 v[20:23], v[144:147], v[176:179], v[20:23]
	v_mfma_f32_16x16x32_bf16 v[16:19], v[152:155], v[176:179], v[16:19]
	v_mfma_f32_16x16x32_bf16 v[4:7], v[144:147], v[200:203], v[4:7]
	v_mfma_f32_16x16x32_bf16 v[0:3], v[152:155], v[200:203], v[0:3]
	v_mfma_f32_16x16x32_bf16 v[52:55], v[148:151], v[164:167], v[52:55]
	v_mfma_f32_16x16x32_bf16 v[48:51], v[156:159], v[164:167], v[48:51]
	v_mfma_f32_16x16x32_bf16 v[36:39], v[148:151], v[172:175], v[36:39]
	v_mfma_f32_16x16x32_bf16 v[32:35], v[156:159], v[172:175], v[32:35]
	s_setprio 2
	s_barrier
	v_mfma_f32_16x16x32_bf16 v[20:23], v[148:151], v[180:183], v[20:23]
	v_mfma_f32_16x16x32_bf16 v[16:19], v[156:159], v[180:183], v[16:19]
	v_mfma_f32_16x16x32_bf16 v[4:7], v[148:151], v[204:207], v[4:7]
	v_mfma_f32_16x16x32_bf16 v[0:3], v[156:159], v[204:207], v[0:3]
	s_setprio 0
	s_add_i32 s66, s66, 2
	s_add_u32 s38, s38, 0x100
	s_addc_u32 s39, s39, 0
	s_add_u32 s64, s64, 0x100
	s_addc_u32 s65, s65, 0
	s_cmp_gt_u32 s66, 13
.LBB0_1146:
	ds_read_b128 v[120:123], v233
	ds_read_b128 v[132:135], v233 offset:1024
	ds_read_b128 v[136:139], v233 offset:2048
	ds_read_b128 v[140:143], v233 offset:3072
	ds_read_b128 v[144:147], v234
	ds_read_b128 v[148:151], v234 offset:1024
	ds_read_b128 v[152:155], v234 offset:2048
	ds_read_b128 v[156:159], v234 offset:3072
	s_add_u32 s40, s38, 0xfffc0080
	s_addc_u32 s41, s39, -1
	s_cmp_eq_u32 s66, 12
	s_cselect_b32 s43, s23, s41
	s_cselect_b32 s42, s31, s40
	s_cselect_b32 s41, s25, s65
	s_cselect_b32 s40, s37, s64
	v_lshl_add_u64 v[208:209], s[38:39], 0, v[192:193]
	s_add_i32 m0, s50, 0xc000
	ds_read_b128 v[160:163], v235
	ds_read_b128 v[164:167], v235 offset:1024
	ds_read_b128 v[168:171], v235 offset:2048
	ds_read_b128 v[172:175], v235 offset:3072
	ds_read_b128 v[176:179], v235 offset:4096
	ds_read_b128 v[180:183], v235 offset:5120
	ds_read_b128 v[200:203], v235 offset:6144
	ds_read_b128 v[204:207], v235 offset:7168
	global_load_lds_dwordx4 v[208:209], off
	s_add_i32 m0, s50, 0xe000
	v_lshl_add_u64 v[208:209], s[38:39], 0, v[194:195]
	global_load_lds_dwordx4 v[208:209], off
	s_waitcnt vmcnt(8) lgkmcnt(0)
	s_barrier
	s_setprio 1
	v_mfma_f32_16x16x32_bf16 v[128:131], v[120:123], v[160:163], v[128:131]
	v_mfma_f32_16x16x32_bf16 v[124:127], v[136:139], v[160:163], v[124:127]
	v_mfma_f32_16x16x32_bf16 v[108:111], v[120:123], v[168:171], v[108:111]
	v_mfma_f32_16x16x32_bf16 v[104:107], v[136:139], v[168:171], v[104:107]
	v_mfma_f32_16x16x32_bf16 v[92:95], v[120:123], v[176:179], v[92:95]
	v_mfma_f32_16x16x32_bf16 v[88:91], v[136:139], v[176:179], v[88:91]
	v_mfma_f32_16x16x32_bf16 v[76:79], v[120:123], v[200:203], v[76:79]
	v_mfma_f32_16x16x32_bf16 v[72:75], v[136:139], v[200:203], v[72:75]
	v_mfma_f32_16x16x32_bf16 v[128:131], v[132:135], v[164:167], v[128:131]
	v_mfma_f32_16x16x32_bf16 v[124:127], v[140:143], v[164:167], v[124:127]
	v_mfma_f32_16x16x32_bf16 v[108:111], v[132:135], v[172:175], v[108:111]
	v_mfma_f32_16x16x32_bf16 v[104:107], v[140:143], v[172:175], v[104:107]
	v_mfma_f32_16x16x32_bf16 v[92:95], v[132:135], v[180:183], v[92:95]
	v_mfma_f32_16x16x32_bf16 v[88:91], v[140:143], v[180:183], v[88:91]
	v_mfma_f32_16x16x32_bf16 v[76:79], v[132:135], v[204:207], v[76:79]
	v_mfma_f32_16x16x32_bf16 v[72:75], v[140:143], v[204:207], v[72:75]
	v_mfma_f32_16x16x32_bf16 v[116:119], v[144:147], v[160:163], v[116:119]
	v_mfma_f32_16x16x32_bf16 v[112:115], v[152:155], v[160:163], v[112:115]
	v_mfma_f32_16x16x32_bf16 v[100:103], v[144:147], v[168:171], v[100:103]
	v_mfma_f32_16x16x32_bf16 v[96:99], v[152:155], v[168:171], v[96:99]
	v_mfma_f32_16x16x32_bf16 v[84:87], v[144:147], v[176:179], v[84:87]
	v_mfma_f32_16x16x32_bf16 v[80:83], v[152:155], v[176:179], v[80:83]
	v_mfma_f32_16x16x32_bf16 v[68:71], v[144:147], v[200:203], v[68:71]
	v_mfma_f32_16x16x32_bf16 v[64:67], v[152:155], v[200:203], v[64:67]
	v_mfma_f32_16x16x32_bf16 v[116:119], v[148:151], v[164:167], v[116:119]
	v_mfma_f32_16x16x32_bf16 v[112:115], v[156:159], v[164:167], v[112:115]
	v_mfma_f32_16x16x32_bf16 v[100:103], v[148:151], v[172:175], v[100:103]
	v_mfma_f32_16x16x32_bf16 v[96:99], v[156:159], v[172:175], v[96:99]
	s_setprio 2
	s_barrier
	v_mfma_f32_16x16x32_bf16 v[84:87], v[148:151], v[180:183], v[84:87]
	v_mfma_f32_16x16x32_bf16 v[80:83], v[156:159], v[180:183], v[80:83]
	v_mfma_f32_16x16x32_bf16 v[68:71], v[148:151], v[204:207], v[68:71]
	v_mfma_f32_16x16x32_bf16 v[64:67], v[156:159], v[204:207], v[64:67]
	s_setprio 2
	s_mov_b32 m0, s50
	v_lshl_add_u64 v[212:213], s[42:43], 0, v[184:185]
	global_load_lds_dwordx4 v[212:213], off
	s_mov_b32 m0, s51
	v_lshl_add_u64 v[214:215], s[42:43], 0, v[188:189]
	global_load_lds_dwordx4 v[214:215], off
	s_add_i32 s67, s62, s49
	v_lshl_add_u64 v[208:209], s[40:41], 0, v[186:187]
	s_mov_b32 m0, s67
	ds_read_b128 v[160:163], v235 offset:16384
	ds_read_b128 v[164:167], v235 offset:17408
	ds_read_b128 v[168:171], v235 offset:18432
	ds_read_b128 v[172:175], v235 offset:19456
	ds_read_b128 v[176:179], v235 offset:20480
	ds_read_b128 v[180:183], v235 offset:21504
	ds_read_b128 v[200:203], v235 offset:22528
	ds_read_b128 v[204:207], v235 offset:23552
	global_load_lds_dwordx4 v[208:209], off
	s_add_i32 m0, s67, 0x2000
	s_add_u32 s68, s40, 0x40000
	v_lshl_add_u64 v[210:211], s[40:41], 0, v[190:191]
	s_addc_u32 s69, s41, 0
	s_add_i32 s67, s63, s49
	global_load_lds_dwordx4 v[210:211], off
	v_lshl_add_u64 v[252:253], s[68:69], 0, v[186:187]
	s_mov_b32 m0, s67
	global_load_lds_dwordx4 v[252:253], off
	s_add_i32 m0, s67, 0x2000
	v_lshl_add_u64 v[252:253], s[68:69], 0, v[190:191]
	global_load_lds_dwordx4 v[252:253], off
	s_waitcnt vmcnt(8) lgkmcnt(0)
	s_barrier
	s_setprio 1
	v_mfma_f32_16x16x32_bf16 v[60:63], v[120:123], v[160:163], v[60:63]
	v_mfma_f32_16x16x32_bf16 v[56:59], v[136:139], v[160:163], v[56:59]
	v_mfma_f32_16x16x32_bf16 v[44:47], v[120:123], v[168:171], v[44:47]
	v_mfma_f32_16x16x32_bf16 v[40:43], v[136:139], v[168:171], v[40:43]
	v_mfma_f32_16x16x32_bf16 v[28:31], v[120:123], v[176:179], v[28:31]
	v_mfma_f32_16x16x32_bf16 v[24:27], v[136:139], v[176:179], v[24:27]
	v_mfma_f32_16x16x32_bf16 v[12:15], v[120:123], v[200:203], v[12:15]
	v_mfma_f32_16x16x32_bf16 v[8:11], v[136:139], v[200:203], v[8:11]
	v_mfma_f32_16x16x32_bf16 v[60:63], v[132:135], v[164:167], v[60:63]
	v_mfma_f32_16x16x32_bf16 v[56:59], v[140:143], v[164:167], v[56:59]
	v_mfma_f32_16x16x32_bf16 v[44:47], v[132:135], v[172:175], v[44:47]
	v_mfma_f32_16x16x32_bf16 v[40:43], v[140:143], v[172:175], v[40:43]
	v_mfma_f32_16x16x32_bf16 v[28:31], v[132:135], v[180:183], v[28:31]
	v_mfma_f32_16x16x32_bf16 v[24:27], v[140:143], v[180:183], v[24:27]
	v_mfma_f32_16x16x32_bf16 v[12:15], v[132:135], v[204:207], v[12:15]
	v_mfma_f32_16x16x32_bf16 v[8:11], v[140:143], v[204:207], v[8:11]
	v_mfma_f32_16x16x32_bf16 v[52:55], v[144:147], v[160:163], v[52:55]
	v_mfma_f32_16x16x32_bf16 v[48:51], v[152:155], v[160:163], v[48:51]
	v_mfma_f32_16x16x32_bf16 v[36:39], v[144:147], v[168:171], v[36:39]
	v_mfma_f32_16x16x32_bf16 v[32:35], v[152:155], v[168:171], v[32:35]
	v_mfma_f32_16x16x32_bf16 v[20:23], v[144:147], v[176:179], v[20:23]
	v_mfma_f32_16x16x32_bf16 v[16:19], v[152:155], v[176:179], v[16:19]
	v_mfma_f32_16x16x32_bf16 v[4:7], v[144:147], v[200:203], v[4:7]
	v_mfma_f32_16x16x32_bf16 v[0:3], v[152:155], v[200:203], v[0:3]
	v_mfma_f32_16x16x32_bf16 v[52:55], v[148:151], v[164:167], v[52:55]
	v_mfma_f32_16x16x32_bf16 v[48:51], v[156:159], v[164:167], v[48:51]
	v_mfma_f32_16x16x32_bf16 v[36:39], v[148:151], v[172:175], v[36:39]
	v_mfma_f32_16x16x32_bf16 v[32:35], v[156:159], v[172:175], v[32:35]
	s_setprio 2
	s_barrier
	v_mfma_f32_16x16x32_bf16 v[20:23], v[148:151], v[180:183], v[20:23]
	v_mfma_f32_16x16x32_bf16 v[16:19], v[156:159], v[180:183], v[16:19]
	v_mfma_f32_16x16x32_bf16 v[4:7], v[148:151], v[204:207], v[4:7]
	v_mfma_f32_16x16x32_bf16 v[0:3], v[156:159], v[204:207], v[0:3]
	s_setprio 0
	s_add_i32 s67, 0, 0x18000
	s_add_i32 s68, 0, 0x1c000
	v_add_u32_e32 v140, s67, v232
	v_add_u32_e32 v156, s68, v232
	ds_read_b128 v[120:123], v140
	ds_read_b128 v[132:135], v140 offset:1024
	ds_read_b128 v[136:139], v140 offset:2048
	ds_read_b128 v[140:143], v140 offset:3072
	ds_read_b128 v[144:147], v156
	ds_read_b128 v[148:151], v156 offset:1024
	ds_read_b128 v[152:155], v156 offset:2048
	ds_read_b128 v[156:159], v156 offset:3072
	s_add_u32 s42, s42, 0x40000
	s_addc_u32 s43, s43, 0
	s_mov_b32 m0, s54
	v_lshl_add_u64 v[216:217], s[42:43], 0, v[184:185]
	ds_read_b128 v[160:163], v235 offset:32768
	ds_read_b128 v[164:167], v235 offset:33792
	ds_read_b128 v[168:171], v235 offset:34816
	ds_read_b128 v[172:175], v235 offset:35840
	ds_read_b128 v[176:179], v235 offset:36864
	ds_read_b128 v[180:183], v235 offset:37888
	ds_read_b128 v[200:203], v235 offset:38912
	ds_read_b128 v[204:207], v235 offset:39936
	global_load_lds_dwordx4 v[216:217], off
	s_mov_b32 m0, s55
	v_lshl_add_u64 v[216:217], s[42:43], 0, v[188:189]
	global_load_lds_dwordx4 v[216:217], off
	s_waitcnt vmcnt(8) lgkmcnt(0)
	s_barrier
	s_setprio 1
	v_mfma_f32_16x16x32_bf16 v[128:131], v[120:123], v[160:163], v[128:131]
	v_mfma_f32_16x16x32_bf16 v[124:127], v[136:139], v[160:163], v[124:127]
	v_mfma_f32_16x16x32_bf16 v[108:111], v[120:123], v[168:171], v[108:111]
	v_mfma_f32_16x16x32_bf16 v[104:107], v[136:139], v[168:171], v[104:107]
	v_mfma_f32_16x16x32_bf16 v[92:95], v[120:123], v[176:179], v[92:95]
	v_mfma_f32_16x16x32_bf16 v[88:91], v[136:139], v[176:179], v[88:91]
	v_mfma_f32_16x16x32_bf16 v[76:79], v[120:123], v[200:203], v[76:79]
	v_mfma_f32_16x16x32_bf16 v[72:75], v[136:139], v[200:203], v[72:75]
	v_mfma_f32_16x16x32_bf16 v[128:131], v[132:135], v[164:167], v[128:131]
	v_mfma_f32_16x16x32_bf16 v[124:127], v[140:143], v[164:167], v[124:127]
	v_mfma_f32_16x16x32_bf16 v[108:111], v[132:135], v[172:175], v[108:111]
	v_mfma_f32_16x16x32_bf16 v[104:107], v[140:143], v[172:175], v[104:107]
	v_mfma_f32_16x16x32_bf16 v[92:95], v[132:135], v[180:183], v[92:95]
	v_mfma_f32_16x16x32_bf16 v[88:91], v[140:143], v[180:183], v[88:91]
	v_mfma_f32_16x16x32_bf16 v[76:79], v[132:135], v[204:207], v[76:79]
	v_mfma_f32_16x16x32_bf16 v[72:75], v[140:143], v[204:207], v[72:75]
	v_mfma_f32_16x16x32_bf16 v[116:119], v[144:147], v[160:163], v[116:119]
	v_mfma_f32_16x16x32_bf16 v[112:115], v[152:155], v[160:163], v[112:115]
	v_mfma_f32_16x16x32_bf16 v[100:103], v[144:147], v[168:171], v[100:103]
	v_mfma_f32_16x16x32_bf16 v[96:99], v[152:155], v[168:171], v[96:99]
	v_mfma_f32_16x16x32_bf16 v[84:87], v[144:147], v[176:179], v[84:87]
	v_mfma_f32_16x16x32_bf16 v[80:83], v[152:155], v[176:179], v[80:83]
	v_mfma_f32_16x16x32_bf16 v[68:71], v[144:147], v[200:203], v[68:71]
	v_mfma_f32_16x16x32_bf16 v[64:67], v[152:155], v[200:203], v[64:67]
	v_mfma_f32_16x16x32_bf16 v[116:119], v[148:151], v[164:167], v[116:119]
	v_mfma_f32_16x16x32_bf16 v[112:115], v[156:159], v[164:167], v[112:115]
	v_mfma_f32_16x16x32_bf16 v[100:103], v[148:151], v[172:175], v[100:103]
	v_mfma_f32_16x16x32_bf16 v[96:99], v[156:159], v[172:175], v[96:99]
	s_setprio 2
	s_barrier
	v_mfma_f32_16x16x32_bf16 v[84:87], v[148:151], v[180:183], v[84:87]
	v_mfma_f32_16x16x32_bf16 v[80:83], v[156:159], v[180:183], v[80:83]
	v_mfma_f32_16x16x32_bf16 v[68:71], v[148:151], v[204:207], v[68:71]
	v_mfma_f32_16x16x32_bf16 v[64:67], v[156:159], v[204:207], v[64:67]
	s_setprio 2
	s_mov_b32 m0, s57
	v_lshl_add_u64 v[252:253], v[212:213], 0, s[18:19]
	global_load_lds_dwordx4 v[252:253], off
	s_mov_b32 m0, s58
	v_lshl_add_u64 v[252:253], v[214:215], 0, s[18:19]
	global_load_lds_dwordx4 v[252:253], off
	s_add_i32 s42, s67, s49
	v_lshl_add_u64 v[208:209], v[208:209], 0, s[18:19]
	s_mov_b32 m0, s42
	ds_read_b128 v[160:163], v235 offset:49152
	ds_read_b128 v[164:167], v235 offset:50176
	ds_read_b128 v[168:171], v235 offset:51200
	ds_read_b128 v[172:175], v235 offset:52224
	ds_read_b128 v[176:179], v235 offset:53248
	ds_read_b128 v[180:183], v235 offset:54272
	ds_read_b128 v[200:203], v235 offset:55296
	ds_read_b128 v[204:207], v235 offset:56320
	global_load_lds_dwordx4 v[208:209], off
	s_add_i32 m0, s42, 0x2000
	s_add_u32 s40, s40, 0x40080
	v_lshl_add_u64 v[208:209], v[210:211], 0, s[18:19]
	s_addc_u32 s41, s41, 0
	s_add_i32 s42, s68, s49
	global_load_lds_dwordx4 v[208:209], off
	s_mov_b32 m0, s42
	v_lshl_add_u64 v[208:209], s[40:41], 0, v[186:187]
	global_load_lds_dwordx4 v[208:209], off
	s_add_i32 m0, s42, 0x2000
	v_lshl_add_u64 v[208:209], s[40:41], 0, v[190:191]
	global_load_lds_dwordx4 v[208:209], off
	s_waitcnt vmcnt(8) lgkmcnt(0)
	s_barrier
	s_setprio 1
	v_mfma_f32_16x16x32_bf16 v[60:63], v[120:123], v[160:163], v[60:63]
	v_mfma_f32_16x16x32_bf16 v[56:59], v[136:139], v[160:163], v[56:59]
	v_mfma_f32_16x16x32_bf16 v[44:47], v[120:123], v[168:171], v[44:47]
	v_mfma_f32_16x16x32_bf16 v[40:43], v[136:139], v[168:171], v[40:43]
	v_mfma_f32_16x16x32_bf16 v[28:31], v[120:123], v[176:179], v[28:31]
	v_mfma_f32_16x16x32_bf16 v[24:27], v[136:139], v[176:179], v[24:27]
	v_mfma_f32_16x16x32_bf16 v[12:15], v[120:123], v[200:203], v[12:15]
	v_mfma_f32_16x16x32_bf16 v[8:11], v[136:139], v[200:203], v[8:11]
	v_mfma_f32_16x16x32_bf16 v[60:63], v[132:135], v[164:167], v[60:63]
	v_mfma_f32_16x16x32_bf16 v[56:59], v[140:143], v[164:167], v[56:59]
	v_mfma_f32_16x16x32_bf16 v[44:47], v[132:135], v[172:175], v[44:47]
	v_mfma_f32_16x16x32_bf16 v[40:43], v[140:143], v[172:175], v[40:43]
	v_mfma_f32_16x16x32_bf16 v[28:31], v[132:135], v[180:183], v[28:31]
	v_mfma_f32_16x16x32_bf16 v[24:27], v[140:143], v[180:183], v[24:27]
	v_mfma_f32_16x16x32_bf16 v[12:15], v[132:135], v[204:207], v[12:15]
	v_mfma_f32_16x16x32_bf16 v[8:11], v[140:143], v[204:207], v[8:11]
	v_mfma_f32_16x16x32_bf16 v[52:55], v[144:147], v[160:163], v[52:55]
	v_mfma_f32_16x16x32_bf16 v[48:51], v[152:155], v[160:163], v[48:51]
	v_mfma_f32_16x16x32_bf16 v[36:39], v[144:147], v[168:171], v[36:39]
	v_mfma_f32_16x16x32_bf16 v[32:35], v[152:155], v[168:171], v[32:35]
	v_mfma_f32_16x16x32_bf16 v[20:23], v[144:147], v[176:179], v[20:23]
	v_mfma_f32_16x16x32_bf16 v[16:19], v[152:155], v[176:179], v[16:19]
	v_mfma_f32_16x16x32_bf16 v[4:7], v[144:147], v[200:203], v[4:7]
	v_mfma_f32_16x16x32_bf16 v[0:3], v[152:155], v[200:203], v[0:3]
	v_mfma_f32_16x16x32_bf16 v[52:55], v[148:151], v[164:167], v[52:55]
	v_mfma_f32_16x16x32_bf16 v[48:51], v[156:159], v[164:167], v[48:51]
	v_mfma_f32_16x16x32_bf16 v[36:39], v[148:151], v[172:175], v[36:39]
	v_mfma_f32_16x16x32_bf16 v[32:35], v[156:159], v[172:175], v[32:35]
	s_setprio 2
	s_barrier
	v_mfma_f32_16x16x32_bf16 v[20:23], v[148:151], v[180:183], v[20:23]
	v_mfma_f32_16x16x32_bf16 v[16:19], v[156:159], v[180:183], v[16:19]
	v_mfma_f32_16x16x32_bf16 v[4:7], v[148:151], v[204:207], v[4:7]
	v_mfma_f32_16x16x32_bf16 v[0:3], v[156:159], v[204:207], v[0:3]
	s_setprio 0
	s_add_i32 s66, s66, 2
	s_add_u32 s38, s38, 0x100
	s_addc_u32 s39, s39, 0
	s_add_u32 s64, s64, 0x100
	s_addc_u32 s65, s65, 0
	s_cmp_gt_u32 s66, 13
	s_cbranch_scc0 .LBB0_1146

.LBB0_1309:
	s_add_u32 s51, s26, 0x100
	s_addc_u32 s52, s27, 0
	s_mov_b32 s53, -2
	ds_read_b128 v[128:131], v197
	ds_read_b128 v[132:135], v197 offset:1024
	ds_read_b128 v[136:139], v197 offset:2048
	ds_read_b128 v[140:143], v197 offset:3072
	ds_read_b128 v[144:147], v198
	ds_read_b128 v[148:151], v198 offset:1024
	ds_read_b128 v[152:155], v198 offset:2048
	ds_read_b128 v[156:159], v198 offset:3072
	s_add_u32 s4, s24, 0x100
	s_addc_u32 s5, s25, 0
	s_cmp_eq_u32 s53, 40
	s_cselect_b32 s29, s21, s5
	s_cselect_b32 s28, s20, s4
	s_cselect_b32 s27, s23, s52
	s_cselect_b32 s26, s22, s51
	v_lshl_add_u64 v[212:213], s[24:25], 0, v[172:173]
	s_add_i32 m0, s36, 0xc000
	ds_read_b128 v[160:163], v199
	ds_read_b128 v[180:183], v199 offset:1024
	ds_read_b128 v[184:187], v199 offset:2048
	ds_read_b128 v[188:191], v199 offset:3072
	ds_read_b128 v[192:195], v199 offset:4096
	ds_read_b128 v[200:203], v199 offset:5120
	ds_read_b128 v[204:207], v199 offset:6144
	ds_read_b128 v[208:211], v199 offset:7168
	global_load_lds_dwordx4 v[212:213], off
	s_add_i32 m0, s36, 0xe000
	v_lshl_add_u64 v[212:213], s[24:25], 0, v[174:175]
	global_load_lds_dwordx4 v[212:213], off
	s_waitcnt vmcnt(8) lgkmcnt(0)
	s_barrier
	s_setprio 1
	v_mfma_f32_16x16x32_bf16 v[124:127], v[128:131], v[160:163], 0
	v_mfma_f32_16x16x32_bf16 v[120:123], v[136:139], v[160:163], 0
	v_mfma_f32_16x16x32_bf16 v[116:119], v[128:131], v[184:187], 0
	v_mfma_f32_16x16x32_bf16 v[108:111], v[136:139], v[184:187], 0
	v_mfma_f32_16x16x32_bf16 v[88:91], v[128:131], v[192:195], 0
	v_mfma_f32_16x16x32_bf16 v[100:103], v[136:139], v[192:195], 0
	v_mfma_f32_16x16x32_bf16 v[72:75], v[128:131], v[204:207], 0
	v_mfma_f32_16x16x32_bf16 v[76:79], v[136:139], v[204:207], 0
	v_mfma_f32_16x16x32_bf16 v[124:127], v[132:135], v[180:183], v[124:127]
	v_mfma_f32_16x16x32_bf16 v[120:123], v[140:143], v[180:183], v[120:123]
	v_mfma_f32_16x16x32_bf16 v[116:119], v[132:135], v[188:191], v[116:119]
	v_mfma_f32_16x16x32_bf16 v[108:111], v[140:143], v[188:191], v[108:111]
	v_mfma_f32_16x16x32_bf16 v[88:91], v[132:135], v[200:203], v[88:91]
	v_mfma_f32_16x16x32_bf16 v[100:103], v[140:143], v[200:203], v[100:103]
	v_mfma_f32_16x16x32_bf16 v[72:75], v[132:135], v[208:211], v[72:75]
	v_mfma_f32_16x16x32_bf16 v[76:79], v[140:143], v[208:211], v[76:79]
	v_mfma_f32_16x16x32_bf16 v[112:115], v[144:147], v[160:163], 0
	v_mfma_f32_16x16x32_bf16 v[104:107], v[152:155], v[160:163], 0
	v_mfma_f32_16x16x32_bf16 v[96:99], v[144:147], v[184:187], 0
	v_mfma_f32_16x16x32_bf16 v[92:95], v[152:155], v[184:187], 0
	v_mfma_f32_16x16x32_bf16 v[80:83], v[144:147], v[192:195], 0
	v_mfma_f32_16x16x32_bf16 v[84:87], v[152:155], v[192:195], 0
	v_mfma_f32_16x16x32_bf16 v[64:67], v[144:147], v[204:207], 0
	v_mfma_f32_16x16x32_bf16 v[68:71], v[152:155], v[204:207], 0
	v_mfma_f32_16x16x32_bf16 v[112:115], v[148:151], v[180:183], v[112:115]
	v_mfma_f32_16x16x32_bf16 v[104:107], v[156:159], v[180:183], v[104:107]
	v_mfma_f32_16x16x32_bf16 v[96:99], v[148:151], v[188:191], v[96:99]
	v_mfma_f32_16x16x32_bf16 v[92:95], v[156:159], v[188:191], v[92:95]
	s_setprio 2
	s_barrier
	v_mfma_f32_16x16x32_bf16 v[80:83], v[148:151], v[200:203], v[80:83]
	v_mfma_f32_16x16x32_bf16 v[84:87], v[156:159], v[200:203], v[84:87]
	v_mfma_f32_16x16x32_bf16 v[64:67], v[148:151], v[208:211], v[64:67]
	v_mfma_f32_16x16x32_bf16 v[68:71], v[156:159], v[208:211], v[68:71]
	s_setprio 2
	s_mov_b32 m0, s36
	v_lshl_add_u64 v[216:217], s[28:29], 0, v[164:165]
	global_load_lds_dwordx4 v[216:217], off
	s_mov_b32 m0, s37
	v_lshl_add_u64 v[218:219], s[28:29], 0, v[168:169]
	global_load_lds_dwordx4 v[218:219], off
	s_add_i32 s24, s45, s35
	v_lshl_add_u64 v[212:213], s[26:27], 0, v[166:167]
	s_mov_b32 m0, s24
	ds_read_b128 v[160:163], v199 offset:16384
	ds_read_b128 v[180:183], v199 offset:17408
	ds_read_b128 v[184:187], v199 offset:18432
	ds_read_b128 v[188:191], v199 offset:19456
	ds_read_b128 v[192:195], v199 offset:20480
	ds_read_b128 v[200:203], v199 offset:21504
	ds_read_b128 v[204:207], v199 offset:22528
	ds_read_b128 v[208:211], v199 offset:23552
	global_load_lds_dwordx4 v[212:213], off
	s_add_i32 m0, s24, 0x2000
	s_add_u32 s24, s26, 0xb0000
	v_lshl_add_u64 v[214:215], s[26:27], 0, v[170:171]
	s_addc_u32 s25, s27, 0
	s_add_i32 s54, s46, s35
	global_load_lds_dwordx4 v[214:215], off
	v_lshl_add_u64 v[250:251], s[24:25], 0, v[166:167]
	s_mov_b32 m0, s54
	global_load_lds_dwordx4 v[250:251], off
	s_add_i32 m0, s54, 0x2000
	v_lshl_add_u64 v[250:251], s[24:25], 0, v[170:171]
	global_load_lds_dwordx4 v[250:251], off
	s_waitcnt vmcnt(8) lgkmcnt(0)
	s_barrier
	s_setprio 1
	v_mfma_f32_16x16x32_bf16 v[56:59], v[128:131], v[160:163], 0
	v_mfma_f32_16x16x32_bf16 v[60:63], v[136:139], v[160:163], 0
	v_mfma_f32_16x16x32_bf16 v[40:43], v[128:131], v[184:187], 0
	v_mfma_f32_16x16x32_bf16 v[44:47], v[136:139], v[184:187], 0
	v_mfma_f32_16x16x32_bf16 v[24:27], v[128:131], v[192:195], 0
	v_mfma_f32_16x16x32_bf16 v[28:31], v[136:139], v[192:195], 0
	v_mfma_f32_16x16x32_bf16 v[8:11], v[128:131], v[204:207], 0
	v_mfma_f32_16x16x32_bf16 v[12:15], v[136:139], v[204:207], 0
	v_mfma_f32_16x16x32_bf16 v[56:59], v[132:135], v[180:183], v[56:59]
	v_mfma_f32_16x16x32_bf16 v[60:63], v[140:143], v[180:183], v[60:63]
	v_mfma_f32_16x16x32_bf16 v[40:43], v[132:135], v[188:191], v[40:43]
	v_mfma_f32_16x16x32_bf16 v[44:47], v[140:143], v[188:191], v[44:47]
	v_mfma_f32_16x16x32_bf16 v[24:27], v[132:135], v[200:203], v[24:27]
	v_mfma_f32_16x16x32_bf16 v[28:31], v[140:143], v[200:203], v[28:31]
	v_mfma_f32_16x16x32_bf16 v[8:11], v[132:135], v[208:211], v[8:11]
	v_mfma_f32_16x16x32_bf16 v[12:15], v[140:143], v[208:211], v[12:15]
	v_mfma_f32_16x16x32_bf16 v[48:51], v[144:147], v[160:163], 0
	v_mfma_f32_16x16x32_bf16 v[52:55], v[152:155], v[160:163], 0
	v_mfma_f32_16x16x32_bf16 v[32:35], v[144:147], v[184:187], 0
	v_mfma_f32_16x16x32_bf16 v[36:39], v[152:155], v[184:187], 0
	v_mfma_f32_16x16x32_bf16 v[16:19], v[144:147], v[192:195], 0
	v_mfma_f32_16x16x32_bf16 v[20:23], v[152:155], v[192:195], 0
	v_mfma_f32_16x16x32_bf16 v[0:3], v[144:147], v[204:207], 0
	v_mfma_f32_16x16x32_bf16 v[4:7], v[152:155], v[204:207], 0
	v_mfma_f32_16x16x32_bf16 v[48:51], v[148:151], v[180:183], v[48:51]
	v_mfma_f32_16x16x32_bf16 v[52:55], v[156:159], v[180:183], v[52:55]
	v_mfma_f32_16x16x32_bf16 v[32:35], v[148:151], v[188:191], v[32:35]
	v_mfma_f32_16x16x32_bf16 v[36:39], v[156:159], v[188:191], v[36:39]
	s_setprio 2
	s_barrier
	v_mfma_f32_16x16x32_bf16 v[16:19], v[148:151], v[200:203], v[16:19]
	v_mfma_f32_16x16x32_bf16 v[20:23], v[156:159], v[200:203], v[20:23]
	v_mfma_f32_16x16x32_bf16 v[0:3], v[148:151], v[208:211], v[0:3]
	v_mfma_f32_16x16x32_bf16 v[4:7], v[156:159], v[208:211], v[4:7]
	s_setprio 0
	s_add_i32 s54, 0, 0x18000
	s_add_i32 s55, 0, 0x1c000
	v_add_u32_e32 v140, s54, v196
	v_add_u32_e32 v156, s55, v196
	ds_read_b128 v[128:131], v140
	ds_read_b128 v[132:135], v140 offset:1024
	ds_read_b128 v[136:139], v140 offset:2048
	ds_read_b128 v[140:143], v140 offset:3072
	ds_read_b128 v[144:147], v156
	ds_read_b128 v[148:151], v156 offset:1024
	ds_read_b128 v[152:155], v156 offset:2048
	ds_read_b128 v[156:159], v156 offset:3072
	s_add_u32 s24, s28, 0xb0000
	s_addc_u32 s25, s29, 0
	s_mov_b32 m0, s38
	v_lshl_add_u64 v[220:221], s[24:25], 0, v[164:165]
	ds_read_b128 v[160:163], v199 offset:32768
	ds_read_b128 v[180:183], v199 offset:33792
	ds_read_b128 v[184:187], v199 offset:34816
	ds_read_b128 v[188:191], v199 offset:35840
	ds_read_b128 v[192:195], v199 offset:36864
	ds_read_b128 v[200:203], v199 offset:37888
	ds_read_b128 v[204:207], v199 offset:38912
	ds_read_b128 v[208:211], v199 offset:39936
	global_load_lds_dwordx4 v[220:221], off
	s_mov_b32 m0, s39
	v_lshl_add_u64 v[220:221], s[24:25], 0, v[168:169]
	global_load_lds_dwordx4 v[220:221], off
	s_waitcnt vmcnt(8) lgkmcnt(0)
	s_barrier
	s_setprio 1
	v_mfma_f32_16x16x32_bf16 v[124:127], v[128:131], v[160:163], v[124:127]
	v_mfma_f32_16x16x32_bf16 v[120:123], v[136:139], v[160:163], v[120:123]
	v_mfma_f32_16x16x32_bf16 v[116:119], v[128:131], v[184:187], v[116:119]
	v_mfma_f32_16x16x32_bf16 v[108:111], v[136:139], v[184:187], v[108:111]
	v_mfma_f32_16x16x32_bf16 v[88:91], v[128:131], v[192:195], v[88:91]
	v_mfma_f32_16x16x32_bf16 v[100:103], v[136:139], v[192:195], v[100:103]
	v_mfma_f32_16x16x32_bf16 v[72:75], v[128:131], v[204:207], v[72:75]
	v_mfma_f32_16x16x32_bf16 v[76:79], v[136:139], v[204:207], v[76:79]
	v_mfma_f32_16x16x32_bf16 v[124:127], v[132:135], v[180:183], v[124:127]
	v_mfma_f32_16x16x32_bf16 v[120:123], v[140:143], v[180:183], v[120:123]
	v_mfma_f32_16x16x32_bf16 v[116:119], v[132:135], v[188:191], v[116:119]
	v_mfma_f32_16x16x32_bf16 v[108:111], v[140:143], v[188:191], v[108:111]
	v_mfma_f32_16x16x32_bf16 v[88:91], v[132:135], v[200:203], v[88:91]
	v_mfma_f32_16x16x32_bf16 v[100:103], v[140:143], v[200:203], v[100:103]
	v_mfma_f32_16x16x32_bf16 v[72:75], v[132:135], v[208:211], v[72:75]
	v_mfma_f32_16x16x32_bf16 v[76:79], v[140:143], v[208:211], v[76:79]
	v_mfma_f32_16x16x32_bf16 v[112:115], v[144:147], v[160:163], v[112:115]
	v_mfma_f32_16x16x32_bf16 v[104:107], v[152:155], v[160:163], v[104:107]
	v_mfma_f32_16x16x32_bf16 v[96:99], v[144:147], v[184:187], v[96:99]
	v_mfma_f32_16x16x32_bf16 v[92:95], v[152:155], v[184:187], v[92:95]
	v_mfma_f32_16x16x32_bf16 v[80:83], v[144:147], v[192:195], v[80:83]
	v_mfma_f32_16x16x32_bf16 v[84:87], v[152:155], v[192:195], v[84:87]
	v_mfma_f32_16x16x32_bf16 v[64:67], v[144:147], v[204:207], v[64:67]
	v_mfma_f32_16x16x32_bf16 v[68:71], v[152:155], v[204:207], v[68:71]
	v_mfma_f32_16x16x32_bf16 v[112:115], v[148:151], v[180:183], v[112:115]
	v_mfma_f32_16x16x32_bf16 v[104:107], v[156:159], v[180:183], v[104:107]
	v_mfma_f32_16x16x32_bf16 v[96:99], v[148:151], v[188:191], v[96:99]
	v_mfma_f32_16x16x32_bf16 v[92:95], v[156:159], v[188:191], v[92:95]
	s_setprio 2
	s_barrier
	v_mfma_f32_16x16x32_bf16 v[80:83], v[148:151], v[200:203], v[80:83]
	v_mfma_f32_16x16x32_bf16 v[84:87], v[156:159], v[200:203], v[84:87]
	v_mfma_f32_16x16x32_bf16 v[64:67], v[148:151], v[208:211], v[64:67]
	v_mfma_f32_16x16x32_bf16 v[68:71], v[156:159], v[208:211], v[68:71]
	s_setprio 2
	s_mov_b32 m0, s41
	v_lshl_add_u64 v[250:251], v[216:217], 0, s[16:17]
	global_load_lds_dwordx4 v[250:251], off
	s_mov_b32 m0, s42
	v_lshl_add_u64 v[250:251], v[218:219], 0, s[16:17]
	global_load_lds_dwordx4 v[250:251], off
	s_add_i32 s24, s54, s35
	v_lshl_add_u64 v[212:213], v[212:213], 0, s[16:17]
	s_mov_b32 m0, s24
	ds_read_b128 v[160:163], v199 offset:49152
	ds_read_b128 v[180:183], v199 offset:50176
	ds_read_b128 v[184:187], v199 offset:51200
	ds_read_b128 v[188:191], v199 offset:52224
	ds_read_b128 v[192:195], v199 offset:53248
	ds_read_b128 v[200:203], v199 offset:54272
	ds_read_b128 v[204:207], v199 offset:55296
	ds_read_b128 v[208:211], v199 offset:56320
	global_load_lds_dwordx4 v[212:213], off
	s_add_i32 m0, s24, 0x2000
	s_add_u32 s24, s26, 0xb0080
	v_lshl_add_u64 v[212:213], v[214:215], 0, s[16:17]
	s_addc_u32 s25, s27, 0
	s_add_i32 s26, s55, s35
	global_load_lds_dwordx4 v[212:213], off
	s_mov_b32 m0, s26
	v_lshl_add_u64 v[212:213], s[24:25], 0, v[166:167]
	global_load_lds_dwordx4 v[212:213], off
	s_add_i32 m0, s26, 0x2000
	v_lshl_add_u64 v[212:213], s[24:25], 0, v[170:171]
	global_load_lds_dwordx4 v[212:213], off
	s_waitcnt vmcnt(8) lgkmcnt(0)
	s_barrier
	s_setprio 1
	v_mfma_f32_16x16x32_bf16 v[56:59], v[128:131], v[160:163], v[56:59]
	v_mfma_f32_16x16x32_bf16 v[60:63], v[136:139], v[160:163], v[60:63]
	v_mfma_f32_16x16x32_bf16 v[40:43], v[128:131], v[184:187], v[40:43]
	v_mfma_f32_16x16x32_bf16 v[44:47], v[136:139], v[184:187], v[44:47]
	v_mfma_f32_16x16x32_bf16 v[24:27], v[128:131], v[192:195], v[24:27]
	v_mfma_f32_16x16x32_bf16 v[28:31], v[136:139], v[192:195], v[28:31]
	v_mfma_f32_16x16x32_bf16 v[8:11], v[128:131], v[204:207], v[8:11]
	v_mfma_f32_16x16x32_bf16 v[12:15], v[136:139], v[204:207], v[12:15]
	v_mfma_f32_16x16x32_bf16 v[56:59], v[132:135], v[180:183], v[56:59]
	v_mfma_f32_16x16x32_bf16 v[60:63], v[140:143], v[180:183], v[60:63]
	v_mfma_f32_16x16x32_bf16 v[40:43], v[132:135], v[188:191], v[40:43]
	v_mfma_f32_16x16x32_bf16 v[44:47], v[140:143], v[188:191], v[44:47]
	v_mfma_f32_16x16x32_bf16 v[24:27], v[132:135], v[200:203], v[24:27]
	v_mfma_f32_16x16x32_bf16 v[28:31], v[140:143], v[200:203], v[28:31]
	v_mfma_f32_16x16x32_bf16 v[8:11], v[132:135], v[208:211], v[8:11]
	v_mfma_f32_16x16x32_bf16 v[12:15], v[140:143], v[208:211], v[12:15]
	v_mfma_f32_16x16x32_bf16 v[48:51], v[144:147], v[160:163], v[48:51]
	v_mfma_f32_16x16x32_bf16 v[52:55], v[152:155], v[160:163], v[52:55]
	v_mfma_f32_16x16x32_bf16 v[32:35], v[144:147], v[184:187], v[32:35]
	v_mfma_f32_16x16x32_bf16 v[36:39], v[152:155], v[184:187], v[36:39]
	v_mfma_f32_16x16x32_bf16 v[16:19], v[144:147], v[192:195], v[16:19]
	v_mfma_f32_16x16x32_bf16 v[20:23], v[152:155], v[192:195], v[20:23]
	v_mfma_f32_16x16x32_bf16 v[0:3], v[144:147], v[204:207], v[0:3]
	v_mfma_f32_16x16x32_bf16 v[4:7], v[152:155], v[204:207], v[4:7]
	v_mfma_f32_16x16x32_bf16 v[48:51], v[148:151], v[180:183], v[48:51]
	v_mfma_f32_16x16x32_bf16 v[52:55], v[156:159], v[180:183], v[52:55]
	v_mfma_f32_16x16x32_bf16 v[32:35], v[148:151], v[188:191], v[32:35]
	v_mfma_f32_16x16x32_bf16 v[36:39], v[156:159], v[188:191], v[36:39]
	s_setprio 2
	s_barrier
	v_mfma_f32_16x16x32_bf16 v[16:19], v[148:151], v[200:203], v[16:19]
	v_mfma_f32_16x16x32_bf16 v[20:23], v[156:159], v[200:203], v[20:23]
	v_mfma_f32_16x16x32_bf16 v[0:3], v[148:151], v[208:211], v[0:3]
	v_mfma_f32_16x16x32_bf16 v[4:7], v[156:159], v[208:211], v[4:7]
	s_setprio 0
	s_add_i32 s53, s53, 2
	s_add_u32 s51, s51, 0x100
	s_addc_u32 s52, s52, 0
	s_cmp_gt_u32 s53, 41
	s_mov_b64 s[24:25], s[4:5]
.LBB0_1310:
	ds_read_b128 v[128:131], v197
	ds_read_b128 v[132:135], v197 offset:1024
	ds_read_b128 v[136:139], v197 offset:2048
	ds_read_b128 v[140:143], v197 offset:3072
	ds_read_b128 v[144:147], v198
	ds_read_b128 v[148:151], v198 offset:1024
	ds_read_b128 v[152:155], v198 offset:2048
	ds_read_b128 v[156:159], v198 offset:3072
	s_add_u32 s4, s24, 0x100
	s_addc_u32 s5, s25, 0
	s_cmp_eq_u32 s53, 40
	s_cselect_b32 s29, s21, s5
	s_cselect_b32 s28, s20, s4
	s_cselect_b32 s27, s23, s52
	s_cselect_b32 s26, s22, s51
	v_lshl_add_u64 v[212:213], s[24:25], 0, v[172:173]
	s_add_i32 m0, s36, 0xc000
	ds_read_b128 v[160:163], v199
	ds_read_b128 v[180:183], v199 offset:1024
	ds_read_b128 v[184:187], v199 offset:2048
	ds_read_b128 v[188:191], v199 offset:3072
	ds_read_b128 v[192:195], v199 offset:4096
	ds_read_b128 v[200:203], v199 offset:5120
	ds_read_b128 v[204:207], v199 offset:6144
	ds_read_b128 v[208:211], v199 offset:7168
	global_load_lds_dwordx4 v[212:213], off
	s_add_i32 m0, s36, 0xe000
	v_lshl_add_u64 v[212:213], s[24:25], 0, v[174:175]
	global_load_lds_dwordx4 v[212:213], off
	s_waitcnt vmcnt(8) lgkmcnt(0)
	s_barrier
	s_setprio 1
	v_mfma_f32_16x16x32_bf16 v[124:127], v[128:131], v[160:163], v[124:127]
	v_mfma_f32_16x16x32_bf16 v[120:123], v[136:139], v[160:163], v[120:123]
	v_mfma_f32_16x16x32_bf16 v[116:119], v[128:131], v[184:187], v[116:119]
	v_mfma_f32_16x16x32_bf16 v[108:111], v[136:139], v[184:187], v[108:111]
	v_mfma_f32_16x16x32_bf16 v[88:91], v[128:131], v[192:195], v[88:91]
	v_mfma_f32_16x16x32_bf16 v[100:103], v[136:139], v[192:195], v[100:103]
	v_mfma_f32_16x16x32_bf16 v[72:75], v[128:131], v[204:207], v[72:75]
	v_mfma_f32_16x16x32_bf16 v[76:79], v[136:139], v[204:207], v[76:79]
	v_mfma_f32_16x16x32_bf16 v[124:127], v[132:135], v[180:183], v[124:127]
	v_mfma_f32_16x16x32_bf16 v[120:123], v[140:143], v[180:183], v[120:123]
	v_mfma_f32_16x16x32_bf16 v[116:119], v[132:135], v[188:191], v[116:119]
	v_mfma_f32_16x16x32_bf16 v[108:111], v[140:143], v[188:191], v[108:111]
	v_mfma_f32_16x16x32_bf16 v[88:91], v[132:135], v[200:203], v[88:91]
	v_mfma_f32_16x16x32_bf16 v[100:103], v[140:143], v[200:203], v[100:103]
	v_mfma_f32_16x16x32_bf16 v[72:75], v[132:135], v[208:211], v[72:75]
	v_mfma_f32_16x16x32_bf16 v[76:79], v[140:143], v[208:211], v[76:79]
	v_mfma_f32_16x16x32_bf16 v[112:115], v[144:147], v[160:163], v[112:115]
	v_mfma_f32_16x16x32_bf16 v[104:107], v[152:155], v[160:163], v[104:107]
	v_mfma_f32_16x16x32_bf16 v[96:99], v[144:147], v[184:187], v[96:99]
	v_mfma_f32_16x16x32_bf16 v[92:95], v[152:155], v[184:187], v[92:95]
	v_mfma_f32_16x16x32_bf16 v[80:83], v[144:147], v[192:195], v[80:83]
	v_mfma_f32_16x16x32_bf16 v[84:87], v[152:155], v[192:195], v[84:87]
	v_mfma_f32_16x16x32_bf16 v[64:67], v[144:147], v[204:207], v[64:67]
	v_mfma_f32_16x16x32_bf16 v[68:71], v[152:155], v[204:207], v[68:71]
	v_mfma_f32_16x16x32_bf16 v[112:115], v[148:151], v[180:183], v[112:115]
	v_mfma_f32_16x16x32_bf16 v[104:107], v[156:159], v[180:183], v[104:107]
	v_mfma_f32_16x16x32_bf16 v[96:99], v[148:151], v[188:191], v[96:99]
	v_mfma_f32_16x16x32_bf16 v[92:95], v[156:159], v[188:191], v[92:95]
	s_setprio 2
	s_barrier
	v_mfma_f32_16x16x32_bf16 v[80:83], v[148:151], v[200:203], v[80:83]
	v_mfma_f32_16x16x32_bf16 v[84:87], v[156:159], v[200:203], v[84:87]
	v_mfma_f32_16x16x32_bf16 v[64:67], v[148:151], v[208:211], v[64:67]
	v_mfma_f32_16x16x32_bf16 v[68:71], v[156:159], v[208:211], v[68:71]
	s_setprio 2
	s_mov_b32 m0, s36
	v_lshl_add_u64 v[216:217], s[28:29], 0, v[164:165]
	global_load_lds_dwordx4 v[216:217], off
	s_mov_b32 m0, s37
	v_lshl_add_u64 v[218:219], s[28:29], 0, v[168:169]
	global_load_lds_dwordx4 v[218:219], off
	s_add_i32 s24, s45, s35
	v_lshl_add_u64 v[212:213], s[26:27], 0, v[166:167]
	s_mov_b32 m0, s24
	ds_read_b128 v[160:163], v199 offset:16384
	ds_read_b128 v[180:183], v199 offset:17408
	ds_read_b128 v[184:187], v199 offset:18432
	ds_read_b128 v[188:191], v199 offset:19456
	ds_read_b128 v[192:195], v199 offset:20480
	ds_read_b128 v[200:203], v199 offset:21504
	ds_read_b128 v[204:207], v199 offset:22528
	ds_read_b128 v[208:211], v199 offset:23552
	global_load_lds_dwordx4 v[212:213], off
	s_add_i32 m0, s24, 0x2000
	s_add_u32 s24, s26, 0xb0000
	v_lshl_add_u64 v[214:215], s[26:27], 0, v[170:171]
	s_addc_u32 s25, s27, 0
	s_add_i32 s54, s46, s35
	global_load_lds_dwordx4 v[214:215], off
	v_lshl_add_u64 v[250:251], s[24:25], 0, v[166:167]
	s_mov_b32 m0, s54
	global_load_lds_dwordx4 v[250:251], off
	s_add_i32 m0, s54, 0x2000
	v_lshl_add_u64 v[250:251], s[24:25], 0, v[170:171]
	global_load_lds_dwordx4 v[250:251], off
	s_waitcnt vmcnt(8) lgkmcnt(0)
	s_barrier
	s_setprio 1
	v_mfma_f32_16x16x32_bf16 v[56:59], v[128:131], v[160:163], v[56:59]
	v_mfma_f32_16x16x32_bf16 v[60:63], v[136:139], v[160:163], v[60:63]
	v_mfma_f32_16x16x32_bf16 v[40:43], v[128:131], v[184:187], v[40:43]
	v_mfma_f32_16x16x32_bf16 v[44:47], v[136:139], v[184:187], v[44:47]
	v_mfma_f32_16x16x32_bf16 v[24:27], v[128:131], v[192:195], v[24:27]
	v_mfma_f32_16x16x32_bf16 v[28:31], v[136:139], v[192:195], v[28:31]
	v_mfma_f32_16x16x32_bf16 v[8:11], v[128:131], v[204:207], v[8:11]
	v_mfma_f32_16x16x32_bf16 v[12:15], v[136:139], v[204:207], v[12:15]
	v_mfma_f32_16x16x32_bf16 v[56:59], v[132:135], v[180:183], v[56:59]
	v_mfma_f32_16x16x32_bf16 v[60:63], v[140:143], v[180:183], v[60:63]
	v_mfma_f32_16x16x32_bf16 v[40:43], v[132:135], v[188:191], v[40:43]
	v_mfma_f32_16x16x32_bf16 v[44:47], v[140:143], v[188:191], v[44:47]
	v_mfma_f32_16x16x32_bf16 v[24:27], v[132:135], v[200:203], v[24:27]
	v_mfma_f32_16x16x32_bf16 v[28:31], v[140:143], v[200:203], v[28:31]
	v_mfma_f32_16x16x32_bf16 v[8:11], v[132:135], v[208:211], v[8:11]
	v_mfma_f32_16x16x32_bf16 v[12:15], v[140:143], v[208:211], v[12:15]
	v_mfma_f32_16x16x32_bf16 v[48:51], v[144:147], v[160:163], v[48:51]
	v_mfma_f32_16x16x32_bf16 v[52:55], v[152:155], v[160:163], v[52:55]
	v_mfma_f32_16x16x32_bf16 v[32:35], v[144:147], v[184:187], v[32:35]
	v_mfma_f32_16x16x32_bf16 v[36:39], v[152:155], v[184:187], v[36:39]
	v_mfma_f32_16x16x32_bf16 v[16:19], v[144:147], v[192:195], v[16:19]
	v_mfma_f32_16x16x32_bf16 v[20:23], v[152:155], v[192:195], v[20:23]
	v_mfma_f32_16x16x32_bf16 v[0:3], v[144:147], v[204:207], v[0:3]
	v_mfma_f32_16x16x32_bf16 v[4:7], v[152:155], v[204:207], v[4:7]
	v_mfma_f32_16x16x32_bf16 v[48:51], v[148:151], v[180:183], v[48:51]
	v_mfma_f32_16x16x32_bf16 v[52:55], v[156:159], v[180:183], v[52:55]
	v_mfma_f32_16x16x32_bf16 v[32:35], v[148:151], v[188:191], v[32:35]
	v_mfma_f32_16x16x32_bf16 v[36:39], v[156:159], v[188:191], v[36:39]
	s_setprio 2
	s_barrier
	v_mfma_f32_16x16x32_bf16 v[16:19], v[148:151], v[200:203], v[16:19]
	v_mfma_f32_16x16x32_bf16 v[20:23], v[156:159], v[200:203], v[20:23]
	v_mfma_f32_16x16x32_bf16 v[0:3], v[148:151], v[208:211], v[0:3]
	v_mfma_f32_16x16x32_bf16 v[4:7], v[156:159], v[208:211], v[4:7]
	s_setprio 0
	s_add_i32 s54, 0, 0x18000
	s_add_i32 s55, 0, 0x1c000
	v_add_u32_e32 v140, s54, v196
	v_add_u32_e32 v156, s55, v196
	ds_read_b128 v[128:131], v140
	ds_read_b128 v[132:135], v140 offset:1024
	ds_read_b128 v[136:139], v140 offset:2048
	ds_read_b128 v[140:143], v140 offset:3072
	ds_read_b128 v[144:147], v156
	ds_read_b128 v[148:151], v156 offset:1024
	ds_read_b128 v[152:155], v156 offset:2048
	ds_read_b128 v[156:159], v156 offset:3072
	s_add_u32 s24, s28, 0xb0000
	s_addc_u32 s25, s29, 0
	s_mov_b32 m0, s38
	v_lshl_add_u64 v[220:221], s[24:25], 0, v[164:165]
	ds_read_b128 v[160:163], v199 offset:32768
	ds_read_b128 v[180:183], v199 offset:33792
	ds_read_b128 v[184:187], v199 offset:34816
	ds_read_b128 v[188:191], v199 offset:35840
	ds_read_b128 v[192:195], v199 offset:36864
	ds_read_b128 v[200:203], v199 offset:37888
	ds_read_b128 v[204:207], v199 offset:38912
	ds_read_b128 v[208:211], v199 offset:39936
	global_load_lds_dwordx4 v[220:221], off
	s_mov_b32 m0, s39
	v_lshl_add_u64 v[220:221], s[24:25], 0, v[168:169]
	global_load_lds_dwordx4 v[220:221], off
	s_waitcnt vmcnt(8) lgkmcnt(0)
	s_barrier
	s_setprio 1
	v_mfma_f32_16x16x32_bf16 v[124:127], v[128:131], v[160:163], v[124:127]
	v_mfma_f32_16x16x32_bf16 v[120:123], v[136:139], v[160:163], v[120:123]
	v_mfma_f32_16x16x32_bf16 v[116:119], v[128:131], v[184:187], v[116:119]
	v_mfma_f32_16x16x32_bf16 v[108:111], v[136:139], v[184:187], v[108:111]
	v_mfma_f32_16x16x32_bf16 v[88:91], v[128:131], v[192:195], v[88:91]
	v_mfma_f32_16x16x32_bf16 v[100:103], v[136:139], v[192:195], v[100:103]
	v_mfma_f32_16x16x32_bf16 v[72:75], v[128:131], v[204:207], v[72:75]
	v_mfma_f32_16x16x32_bf16 v[76:79], v[136:139], v[204:207], v[76:79]
	v_mfma_f32_16x16x32_bf16 v[124:127], v[132:135], v[180:183], v[124:127]
	v_mfma_f32_16x16x32_bf16 v[120:123], v[140:143], v[180:183], v[120:123]
	v_mfma_f32_16x16x32_bf16 v[116:119], v[132:135], v[188:191], v[116:119]
	v_mfma_f32_16x16x32_bf16 v[108:111], v[140:143], v[188:191], v[108:111]
	v_mfma_f32_16x16x32_bf16 v[88:91], v[132:135], v[200:203], v[88:91]
	v_mfma_f32_16x16x32_bf16 v[100:103], v[140:143], v[200:203], v[100:103]
	v_mfma_f32_16x16x32_bf16 v[72:75], v[132:135], v[208:211], v[72:75]
	v_mfma_f32_16x16x32_bf16 v[76:79], v[140:143], v[208:211], v[76:79]
	v_mfma_f32_16x16x32_bf16 v[112:115], v[144:147], v[160:163], v[112:115]
	v_mfma_f32_16x16x32_bf16 v[104:107], v[152:155], v[160:163], v[104:107]
	v_mfma_f32_16x16x32_bf16 v[96:99], v[144:147], v[184:187], v[96:99]
	v_mfma_f32_16x16x32_bf16 v[92:95], v[152:155], v[184:187], v[92:95]
	v_mfma_f32_16x16x32_bf16 v[80:83], v[144:147], v[192:195], v[80:83]
	v_mfma_f32_16x16x32_bf16 v[84:87], v[152:155], v[192:195], v[84:87]
	v_mfma_f32_16x16x32_bf16 v[64:67], v[144:147], v[204:207], v[64:67]
	v_mfma_f32_16x16x32_bf16 v[68:71], v[152:155], v[204:207], v[68:71]
	v_mfma_f32_16x16x32_bf16 v[112:115], v[148:151], v[180:183], v[112:115]
	v_mfma_f32_16x16x32_bf16 v[104:107], v[156:159], v[180:183], v[104:107]
	v_mfma_f32_16x16x32_bf16 v[96:99], v[148:151], v[188:191], v[96:99]
	v_mfma_f32_16x16x32_bf16 v[92:95], v[156:159], v[188:191], v[92:95]
	s_setprio 2
	s_barrier
	v_mfma_f32_16x16x32_bf16 v[80:83], v[148:151], v[200:203], v[80:83]
	v_mfma_f32_16x16x32_bf16 v[84:87], v[156:159], v[200:203], v[84:87]
	v_mfma_f32_16x16x32_bf16 v[64:67], v[148:151], v[208:211], v[64:67]
	v_mfma_f32_16x16x32_bf16 v[68:71], v[156:159], v[208:211], v[68:71]
	s_setprio 2
	s_mov_b32 m0, s41
	v_lshl_add_u64 v[250:251], v[216:217], 0, s[16:17]
	global_load_lds_dwordx4 v[250:251], off
	s_mov_b32 m0, s42
	v_lshl_add_u64 v[250:251], v[218:219], 0, s[16:17]
	global_load_lds_dwordx4 v[250:251], off
	s_add_i32 s24, s54, s35
	v_lshl_add_u64 v[212:213], v[212:213], 0, s[16:17]
	s_mov_b32 m0, s24
	ds_read_b128 v[160:163], v199 offset:49152
	ds_read_b128 v[180:183], v199 offset:50176
	ds_read_b128 v[184:187], v199 offset:51200
	ds_read_b128 v[188:191], v199 offset:52224
	ds_read_b128 v[192:195], v199 offset:53248
	ds_read_b128 v[200:203], v199 offset:54272
	ds_read_b128 v[204:207], v199 offset:55296
	ds_read_b128 v[208:211], v199 offset:56320
	global_load_lds_dwordx4 v[212:213], off
	s_add_i32 m0, s24, 0x2000
	s_add_u32 s24, s26, 0xb0080
	v_lshl_add_u64 v[212:213], v[214:215], 0, s[16:17]
	s_addc_u32 s25, s27, 0
	s_add_i32 s26, s55, s35
	global_load_lds_dwordx4 v[212:213], off
	s_mov_b32 m0, s26
	v_lshl_add_u64 v[212:213], s[24:25], 0, v[166:167]
	global_load_lds_dwordx4 v[212:213], off
	s_add_i32 m0, s26, 0x2000
	v_lshl_add_u64 v[212:213], s[24:25], 0, v[170:171]
	global_load_lds_dwordx4 v[212:213], off
	s_waitcnt vmcnt(8) lgkmcnt(0)
	s_barrier
	s_setprio 1
	v_mfma_f32_16x16x32_bf16 v[56:59], v[128:131], v[160:163], v[56:59]
	v_mfma_f32_16x16x32_bf16 v[60:63], v[136:139], v[160:163], v[60:63]
	v_mfma_f32_16x16x32_bf16 v[40:43], v[128:131], v[184:187], v[40:43]
	v_mfma_f32_16x16x32_bf16 v[44:47], v[136:139], v[184:187], v[44:47]
	v_mfma_f32_16x16x32_bf16 v[24:27], v[128:131], v[192:195], v[24:27]
	v_mfma_f32_16x16x32_bf16 v[28:31], v[136:139], v[192:195], v[28:31]
	v_mfma_f32_16x16x32_bf16 v[8:11], v[128:131], v[204:207], v[8:11]
	v_mfma_f32_16x16x32_bf16 v[12:15], v[136:139], v[204:207], v[12:15]
	v_mfma_f32_16x16x32_bf16 v[56:59], v[132:135], v[180:183], v[56:59]
	v_mfma_f32_16x16x32_bf16 v[60:63], v[140:143], v[180:183], v[60:63]
	v_mfma_f32_16x16x32_bf16 v[40:43], v[132:135], v[188:191], v[40:43]
	v_mfma_f32_16x16x32_bf16 v[44:47], v[140:143], v[188:191], v[44:47]
	v_mfma_f32_16x16x32_bf16 v[24:27], v[132:135], v[200:203], v[24:27]
	v_mfma_f32_16x16x32_bf16 v[28:31], v[140:143], v[200:203], v[28:31]
	v_mfma_f32_16x16x32_bf16 v[8:11], v[132:135], v[208:211], v[8:11]
	v_mfma_f32_16x16x32_bf16 v[12:15], v[140:143], v[208:211], v[12:15]
	v_mfma_f32_16x16x32_bf16 v[48:51], v[144:147], v[160:163], v[48:51]
	v_mfma_f32_16x16x32_bf16 v[52:55], v[152:155], v[160:163], v[52:55]
	v_mfma_f32_16x16x32_bf16 v[32:35], v[144:147], v[184:187], v[32:35]
	v_mfma_f32_16x16x32_bf16 v[36:39], v[152:155], v[184:187], v[36:39]
	v_mfma_f32_16x16x32_bf16 v[16:19], v[144:147], v[192:195], v[16:19]
	v_mfma_f32_16x16x32_bf16 v[20:23], v[152:155], v[192:195], v[20:23]
	v_mfma_f32_16x16x32_bf16 v[0:3], v[144:147], v[204:207], v[0:3]
	v_mfma_f32_16x16x32_bf16 v[4:7], v[152:155], v[204:207], v[4:7]
	v_mfma_f32_16x16x32_bf16 v[48:51], v[148:151], v[180:183], v[48:51]
	v_mfma_f32_16x16x32_bf16 v[52:55], v[156:159], v[180:183], v[52:55]
	v_mfma_f32_16x16x32_bf16 v[32:35], v[148:151], v[188:191], v[32:35]
	v_mfma_f32_16x16x32_bf16 v[36:39], v[156:159], v[188:191], v[36:39]
	s_setprio 2
	s_barrier
	v_mfma_f32_16x16x32_bf16 v[16:19], v[148:151], v[200:203], v[16:19]
	v_mfma_f32_16x16x32_bf16 v[20:23], v[156:159], v[200:203], v[20:23]
	v_mfma_f32_16x16x32_bf16 v[0:3], v[148:151], v[208:211], v[0:3]
	v_mfma_f32_16x16x32_bf16 v[4:7], v[156:159], v[208:211], v[4:7]
	s_setprio 0
	s_add_i32 s53, s53, 2
	s_add_u32 s51, s51, 0x100
	s_addc_u32 s52, s52, 0
	s_cmp_gt_u32 s53, 41
	s_mov_b64 s[24:25], s[4:5]
	s_cbranch_scc0 .LBB0_1310
